# stack on v46: GLA loop LDS reads hoisted with counted lgkmcnt (I), RWKV stage-H token-block reads hoisted (H), hand-scheduled final RMSNorm loop (J)
# speedup vs baseline: 1.0178x; 1.0092x over previous
.LBB0_327:
	s_or_b64 exec, exec, s[0:1]
	s_nop 5
	v_cvt_f16_f32_e32 v2, v52
	v_cvt_f16_f32_e32 v52, v53
	v_cvt_f16_f32_e32 v53, v54
	v_cvt_f16_f32_e32 v54, v55
	v_cndmask_b32_e64 v2, v2, 0, s[18:19]
	v_cndmask_b32_e64 v52, 0, v52, s[20:21]
	v_cndmask_b32_e64 v53, v53, 0, s[22:23]
	v_cndmask_b32_e64 v54, v54, 0, s[24:25]
	v_pack_b32_f16 v53, v53, v54
	v_pack_b32_f16 v52, v2, v52
	ds_write_b64 v123, v[52:53]
	s_waitcnt lgkmcnt(0)
	s_barrier
	ds_read_b128 v[126:129], v124 offset:55360
	ds_read_b128 v[52:55], v125
	ds_read_b128 v[134:137], v125 offset:64
	ds_read_b128 v[138:141], v125 offset:2304
	ds_read_b128 v[142:145], v125 offset:2368
	ds_read_b128 v[146:149], v125 offset:4608
	ds_read_b128 v[178:181], v125 offset:4672
	ds_read_b128 v[68:71], v124 offset:55296
	s_nop 0
	s_nop 0
	ds_read_b128 v[182:185], v125 offset:6912
	s_nop 0
	s_waitcnt lgkmcnt(1)
	v_mfma_f32_16x16x32_f16 v[48:51], v[68:71], v[52:55], v[48:51]
	s_nop 0
	v_add_u32_e32 v2, 0x1e500, v96
	ds_read_b128 v[186:189], v125 offset:6976
	s_add_i32 s28, s28, 1
	s_nop 0
	v_mfma_f32_16x16x32_f16 v[52:55], v[126:129], v[134:137], v[48:51]
	ds_read_b128 v[134:137], v2
	s_nop 2
	s_nop 0
	s_nop 0
	v_mfma_f32_16x16x32_f16 v[48:51], v[68:71], v[138:141], v[56:59]
	s_nop 2
	s_nop 0
	ds_read_b128 v[138:141], v248 offset:46080
	v_cvt_pk_f16_f32 v55, v54, v55
	v_cvt_pk_f16_f32 v54, v52, v53
	s_nop 0
	v_mfma_f32_16x16x32_f16 v[56:59], v[126:129], v[142:145], v[48:51]
	ds_read_b128 v[142:145], v248 offset:46144
	s_nop 2
	s_nop 0
	s_nop 0
	ds_read_b128 v[190:193], v2 offset:64
	v_mfma_f32_16x16x32_f16 v[48:51], v[68:71], v[146:149], v[60:63]
	s_nop 2
	s_nop 0
	s_nop 0
	ds_read_b128 v[146:149], v249 offset:48384
	v_mfma_f32_16x16x32_f16 v[60:63], v[126:129], v[178:181], v[48:51]
	s_nop 2
	s_nop 0
	ds_read_b128 v[178:181], v249 offset:48448
	s_nop 0
	s_waitcnt lgkmcnt(7)
	v_mfma_f32_16x16x32_f16 v[48:51], v[68:71], v[182:185], v[64:67]
	s_nop 2
	ds_read_b128 v[182:185], v2 offset:128
	s_nop 0
	s_nop 0
	s_waitcnt lgkmcnt(7)
	v_mfma_f32_16x16x32_f16 v[48:51], v[126:129], v[186:189], v[48:51]
	s_nop 0
	ds_read_b128 v[186:189], v248 offset:50688
	s_nop 0
	s_waitcnt lgkmcnt(7)
	v_pk_mul_f32 v[44:45], v[44:45], v[134:135]
	v_pk_mul_f32 v[46:47], v[46:47], v[136:137]
	ds_read_b128 v[134:137], v248 offset:50752
	s_nop 0
	s_nop 2
	v_cvt_pk_f16_f32 v51, v50, v51
	s_nop 0
	s_waitcnt lgkmcnt(7)
	v_mfma_f32_16x16x32_f16 v[44:47], v[138:141], v[68:71], v[44:47]
	ds_read_b128 v[138:141], v2 offset:192
	s_nop 0
	v_cvt_pk_f16_f32 v50, v48, v49
	s_nop 0
	s_waitcnt lgkmcnt(7)
	v_mfma_f32_16x16x32_f16 v[44:47], v[142:145], v[126:129], v[44:47]
	ds_read_b128 v[142:145], v249 offset:52992
	s_waitcnt lgkmcnt(7)
	v_pk_mul_f32 v[32:33], v[32:33], v[190:191]
	v_pk_mul_f32 v[34:35], v[34:35], v[192:193]
	s_nop 0
	s_nop 0
	s_waitcnt lgkmcnt(6)
	v_mfma_f32_16x16x32_f16 v[32:35], v[146:149], v[68:71], v[32:35]
	s_nop 0
	s_nop 0
	s_waitcnt lgkmcnt(5)
	v_mfma_f32_16x16x32_f16 v[32:35], v[178:181], v[126:129], v[32:35]
	s_waitcnt lgkmcnt(4)
	v_pk_mul_f32 v[40:41], v[40:41], v[182:183]
	v_pk_mul_f32 v[42:43], v[42:43], v[184:185]
	s_nop 0
	s_nop 0
	s_waitcnt lgkmcnt(3)
	v_mfma_f32_16x16x32_f16 v[40:43], v[186:189], v[68:71], v[40:43]
	s_nop 0
	s_nop 0
	s_waitcnt lgkmcnt(2)
	v_mfma_f32_16x16x32_f16 v[40:43], v[134:137], v[126:129], v[40:43]
	v_add_u32_e32 v2, s26, v91
	s_add_i32 s26, s26, 64
	s_waitcnt lgkmcnt(1)
	v_pk_mul_f32 v[36:37], v[36:37], v[138:139]
	v_pk_mul_f32 v[38:39], v[38:39], v[140:141]
	s_nop 0
	s_nop 0
	s_waitcnt lgkmcnt(0)
	v_mfma_f32_16x16x32_f16 v[36:39], v[142:145], v[68:71], v[36:39]
	ds_read_b128 v[64:67], v249 offset:53056
	s_nop 0
	s_waitcnt lgkmcnt(0)
	v_mfma_f32_16x16x32_f16 v[36:39], v[64:67], v[126:129], v[36:39]
	v_add_u32_e32 v64, s27, v112
	v_add_u32_e32 v65, 0xff, v64
	v_cndmask_b32_e64 v65, v65, v2, s[2:3]
	v_add_u32_e32 v52, v65, v89
	v_mad_i64_i32 v[52:53], s[0:1], v52, s91, v[82:83]
	global_store_dwordx2 v[52:53], v[54:55], off
	v_add_u32_e32 v52, 16, v2
	v_add_u32_e32 v53, 0xef, v64
	v_cndmask_b32_e64 v54, v53, v52, s[2:3]
	v_add_u32_e32 v54, v54, v89
	v_cvt_pk_f16_f32 v53, v58, v59
	v_cvt_pk_f16_f32 v52, v56, v57
	v_mad_i64_i32 v[54:55], s[0:1], v54, s91, v[82:83]
	global_store_dwordx2 v[54:55], v[52:53], off
	v_add_u32_e32 v52, 32, v2
	v_add_u32_e32 v53, 0xdf, v64
	v_cndmask_b32_e64 v54, v53, v52, s[2:3]
	v_add_u32_e32 v54, v54, v89
	v_cvt_pk_f16_f32 v53, v62, v63
	v_cvt_pk_f16_f32 v52, v60, v61
	v_mad_i64_i32 v[54:55], s[0:1], v54, s91, v[82:83]
	global_store_dwordx2 v[54:55], v[52:53], off
	v_add_u32_e32 v2, 48, v2
	v_add_u32_e32 v52, 0xcf, v64
	v_cndmask_b32_e64 v2, v52, v2, s[2:3]
	v_add_u32_e32 v2, v2, v89
	s_sub_i32 s27, s27, 64
	v_mad_i64_i32 v[48:49], s[0:1], v2, s91, v[82:83]
	s_cmpk_lg_i32 s27, 0xff00
	global_store_dwordx2 v[48:49], v[50:51], off
	s_cbranch_scc0 .LBB0_485

.LBB0_340:
	s_or_b64 exec, exec, s[0:1]
	s_waitcnt lgkmcnt(0)
	s_barrier
	ds_read_b128 v[52:55], v92 offset:9216
	ds_read_b128 v[60:63], v94
	ds_read_b128 v[48:51], v92
	s_nop 0
	s_nop 0
	ds_read_b128 v[68:71], v101
	ds_read_b128 v[56:59], v250 offset:16
	s_nop 0
	v_add_u32_e32 v81, v95, v103
	s_nop 0
	s_waitcnt lgkmcnt(4)
	v_cvt_f32_f16_sdwa v67, v52 dst_sel:DWORD dst_unused:UNUSED_PAD src0_sel:WORD_1
	s_nop 0
	s_waitcnt lgkmcnt(3)
	v_mul_f32_e32 v2, 0x3fb8aa3b, v60
	v_exp_f32_e32 v60, v2
	v_mul_f32_e32 v2, 0x3fb8aa3b, v61
	v_exp_f32_e32 v61, v2
	v_cvt_f32_f16_e32 v66, v52
	v_rcp_f32_e32 v64, v60
	v_add3_u32 v52, v78, v97, v247
	v_rcp_f32_e32 v65, v61
	v_cvt_f32_f16_sdwa v127, v54 dst_sel:DWORD dst_unused:UNUSED_PAD src0_sel:WORD_1
	v_cvt_f32_f16_e32 v126, v54
	v_pk_mul_f32 v[66:67], v[64:65], v[66:67]
	s_waitcnt lgkmcnt(2)
	v_cvt_f32_f16_sdwa v65, v48 dst_sel:DWORD dst_unused:UNUSED_PAD src0_sel:WORD_1
	v_cvt_f32_f16_e32 v64, v48
	s_nop 0
	s_waitcnt lgkmcnt(1)
	v_fma_mixlo_f16 v2, v68, v66, 0
	ds_write_b16 v52, v2 offset:46080
	v_fma_mixlo_f16 v2, v69, v67, 0
	v_pk_mul_f32 v[64:65], v[64:65], s[68:69] op_sel_hi:[1,0]
	ds_write_b16 v121, v2 offset:46080
	v_mul_f32_e32 v2, 0x3fb8aa3b, v62
	v_pk_mul_f32 v[64:65], v[64:65], v[60:61]
	v_exp_f32_e32 v60, v2
	v_mul_f32_e32 v2, 0x3fb8aa3b, v63
	v_exp_f32_e32 v61, v2
	v_cvt_f32_f16_sdwa v69, v53 dst_sel:DWORD dst_unused:UNUSED_PAD src0_sel:WORD_1
	v_rcp_f32_e32 v62, v60
	v_cvt_f32_f16_e32 v68, v53
	v_rcp_f32_e32 v63, v61
	v_cvt_f32_f16_sdwa v53, v49 dst_sel:DWORD dst_unused:UNUSED_PAD src0_sel:WORD_1
	v_cvt_f32_f16_e32 v52, v49
	v_cvt_pk_f16_f32 v48, v64, v65
	v_pk_mul_f32 v[68:69], v[62:63], v[68:69]
	v_pk_mul_f32 v[52:53], v[52:53], s[68:69] op_sel_hi:[1,0]
	v_fma_mixlo_f16 v2, v70, v68, 0
	ds_write_b16 v121, v2 offset:46224
	v_fma_mixlo_f16 v2, v71, v69, 0
	ds_write_b16 v121, v2 offset:46368
	s_waitcnt lgkmcnt(4)
	v_mul_f32_e32 v2, 0x3fb8aa3b, v56
	v_exp_f32_e32 v56, v2
	v_mul_f32_e32 v2, 0x3fb8aa3b, v57
	v_exp_f32_e32 v57, v2
	v_pk_mul_f32 v[52:53], v[52:53], v[60:61]
	ds_read_b128 v[60:63], v102
	v_rcp_f32_e32 v70, v56
	s_nop 0
	v_rcp_f32_e32 v71, v57
	v_cvt_pk_f16_f32 v49, v52, v53
	v_pk_mul_f32 v[70:71], v[70:71], v[126:127]
	s_nop 0
	s_waitcnt lgkmcnt(0)
	v_fma_mixlo_f16 v2, v60, v70, 0
	ds_write_b16 v121, v2 offset:46512
	v_fma_mixlo_f16 v2, v61, v71, 0
	ds_write_b16 v121, v2 offset:46656
	v_mul_f32_e32 v2, 0x3fb8aa3b, v58
	v_cvt_f32_f16_sdwa v127, v50 dst_sel:DWORD dst_unused:UNUSED_PAD src0_sel:WORD_1
	v_cvt_f32_f16_e32 v126, v50
	v_exp_f32_e32 v58, v2
	v_mul_f32_e32 v2, 0x3fb8aa3b, v59
	v_exp_f32_e32 v59, v2
	v_pk_mul_f32 v[126:127], v[126:127], s[68:69] op_sel_hi:[1,0]
	v_cvt_f32_f16_sdwa v61, v55 dst_sel:DWORD dst_unused:UNUSED_PAD src0_sel:WORD_1
	v_pk_mul_f32 v[126:127], v[126:127], v[56:57]
	v_rcp_f32_e32 v56, v58
	v_rcp_f32_e32 v57, v59
	v_cvt_f32_f16_e32 v60, v55
	v_bfe_u32 v55, v71, 16, 1
	v_add3_u32 v55, v71, v55, s34
	v_cvt_pk_f16_f32 v50, v126, v127
	v_pk_mul_f32 v[128:129], v[56:57], v[60:61]
	v_bfe_u32 v56, v70, 16, 1
	v_fma_mixlo_f16 v2, v62, v128, 0
	ds_write_b16 v121, v2 offset:46800
	v_bfe_u32 v2, v129, 16, 1
	v_bfe_u32 v54, v128, 16, 1
	v_bfe_u32 v57, v69, 16, 1
	v_bfe_u32 v60, v68, 16, 1
	v_bfe_u32 v61, v67, 16, 1
	v_bfe_u32 v62, v66, 16, 1
	v_add3_u32 v62, v66, v62, s34
	v_add3_u32 v61, v67, v61, s34
	v_add3_u32 v60, v68, v60, s34
	v_add3_u32 v66, v69, v57, s34
	v_add3_u32 v56, v70, v56, s34
	v_add3_u32 v54, v128, v54, s34
	v_add3_u32 v2, v129, v2, s34
	v_perm_b32 v57, v2, v54, s82
	v_perm_b32 v56, v55, v56, s82
	v_perm_b32 v55, v66, v60, s82
	v_perm_b32 v54, v61, v62, s82
	v_cvt_f32_f16_sdwa v61, v51 dst_sel:DWORD dst_unused:UNUSED_PAD src0_sel:WORD_1
	v_cvt_f32_f16_e32 v60, v51
	v_bfe_u32 v62, v126, 16, 1
	v_bfe_u32 v66, v53, 16, 1
	v_bfe_u32 v67, v52, 16, 1
	v_pk_mul_f32 v[60:61], v[60:61], s[68:69] op_sel_hi:[1,0]
	v_bfe_u32 v68, v65, 16, 1
	v_pk_mul_f32 v[58:59], v[60:61], v[58:59]
	v_bfe_u32 v61, v127, 16, 1
	v_bfe_u32 v2, v59, 16, 1
	v_bfe_u32 v60, v58, 16, 1
	v_cvt_pk_f16_f32 v51, v58, v59
	v_bfe_u32 v69, v64, 16, 1
	v_add3_u32 v58, v58, v60, s34
	v_add3_u32 v2, v59, v2, s34
	v_add3_u32 v64, v64, v69, s34
	v_add3_u32 v65, v65, v68, s34
	v_add3_u32 v52, v52, v67, s34
	v_add3_u32 v53, v53, v66, s34
	v_add3_u32 v62, v126, v62, s34
	v_add3_u32 v66, v127, v61, s34
	v_perm_b32 v61, v2, v58, s82
	v_fma_mixlo_f16 v2, v63, v129, 0
	v_perm_b32 v60, v66, v62, s82
	v_perm_b32 v59, v53, v52, s82
	v_perm_b32 v58, v65, v64, s82
	ds_write_b16 v121, v2 offset:46944
	ds_write_b128 v92, v[58:61] offset:18432
	ds_write_b128 v92, v[54:57] offset:27648
	ds_write_b128 v92, v[48:51] offset:36864
	v_add_u32_e32 v2, v79, v72
	s_nop 0
	s_barrier
	ds_read_b128 v[52:55], v81 offset:36864
	ds_read_b128 v[56:59], v81 offset:39168
	ds_read_b128 v[60:63], v81 offset:41472
	ds_read_b128 v[64:67], v81 offset:43776
	ds_read_b128 v[68:71], v2 offset:64
	ds_read_b128 v[134:137], v81 offset:36928
	ds_read_b128 v[138:141], v81 offset:39232
	ds_read_b128 v[142:145], v81 offset:41536
	ds_read_b128 v[48:51], v2
	s_nop 0
	s_nop 0
	s_nop 0
	s_nop 0
	s_nop 0
	s_waitcnt lgkmcnt(0)
	v_mfma_f32_16x16x32_f16 v[52:55], v[48:51], v[52:55], 0
	s_nop 0
	v_mfma_f32_16x16x32_f16 v[56:59], v[48:51], v[56:59], 0
	s_nop 0
	v_mfma_f32_16x16x32_f16 v[60:63], v[48:51], v[60:63], 0
	s_nop 0
	v_mfma_f32_16x16x32_f16 v[64:67], v[48:51], v[64:67], 0
	s_nop 0
	s_nop 0
	v_add_u32_e32 v2, v100, v72
	s_nop 0
	v_mfma_f32_16x16x32_f16 v[48:51], v[68:71], v[134:137], v[52:55]
	s_nop 2
	s_nop 0
	s_nop 0
	v_mfma_f32_16x16x32_f16 v[56:59], v[68:71], v[138:141], v[56:59]
	s_nop 0
	s_nop 0
	v_mfma_f32_16x16x32_f16 v[60:63], v[68:71], v[142:145], v[60:63]
	ds_read_b128 v[52:55], v81 offset:43840
	s_nop 0
	s_waitcnt lgkmcnt(0)
	v_mfma_f32_16x16x32_f16 v[64:67], v[68:71], v[52:55], v[64:67]
	v_mov_b32_e32 v52, 0
	v_mov_b32_e32 v68, 0
	v_mov_b32_e32 v69, 0
	v_mov_b32_e32 v70, 0
	v_mov_b32_e32 v71, 0
	s_and_saveexec_b64 s[0:1], s[6:7]
	s_cbranch_execz .LBB0_342
	v_add_u32_e32 v253, v95, v106
	ds_read_b128 v[68:71], v2 offset:18432
	ds_read_b128 v[126:129], v253 offset:27648
	v_add_u32_e32 v53, v95, v106
	s_nop 0
	s_nop 0
	s_nop 0
	s_waitcnt lgkmcnt(0)
	v_mfma_f32_16x16x32_bf16 v[68:71], v[126:129], v[68:71], 0
	ds_read_b128 v[130:133], v53 offset:27712
	ds_read_b128 v[126:129], v2 offset:18496
	s_nop 0
	s_nop 0
	s_waitcnt lgkmcnt(0)
	v_mfma_f32_16x16x32_bf16 v[68:71], v[130:133], v[126:129], v[68:71]

.LBB0_356:
	s_and_b32 s27, s26, 1
	v_lshl_add_u32 v0, s27, 13, v232
	ds_read2_b64 v[36:39], v0 offset1:32
	v_mad_u32_u24 v2, s27, v165, v233
	s_waitcnt lgkmcnt(0)
	v_pk_mul_f32 v[66:67], v[36:37], v[38:39]
	ds_read2_b64 v[38:41], v0 offset0:64 offset1:96
	s_waitcnt lgkmcnt(0)
	v_pk_mul_f32 v[64:65], v[66:67], v[38:39]
	s_nop 0
	v_pk_mul_f32 v[60:61], v[64:65], v[40:41]
	ds_read2_b64 v[38:41], v0 offset0:128 offset1:160
	s_waitcnt lgkmcnt(0)
	v_pk_mul_f32 v[54:55], v[60:61], v[38:39]
	s_nop 0
	v_pk_mul_f32 v[48:49], v[54:55], v[40:41]
	ds_read2_b64 v[38:41], v0 offset0:192 offset1:224
	v_add_u32_e32 v0, 0x800, v0
	ds_read2_b64 v[68:71], v0 offset0:128 offset1:160
	s_waitcnt lgkmcnt(1)
	v_pk_mul_f32 v[44:45], v[48:49], v[38:39]
	s_nop 0
	v_pk_mul_f32 v[38:39], v[44:45], v[40:41]
	ds_read2_b64 v[40:43], v0 offset1:32
	s_waitcnt lgkmcnt(0)
	v_pk_mul_f32 v[58:59], v[38:39], v[40:41]
	s_nop 0
	v_pk_mul_f32 v[50:51], v[58:59], v[42:43]
	ds_read2_b64 v[40:43], v0 offset0:64 offset1:96
	s_waitcnt lgkmcnt(0)
	v_pk_mul_f32 v[46:47], v[50:51], v[40:41]
	s_nop 0
	v_pk_mul_f32 v[42:43], v[46:47], v[42:43]
	v_rcp_f32_e32 v40, v38
	v_pk_mul_f32 v[62:63], v[42:43], v[68:69]
	v_rcp_f32_e32 v41, v39
	v_pk_mul_f32 v[56:57], v[62:63], v[70:71]
	ds_read2_b64 v[68:71], v0 offset0:192 offset1:224
	s_waitcnt lgkmcnt(0)
	v_pk_mul_f32 v[52:53], v[56:57], v[68:69]
	s_nop 0
	v_pk_mul_f32 v[0:1], v[52:53], v[70:71]
	s_and_saveexec_b64 s[28:29], s[4:5]
	s_cbranch_execz .LBB0_358
	v_lshl_add_u32 v253, v177, 1, v2
	ds_read2st64_b32 v[72:73], v253 offset0:96 offset1:112
	ds_read2st64_b32 v[68:69], v253 offset0:64 offset1:80
	v_lshl_add_u32 v74, v177, 1, v2
	s_nop 0
	ds_read_b32 v84, v74 offset:32768
	s_nop 0
	v_rcp_f32_e32 v70, v36
	v_rcp_f32_e32 v71, v37
	s_nop 0
	s_nop 0
	s_waitcnt lgkmcnt(2)
	v_cvt_f32_f16_e32 v78, v73
	v_cvt_f32_f16_sdwa v79, v73 dst_sel:DWORD dst_unused:UNUSED_PAD src0_sel:WORD_1
	v_lshl_add_u32 v253, v184, 1, v2
	ds_read2st64_b32 v[148:149], v253 offset0:64 offset1:80
	s_waitcnt lgkmcnt(2)
	v_cvt_f32_f16_e32 v74, v68
	v_cvt_f32_f16_sdwa v75, v68 dst_sel:DWORD dst_unused:UNUSED_PAD src0_sel:WORD_1
	v_cvt_f32_f16_e32 v76, v72
	ds_read2st64_b32 v[240:241], v253 offset0:96 offset1:112
	v_cvt_f32_f16_sdwa v77, v72 dst_sel:DWORD dst_unused:UNUSED_PAD src0_sel:WORD_1
	v_cvt_f32_f16_e32 v72, v69
	v_cvt_f32_f16_sdwa v73, v69 dst_sel:DWORD dst_unused:UNUSED_PAD src0_sel:WORD_1
	v_pk_mul_f32 v[78:79], v[36:37], v[78:79]
	v_pk_mul_f32 v[76:77], v[70:71], v[76:77]
	v_pk_mul_f32 v[70:71], v[70:71], v[74:75]
	v_pk_mul_f32 v[72:73], v[40:41], v[72:73]
	v_pk_mul_f32 v[74:75], v[40:41], v[78:79]
	v_cvt_pk_f16_f32 v68, v78, v79
	v_pk_mul_f32 v[80:81], v[38:39], v[76:77]
	v_pk_mul_f32 v[82:83], v[38:39], v[70:71]
	ds_write2st64_b32 v183, v69, v68 offset1:18
	v_cvt_pk_f16_f32 v68, v72, v73
	v_cvt_pk_f16_f32 v69, v74, v75
	v_pk_mul_f32 v[76:77], v[0:1], v[76:77]
	ds_write2st64_b32 v183, v68, v69 offset0:36 offset1:54
	v_cvt_pk_f16_f32 v68, v80, v81
	v_cvt_pk_f16_f32 v69, v82, v83
	ds_write2st64_b32 v183, v68, v69 offset0:72 offset1:90
	v_cvt_f16_f32_e32 v68, v76
	v_pk_mul_f32 v[70:71], v[0:1], v[70:71]
	v_cvt_f16_f32_e32 v69, v77
	v_cvt_f16_f32_e32 v70, v70
	v_cvt_f16_f32_e32 v71, v71
	ds_write_b16 v178, v68
	ds_write_b16 v178, v69 offset:40
	ds_write_b16 v178, v70 offset:5120
	ds_write_b16 v178, v71 offset:5160
	s_waitcnt lgkmcnt(9)
	ds_write_b16 v178, v84 offset:10240
	v_lshl_add_u32 v74, v184, 1, v2
	s_nop 0
	s_nop 0
	ds_read_b32 v82, v74 offset:32768
	v_rcp_f32_e32 v70, v66
	v_rcp_f32_e32 v71, v67
	s_waitcnt lgkmcnt(10)
	v_cvt_f32_f16_e32 v76, v149
	v_cvt_f32_f16_sdwa v77, v149 dst_sel:DWORD dst_unused:UNUSED_PAD src0_sel:WORD_1
	s_waitcnt lgkmcnt(9)
	v_cvt_f32_f16_e32 v80, v241
	v_cvt_f32_f16_sdwa v81, v241 dst_sel:DWORD dst_unused:UNUSED_PAD src0_sel:WORD_1
	v_lshl_add_u32 v253, v186, 1, v2
	ds_read2st64_b32 v[242:243], v253 offset0:64 offset1:80
	v_cvt_f32_f16_e32 v74, v148
	v_cvt_f32_f16_e32 v78, v240
	v_cvt_f32_f16_sdwa v79, v240 dst_sel:DWORD dst_unused:UNUSED_PAD src0_sel:WORD_1
	ds_read2st64_b32 v[240:241], v253 offset0:96 offset1:112
	v_cvt_f32_f16_sdwa v75, v148 dst_sel:DWORD dst_unused:UNUSED_PAD src0_sel:WORD_1
	v_pk_mul_f32 v[36:37], v[36:37], v[76:77]
	v_pk_mul_f32 v[68:69], v[66:67], v[80:81]
	v_pk_mul_f32 v[72:73], v[70:71], v[78:79]
	v_pk_mul_f32 v[70:71], v[70:71], v[74:75]
	v_pk_mul_f32 v[74:75], v[40:41], v[36:37]
	v_pk_mul_f32 v[76:77], v[40:41], v[68:69]
	v_cvt_pk_f16_f32 v36, v36, v37
	v_cvt_pk_f16_f32 v37, v68, v69
	v_pk_mul_f32 v[78:79], v[38:39], v[72:73]
	v_pk_mul_f32 v[80:81], v[38:39], v[70:71]
	ds_write2st64_b32 v185, v36, v37 offset1:18
	v_cvt_pk_f16_f32 v36, v74, v75
	v_cvt_pk_f16_f32 v37, v76, v77
	v_pk_mul_f32 v[72:73], v[0:1], v[72:73]
	ds_write2st64_b32 v185, v36, v37 offset0:36 offset1:54
	v_cvt_pk_f16_f32 v36, v78, v79
	v_cvt_pk_f16_f32 v37, v80, v81
	ds_write2st64_b32 v185, v36, v37 offset0:72 offset1:90
	v_cvt_f16_f32_e32 v36, v72
	v_pk_mul_f32 v[70:71], v[0:1], v[70:71]
	v_cvt_f16_f32_e32 v37, v73
	v_cvt_f16_f32_e32 v68, v70
	v_cvt_f16_f32_e32 v69, v71
	ds_write_b16 v178, v36 offset:2
	s_waitcnt lgkmcnt(14)
	ds_write_b16 v178, v37 offset:42
	s_waitcnt lgkmcnt(14)
	ds_write_b16 v178, v68 offset:5122
	s_waitcnt lgkmcnt(14)
	ds_write_b16 v178, v69 offset:5162
	s_waitcnt lgkmcnt(9)
	ds_write_b16 v178, v82 offset:10242
	v_lshl_add_u32 v72, v186, 1, v2
	s_nop 0
	s_nop 0
	ds_read_b32 v80, v72 offset:32768
	v_rcp_f32_e32 v68, v64
	v_rcp_f32_e32 v69, v65
	s_waitcnt lgkmcnt(10)
	v_cvt_f32_f16_e32 v74, v243
	v_cvt_f32_f16_sdwa v75, v243 dst_sel:DWORD dst_unused:UNUSED_PAD src0_sel:WORD_1
	s_waitcnt lgkmcnt(9)
	v_cvt_f32_f16_e32 v78, v241
	v_cvt_f32_f16_sdwa v79, v241 dst_sel:DWORD dst_unused:UNUSED_PAD src0_sel:WORD_1
	v_lshl_add_u32 v253, v188, 1, v2
	ds_read2st64_b32 v[148:149], v253 offset0:64 offset1:80
	v_cvt_f32_f16_e32 v72, v242
	v_cvt_f32_f16_e32 v76, v240
	v_cvt_f32_f16_sdwa v77, v240 dst_sel:DWORD dst_unused:UNUSED_PAD src0_sel:WORD_1
	ds_read2st64_b32 v[240:241], v253 offset0:96 offset1:112
	v_cvt_f32_f16_sdwa v73, v242 dst_sel:DWORD dst_unused:UNUSED_PAD src0_sel:WORD_1
	v_pk_mul_f32 v[36:37], v[66:67], v[74:75]
	v_pk_mul_f32 v[66:67], v[64:65], v[78:79]
	v_pk_mul_f32 v[70:71], v[68:69], v[76:77]
	v_pk_mul_f32 v[68:69], v[68:69], v[72:73]
	v_pk_mul_f32 v[72:73], v[40:41], v[36:37]
	v_pk_mul_f32 v[74:75], v[40:41], v[66:67]
	v_cvt_pk_f16_f32 v36, v36, v37
	v_cvt_pk_f16_f32 v37, v66, v67
	v_pk_mul_f32 v[76:77], v[38:39], v[70:71]
	v_pk_mul_f32 v[78:79], v[38:39], v[68:69]
	ds_write2st64_b32 v187, v36, v37 offset1:18
	v_cvt_pk_f16_f32 v36, v72, v73
	v_cvt_pk_f16_f32 v37, v74, v75
	v_pk_mul_f32 v[70:71], v[0:1], v[70:71]
	ds_write2st64_b32 v187, v36, v37 offset0:36 offset1:54
	v_cvt_pk_f16_f32 v36, v76, v77
	v_cvt_pk_f16_f32 v37, v78, v79
	ds_write2st64_b32 v187, v36, v37 offset0:72 offset1:90
	v_cvt_f16_f32_e32 v36, v70
	v_pk_mul_f32 v[68:69], v[0:1], v[68:69]
	v_cvt_f16_f32_e32 v37, v71
	v_cvt_f16_f32_e32 v66, v68
	v_cvt_f16_f32_e32 v67, v69
	ds_write_b16 v178, v36 offset:4
	s_waitcnt lgkmcnt(14)
	ds_write_b16 v178, v37 offset:44
	s_waitcnt lgkmcnt(14)
	ds_write_b16 v178, v66 offset:5124
	s_waitcnt lgkmcnt(14)
	ds_write_b16 v178, v67 offset:5164
	s_waitcnt lgkmcnt(9)
	ds_write_b16 v178, v80 offset:10244
	v_lshl_add_u32 v70, v188, 1, v2
	s_nop 0
	s_nop 0
	ds_read_b32 v78, v70 offset:32768
	v_rcp_f32_e32 v66, v60
	v_rcp_f32_e32 v67, v61
	s_waitcnt lgkmcnt(10)
	v_cvt_f32_f16_e32 v72, v149
	v_cvt_f32_f16_sdwa v73, v149 dst_sel:DWORD dst_unused:UNUSED_PAD src0_sel:WORD_1
	s_waitcnt lgkmcnt(9)
	v_cvt_f32_f16_e32 v76, v241
	v_cvt_f32_f16_sdwa v77, v241 dst_sel:DWORD dst_unused:UNUSED_PAD src0_sel:WORD_1
	v_cvt_f32_f16_e32 v70, v148
	v_cvt_f32_f16_e32 v74, v240
	v_cvt_f32_f16_sdwa v75, v240 dst_sel:DWORD dst_unused:UNUSED_PAD src0_sel:WORD_1
	v_cvt_f32_f16_sdwa v71, v148 dst_sel:DWORD dst_unused:UNUSED_PAD src0_sel:WORD_1
	v_pk_mul_f32 v[36:37], v[64:65], v[72:73]
	v_pk_mul_f32 v[64:65], v[60:61], v[76:77]
	v_pk_mul_f32 v[68:69], v[66:67], v[74:75]
	v_pk_mul_f32 v[66:67], v[66:67], v[70:71]
	v_pk_mul_f32 v[70:71], v[40:41], v[36:37]
	v_pk_mul_f32 v[72:73], v[40:41], v[64:65]
	v_cvt_pk_f16_f32 v36, v36, v37
	v_cvt_pk_f16_f32 v37, v64, v65
	v_pk_mul_f32 v[74:75], v[38:39], v[68:69]
	v_pk_mul_f32 v[76:77], v[38:39], v[66:67]
	ds_write2st64_b32 v189, v36, v37 offset1:18
	v_cvt_pk_f16_f32 v36, v70, v71
	v_cvt_pk_f16_f32 v37, v72, v73
	v_pk_mul_f32 v[68:69], v[0:1], v[68:69]
	ds_write2st64_b32 v189, v36, v37 offset0:36 offset1:54
	v_cvt_pk_f16_f32 v36, v74, v75
	v_cvt_pk_f16_f32 v37, v76, v77
	ds_write2st64_b32 v189, v36, v37 offset0:72 offset1:90
	v_cvt_f16_f32_e32 v36, v68
	v_pk_mul_f32 v[66:67], v[0:1], v[66:67]
	v_cvt_f16_f32_e32 v37, v69
	v_cvt_f16_f32_e32 v64, v66
	v_cvt_f16_f32_e32 v65, v67
	ds_write_b16 v178, v36 offset:6
	ds_write_b16 v178, v37 offset:46
	ds_write_b16 v178, v64 offset:5126
	s_waitcnt lgkmcnt(14)
	ds_write_b16 v178, v65 offset:5166
	s_nop 0
	s_waitcnt lgkmcnt(7)
	ds_write_b16 v178, v78 offset:10246
	v_perm_b32 v36, v82, v84, s82
	v_perm_b32 v37, v78, v80, s82
	ds_write_b64 v178, v[36:37] offset:10280

.LBB0_369:
	v_cmp_lt_i32_e32 vcc, 2, v176
	s_and_saveexec_b64 s[30:31], vcc
	s_xor_b64 s[70:71], exec, s[30:31]
	s_cbranch_execz .LBB0_371
	v_lshl_add_u32 v253, v206, 1, v2
	ds_read2st64_b32 v[36:37], v253 offset0:64 offset1:80
	ds_read2st64_b32 v[46:47], v253 offset0:96 offset1:112
	v_lshl_add_u32 v48, v206, 1, v2
	s_nop 0
	s_nop 0
	ds_read_b32 v60, v48 offset:32768
	v_rcp_f32_e32 v44, v62
	v_rcp_f32_e32 v45, v63
	s_nop 0
	s_waitcnt lgkmcnt(1)
	v_cvt_f32_f16_e32 v58, v47
	v_cvt_f32_f16_e32 v50, v37
	v_cvt_f32_f16_sdwa v51, v37 dst_sel:DWORD dst_unused:UNUSED_PAD src0_sel:WORD_1
	v_cvt_f32_f16_sdwa v59, v47 dst_sel:DWORD dst_unused:UNUSED_PAD src0_sel:WORD_1
	v_lshl_add_u32 v253, v208, 1, v2
	ds_read2st64_b32 v[148:149], v253 offset0:64 offset1:80
	v_cvt_f32_f16_e32 v48, v36
	v_cvt_f32_f16_e32 v54, v46
	v_cvt_f32_f16_sdwa v55, v46 dst_sel:DWORD dst_unused:UNUSED_PAD src0_sel:WORD_1
	ds_read2st64_b32 v[240:241], v253 offset0:96 offset1:112
	v_cvt_f32_f16_sdwa v49, v36 dst_sel:DWORD dst_unused:UNUSED_PAD src0_sel:WORD_1
	v_pk_mul_f32 v[36:37], v[42:43], v[50:51]
	v_pk_mul_f32 v[42:43], v[62:63], v[58:59]
	v_pk_mul_f32 v[46:47], v[44:45], v[54:55]
	v_pk_mul_f32 v[44:45], v[44:45], v[48:49]
	v_pk_mul_f32 v[48:49], v[40:41], v[36:37]
	v_pk_mul_f32 v[50:51], v[40:41], v[42:43]
	v_cvt_pk_f16_f32 v36, v36, v37
	v_cvt_pk_f16_f32 v37, v42, v43
	v_pk_mul_f32 v[54:55], v[38:39], v[46:47]
	v_pk_mul_f32 v[58:59], v[38:39], v[44:45]
	ds_write2st64_b32 v207, v36, v37 offset1:18
	v_cvt_pk_f16_f32 v36, v48, v49
	v_cvt_pk_f16_f32 v37, v50, v51
	v_pk_mul_f32 v[46:47], v[0:1], v[46:47]
	ds_write2st64_b32 v207, v36, v37 offset0:36 offset1:54
	v_cvt_pk_f16_f32 v36, v54, v55
	v_cvt_pk_f16_f32 v37, v58, v59
	ds_write2st64_b32 v207, v36, v37 offset0:72 offset1:90
	v_cvt_f16_f32_e32 v36, v46
	v_pk_mul_f32 v[44:45], v[0:1], v[44:45]
	v_cvt_f16_f32_e32 v37, v47
	v_cvt_f16_f32_e32 v42, v44
	v_cvt_f16_f32_e32 v43, v45
	ds_write_b16 v178, v36 offset:24
	ds_write_b16 v178, v37 offset:64
	ds_write_b16 v178, v42 offset:5144
	ds_write_b16 v178, v43 offset:5184
	s_waitcnt lgkmcnt(9)
	ds_write_b16 v178, v60 offset:10264
	v_lshl_add_u32 v46, v208, 1, v2
	s_nop 0
	s_nop 0
	ds_read_b32 v61, v46 offset:32768
	v_rcp_f32_e32 v42, v56
	v_rcp_f32_e32 v43, v57
	s_waitcnt lgkmcnt(10)
	v_cvt_f32_f16_e32 v48, v149
	v_cvt_f32_f16_sdwa v49, v149 dst_sel:DWORD dst_unused:UNUSED_PAD src0_sel:WORD_1
	s_waitcnt lgkmcnt(9)
	v_cvt_f32_f16_e32 v54, v241
	v_cvt_f32_f16_sdwa v55, v241 dst_sel:DWORD dst_unused:UNUSED_PAD src0_sel:WORD_1
	v_cvt_f32_f16_e32 v46, v148
	v_lshl_add_u32 v253, v210, 1, v2
	ds_read2st64_b32 v[242:243], v253 offset0:64 offset1:80
	v_cvt_f32_f16_e32 v50, v240
	v_cvt_f32_f16_sdwa v51, v240 dst_sel:DWORD dst_unused:UNUSED_PAD src0_sel:WORD_1
	v_cvt_f32_f16_sdwa v47, v148 dst_sel:DWORD dst_unused:UNUSED_PAD src0_sel:WORD_1
	ds_read2st64_b32 v[148:149], v253 offset0:96 offset1:112
	v_pk_mul_f32 v[36:37], v[62:63], v[48:49]
	v_pk_mul_f32 v[44:45], v[56:57], v[54:55]
	v_pk_mul_f32 v[48:49], v[42:43], v[50:51]
	v_pk_mul_f32 v[42:43], v[42:43], v[46:47]
	v_pk_mul_f32 v[46:47], v[40:41], v[36:37]
	v_pk_mul_f32 v[50:51], v[40:41], v[44:45]
	v_cvt_pk_f16_f32 v36, v36, v37
	v_cvt_pk_f16_f32 v37, v44, v45
	v_pk_mul_f32 v[54:55], v[38:39], v[48:49]
	v_pk_mul_f32 v[58:59], v[38:39], v[42:43]
	ds_write2st64_b32 v209, v36, v37 offset1:18
	v_cvt_pk_f16_f32 v36, v46, v47
	v_cvt_pk_f16_f32 v37, v50, v51
	v_pk_mul_f32 v[48:49], v[0:1], v[48:49]
	ds_write2st64_b32 v209, v36, v37 offset0:36 offset1:54
	v_cvt_pk_f16_f32 v36, v54, v55
	v_cvt_pk_f16_f32 v37, v58, v59
	ds_write2st64_b32 v209, v36, v37 offset0:72 offset1:90
	v_cvt_f16_f32_e32 v36, v48
	v_pk_mul_f32 v[42:43], v[0:1], v[42:43]
	v_cvt_f16_f32_e32 v37, v49
	v_cvt_f16_f32_e32 v42, v42
	v_cvt_f16_f32_e32 v43, v43
	ds_write_b16 v178, v36 offset:26
	s_waitcnt lgkmcnt(14)
	ds_write_b16 v178, v37 offset:66
	s_waitcnt lgkmcnt(14)
	ds_write_b16 v178, v42 offset:5146
	s_waitcnt lgkmcnt(14)
	ds_write_b16 v178, v43 offset:5186
	s_waitcnt lgkmcnt(9)
	ds_write_b16 v178, v61 offset:10266
	v_lshl_add_u32 v46, v210, 1, v2
	s_nop 0
	s_nop 0
	ds_read_b32 v58, v46 offset:32768
	v_rcp_f32_e32 v42, v52
	v_rcp_f32_e32 v43, v53
	v_lshl_add_u32 v2, v212, 1, v2
	s_nop 0
	s_waitcnt lgkmcnt(10)
	v_cvt_f32_f16_e32 v48, v243
	v_cvt_f32_f16_sdwa v49, v243 dst_sel:DWORD dst_unused:UNUSED_PAD src0_sel:WORD_1
	s_nop 0
	s_waitcnt lgkmcnt(9)
	v_cvt_f32_f16_e32 v54, v149
	ds_read2st64_b32 v[240:241], v2 offset0:64 offset1:80
	v_cvt_f32_f16_sdwa v55, v149 dst_sel:DWORD dst_unused:UNUSED_PAD src0_sel:WORD_1
	v_cvt_f32_f16_e32 v46, v242
	v_cvt_f32_f16_e32 v50, v148
	ds_read2st64_b32 v[244:245], v2 offset0:96 offset1:112
	v_cvt_f32_f16_sdwa v51, v148 dst_sel:DWORD dst_unused:UNUSED_PAD src0_sel:WORD_1
	v_cvt_f32_f16_sdwa v47, v242 dst_sel:DWORD dst_unused:UNUSED_PAD src0_sel:WORD_1
	v_pk_mul_f32 v[36:37], v[56:57], v[48:49]
	v_pk_mul_f32 v[44:45], v[52:53], v[54:55]
	v_pk_mul_f32 v[48:49], v[42:43], v[50:51]
	v_pk_mul_f32 v[42:43], v[42:43], v[46:47]
	v_pk_mul_f32 v[46:47], v[40:41], v[36:37]
	v_pk_mul_f32 v[50:51], v[40:41], v[44:45]
	v_cvt_pk_f16_f32 v36, v36, v37
	v_cvt_pk_f16_f32 v37, v44, v45
	v_pk_mul_f32 v[54:55], v[38:39], v[48:49]
	v_pk_mul_f32 v[56:57], v[38:39], v[42:43]
	ds_write2st64_b32 v211, v36, v37 offset1:18
	v_cvt_pk_f16_f32 v36, v46, v47
	v_cvt_pk_f16_f32 v37, v50, v51
	v_pk_mul_f32 v[48:49], v[0:1], v[48:49]
	ds_write2st64_b32 v211, v36, v37 offset0:36 offset1:54
	v_cvt_pk_f16_f32 v36, v54, v55
	v_cvt_pk_f16_f32 v37, v56, v57
	ds_write2st64_b32 v211, v36, v37 offset0:72 offset1:90
	v_cvt_f16_f32_e32 v36, v48
	v_pk_mul_f32 v[42:43], v[0:1], v[42:43]
	v_cvt_f16_f32_e32 v37, v49
	v_cvt_f16_f32_e32 v42, v42
	v_cvt_f16_f32_e32 v43, v43
	ds_write_b16 v178, v36 offset:28
	s_waitcnt lgkmcnt(14)
	ds_write_b16 v178, v37 offset:68
	s_waitcnt lgkmcnt(14)
	ds_write_b16 v178, v42 offset:5148
	s_waitcnt lgkmcnt(14)
	ds_write_b16 v178, v43 offset:5188
	s_waitcnt lgkmcnt(9)
	ds_write_b16 v178, v58 offset:10268
	ds_read_b32 v2, v2 offset:32768
	v_rcp_f32_e32 v42, v0
	v_rcp_f32_e32 v43, v1
	s_waitcnt lgkmcnt(10)
	v_cvt_f32_f16_e32 v48, v241
	v_cvt_f32_f16_sdwa v49, v241 dst_sel:DWORD dst_unused:UNUSED_PAD src0_sel:WORD_1
	s_waitcnt lgkmcnt(9)
	v_cvt_f32_f16_e32 v54, v245
	v_cvt_f32_f16_sdwa v55, v245 dst_sel:DWORD dst_unused:UNUSED_PAD src0_sel:WORD_1
	v_cvt_f32_f16_e32 v46, v240
	v_cvt_f32_f16_e32 v50, v244
	v_cvt_f32_f16_sdwa v51, v244 dst_sel:DWORD dst_unused:UNUSED_PAD src0_sel:WORD_1
	v_cvt_f32_f16_sdwa v47, v240 dst_sel:DWORD dst_unused:UNUSED_PAD src0_sel:WORD_1
	v_pk_mul_f32 v[36:37], v[52:53], v[48:49]
	v_pk_mul_f32 v[44:45], v[0:1], v[54:55]
	v_pk_mul_f32 v[48:49], v[42:43], v[50:51]
	v_pk_mul_f32 v[42:43], v[42:43], v[46:47]
	v_pk_mul_f32 v[46:47], v[40:41], v[36:37]
	v_pk_mul_f32 v[40:41], v[40:41], v[44:45]
	v_cvt_pk_f16_f32 v36, v36, v37
	v_cvt_pk_f16_f32 v37, v44, v45
	v_pk_mul_f32 v[50:51], v[38:39], v[48:49]
	v_pk_mul_f32 v[38:39], v[38:39], v[42:43]
	ds_write2st64_b32 v213, v36, v37 offset1:18
	v_cvt_pk_f16_f32 v36, v46, v47
	v_cvt_pk_f16_f32 v37, v40, v41
	v_pk_mul_f32 v[48:49], v[0:1], v[48:49]
	ds_write2st64_b32 v213, v36, v37 offset0:36 offset1:54
	v_cvt_pk_f16_f32 v36, v50, v51
	v_cvt_pk_f16_f32 v37, v38, v39
	ds_write2st64_b32 v213, v36, v37 offset0:72 offset1:90
	v_cvt_f16_f32_e32 v36, v48
	v_pk_mul_f32 v[42:43], v[0:1], v[42:43]
	v_cvt_f16_f32_e32 v37, v49
	v_cvt_f16_f32_e32 v38, v42
	v_cvt_f16_f32_e32 v39, v43
	ds_write_b16 v178, v36 offset:30
	ds_write_b16 v178, v37 offset:70
	ds_write_b16 v178, v38 offset:5150
	s_waitcnt lgkmcnt(14)
	ds_write_b16 v178, v39 offset:5190
	s_nop 0
	s_waitcnt lgkmcnt(7)
	ds_write_b16 v178, v2 offset:10270
	v_perm_b32 v36, v61, v60, s82
	v_perm_b32 v37, v2, v58, s82
	ds_write_b64 v178, v[36:37] offset:10304
.LBB0_371:
	s_andn2_saveexec_b64 s[70:71], s[70:71]
	s_cbranch_execz .LBB0_373
	v_lshl_add_u32 v253, v198, 1, v2
	ds_read2st64_b32 v[36:37], v253 offset0:64 offset1:80
	ds_read2st64_b32 v[48:49], v253 offset0:96 offset1:112
	v_lshl_add_u32 v52, v198, 1, v2
	s_nop 0
	s_nop 0
	ds_read_b32 v64, v52 offset:32768
	v_rcp_f32_e32 v44, v58
	v_rcp_f32_e32 v45, v59
	s_nop 0
	s_waitcnt lgkmcnt(1)
	v_cvt_f32_f16_e32 v60, v49
	v_cvt_f32_f16_e32 v54, v37
	v_cvt_f32_f16_sdwa v55, v37 dst_sel:DWORD dst_unused:UNUSED_PAD src0_sel:WORD_1
	v_cvt_f32_f16_sdwa v61, v49 dst_sel:DWORD dst_unused:UNUSED_PAD src0_sel:WORD_1
	v_lshl_add_u32 v253, v200, 1, v2
	ds_read2st64_b32 v[148:149], v253 offset0:64 offset1:80
	v_cvt_f32_f16_e32 v52, v36
	v_cvt_f32_f16_e32 v56, v48
	v_cvt_f32_f16_sdwa v57, v48 dst_sel:DWORD dst_unused:UNUSED_PAD src0_sel:WORD_1
	ds_read2st64_b32 v[240:241], v253 offset0:96 offset1:112
	v_cvt_f32_f16_sdwa v53, v36 dst_sel:DWORD dst_unused:UNUSED_PAD src0_sel:WORD_1
	v_pk_mul_f32 v[36:37], v[38:39], v[54:55]
	v_pk_mul_f32 v[48:49], v[58:59], v[60:61]
	v_pk_mul_f32 v[54:55], v[44:45], v[56:57]
	v_pk_mul_f32 v[44:45], v[44:45], v[52:53]
	v_pk_mul_f32 v[52:53], v[40:41], v[36:37]
	v_pk_mul_f32 v[56:57], v[40:41], v[48:49]
	v_cvt_pk_f16_f32 v36, v36, v37
	v_cvt_pk_f16_f32 v37, v48, v49
	v_pk_mul_f32 v[60:61], v[38:39], v[54:55]
	v_pk_mul_f32 v[62:63], v[38:39], v[44:45]
	ds_write2st64_b32 v199, v36, v37 offset1:18
	v_cvt_pk_f16_f32 v36, v52, v53
	v_cvt_pk_f16_f32 v37, v56, v57
	v_pk_mul_f32 v[54:55], v[0:1], v[54:55]
	ds_write2st64_b32 v199, v36, v37 offset0:36 offset1:54
	v_cvt_pk_f16_f32 v36, v60, v61
	v_cvt_pk_f16_f32 v37, v62, v63
	ds_write2st64_b32 v199, v36, v37 offset0:72 offset1:90
	v_cvt_f16_f32_e32 v36, v54
	v_pk_mul_f32 v[44:45], v[0:1], v[44:45]
	v_cvt_f16_f32_e32 v37, v55
	v_cvt_f16_f32_e32 v44, v44
	v_cvt_f16_f32_e32 v45, v45
	ds_write_b16 v178, v36 offset:16
	ds_write_b16 v178, v37 offset:56
	ds_write_b16 v178, v44 offset:5136
	ds_write_b16 v178, v45 offset:5176
	s_waitcnt lgkmcnt(9)
	ds_write_b16 v178, v64 offset:10256
	v_lshl_add_u32 v52, v200, 1, v2
	s_nop 0
	s_nop 0
	ds_read_b32 v62, v52 offset:32768
	v_rcp_f32_e32 v44, v50
	v_rcp_f32_e32 v45, v51
	s_waitcnt lgkmcnt(10)
	v_cvt_f32_f16_e32 v54, v149
	v_cvt_f32_f16_sdwa v55, v149 dst_sel:DWORD dst_unused:UNUSED_PAD src0_sel:WORD_1
	s_waitcnt lgkmcnt(9)
	v_cvt_f32_f16_e32 v60, v241
	v_cvt_f32_f16_sdwa v61, v241 dst_sel:DWORD dst_unused:UNUSED_PAD src0_sel:WORD_1
	v_cvt_f32_f16_e32 v52, v148
	v_lshl_add_u32 v253, v202, 1, v2
	ds_read2st64_b32 v[242:243], v253 offset0:64 offset1:80
	v_cvt_f32_f16_e32 v56, v240
	v_cvt_f32_f16_sdwa v57, v240 dst_sel:DWORD dst_unused:UNUSED_PAD src0_sel:WORD_1
	v_cvt_f32_f16_sdwa v53, v148 dst_sel:DWORD dst_unused:UNUSED_PAD src0_sel:WORD_1
	ds_read2st64_b32 v[148:149], v253 offset0:96 offset1:112
	v_pk_mul_f32 v[36:37], v[58:59], v[54:55]
	v_pk_mul_f32 v[48:49], v[50:51], v[60:61]
	v_pk_mul_f32 v[54:55], v[44:45], v[56:57]
	v_pk_mul_f32 v[44:45], v[44:45], v[52:53]
	v_pk_mul_f32 v[52:53], v[40:41], v[36:37]
	v_pk_mul_f32 v[56:57], v[40:41], v[48:49]
	v_cvt_pk_f16_f32 v36, v36, v37
	v_cvt_pk_f16_f32 v37, v48, v49
	v_pk_mul_f32 v[58:59], v[38:39], v[54:55]
	v_pk_mul_f32 v[60:61], v[38:39], v[44:45]
	ds_write2st64_b32 v201, v36, v37 offset1:18
	v_cvt_pk_f16_f32 v36, v52, v53
	v_cvt_pk_f16_f32 v37, v56, v57
	v_pk_mul_f32 v[54:55], v[0:1], v[54:55]
	ds_write2st64_b32 v201, v36, v37 offset0:36 offset1:54
	v_cvt_pk_f16_f32 v36, v58, v59
	v_cvt_pk_f16_f32 v37, v60, v61
	ds_write2st64_b32 v201, v36, v37 offset0:72 offset1:90
	v_cvt_f16_f32_e32 v36, v54
	v_pk_mul_f32 v[44:45], v[0:1], v[44:45]
	v_cvt_f16_f32_e32 v37, v55
	v_cvt_f16_f32_e32 v44, v44
	v_cvt_f16_f32_e32 v45, v45
	ds_write_b16 v178, v36 offset:18
	s_waitcnt lgkmcnt(14)
	ds_write_b16 v178, v37 offset:58
	s_waitcnt lgkmcnt(14)
	ds_write_b16 v178, v44 offset:5138
	s_waitcnt lgkmcnt(14)
	ds_write_b16 v178, v45 offset:5178
	s_waitcnt lgkmcnt(9)
	ds_write_b16 v178, v62 offset:10258
	v_lshl_add_u32 v52, v202, 1, v2
	s_nop 0
	s_nop 0
	ds_read_b32 v60, v52 offset:32768
	v_rcp_f32_e32 v44, v46
	v_rcp_f32_e32 v45, v47
	v_lshl_add_u32 v2, v204, 1, v2
	s_nop 0
	s_waitcnt lgkmcnt(10)
	v_cvt_f32_f16_e32 v54, v243
	v_cvt_f32_f16_sdwa v55, v243 dst_sel:DWORD dst_unused:UNUSED_PAD src0_sel:WORD_1
	s_nop 0
	s_waitcnt lgkmcnt(9)
	v_cvt_f32_f16_e32 v58, v149
	ds_read2st64_b32 v[240:241], v2 offset0:64 offset1:80
	v_cvt_f32_f16_sdwa v59, v149 dst_sel:DWORD dst_unused:UNUSED_PAD src0_sel:WORD_1
	v_cvt_f32_f16_e32 v52, v242
	v_cvt_f32_f16_e32 v56, v148
	ds_read2st64_b32 v[244:245], v2 offset0:96 offset1:112
	v_cvt_f32_f16_sdwa v57, v148 dst_sel:DWORD dst_unused:UNUSED_PAD src0_sel:WORD_1
	v_cvt_f32_f16_sdwa v53, v242 dst_sel:DWORD dst_unused:UNUSED_PAD src0_sel:WORD_1
	v_pk_mul_f32 v[36:37], v[50:51], v[54:55]
	v_pk_mul_f32 v[48:49], v[46:47], v[58:59]
	v_pk_mul_f32 v[50:51], v[44:45], v[56:57]
	v_pk_mul_f32 v[44:45], v[44:45], v[52:53]
	v_pk_mul_f32 v[52:53], v[40:41], v[36:37]
	v_pk_mul_f32 v[54:55], v[40:41], v[48:49]
	v_cvt_pk_f16_f32 v36, v36, v37
	v_cvt_pk_f16_f32 v37, v48, v49
	v_pk_mul_f32 v[56:57], v[38:39], v[50:51]
	v_pk_mul_f32 v[58:59], v[38:39], v[44:45]
	ds_write2st64_b32 v203, v36, v37 offset1:18
	v_cvt_pk_f16_f32 v36, v52, v53
	v_cvt_pk_f16_f32 v37, v54, v55
	v_pk_mul_f32 v[50:51], v[0:1], v[50:51]
	ds_write2st64_b32 v203, v36, v37 offset0:36 offset1:54
	v_cvt_pk_f16_f32 v36, v56, v57
	v_cvt_pk_f16_f32 v37, v58, v59
	ds_write2st64_b32 v203, v36, v37 offset0:72 offset1:90
	v_cvt_f16_f32_e32 v36, v50
	v_pk_mul_f32 v[44:45], v[0:1], v[44:45]
	v_cvt_f16_f32_e32 v37, v51
	v_cvt_f16_f32_e32 v44, v44
	v_cvt_f16_f32_e32 v45, v45
	ds_write_b16 v178, v36 offset:20
	s_waitcnt lgkmcnt(14)
	ds_write_b16 v178, v37 offset:60
	s_waitcnt lgkmcnt(14)
	ds_write_b16 v178, v44 offset:5140
	s_waitcnt lgkmcnt(14)
	ds_write_b16 v178, v45 offset:5180
	s_waitcnt lgkmcnt(9)
	ds_write_b16 v178, v60 offset:10260
	ds_read_b32 v2, v2 offset:32768
	v_rcp_f32_e32 v44, v42
	v_rcp_f32_e32 v45, v43
	s_waitcnt lgkmcnt(10)
	v_cvt_f32_f16_e32 v52, v241
	v_cvt_f32_f16_sdwa v53, v241 dst_sel:DWORD dst_unused:UNUSED_PAD src0_sel:WORD_1
	s_waitcnt lgkmcnt(9)
	v_cvt_f32_f16_e32 v56, v245
	v_cvt_f32_f16_sdwa v57, v245 dst_sel:DWORD dst_unused:UNUSED_PAD src0_sel:WORD_1
	v_cvt_f32_f16_e32 v50, v240
	v_cvt_f32_f16_e32 v54, v244
	v_cvt_f32_f16_sdwa v55, v244 dst_sel:DWORD dst_unused:UNUSED_PAD src0_sel:WORD_1
	v_cvt_f32_f16_sdwa v51, v240 dst_sel:DWORD dst_unused:UNUSED_PAD src0_sel:WORD_1
	v_pk_mul_f32 v[36:37], v[46:47], v[52:53]
	v_pk_mul_f32 v[42:43], v[42:43], v[56:57]
	v_pk_mul_f32 v[46:47], v[44:45], v[54:55]
	v_pk_mul_f32 v[44:45], v[44:45], v[50:51]
	v_pk_mul_f32 v[48:49], v[40:41], v[36:37]
	v_pk_mul_f32 v[40:41], v[40:41], v[42:43]
	v_cvt_pk_f16_f32 v36, v36, v37
	v_cvt_pk_f16_f32 v37, v42, v43
	v_pk_mul_f32 v[50:51], v[38:39], v[46:47]
	v_pk_mul_f32 v[38:39], v[38:39], v[44:45]
	ds_write2st64_b32 v205, v36, v37 offset1:18
	v_cvt_pk_f16_f32 v36, v48, v49
	v_cvt_pk_f16_f32 v37, v40, v41
	v_pk_mul_f32 v[46:47], v[0:1], v[46:47]
	ds_write2st64_b32 v205, v36, v37 offset0:36 offset1:54
	v_cvt_pk_f16_f32 v36, v50, v51
	v_cvt_pk_f16_f32 v37, v38, v39
	ds_write2st64_b32 v205, v36, v37 offset0:72 offset1:90
	v_cvt_f16_f32_e32 v36, v46
	v_pk_mul_f32 v[44:45], v[0:1], v[44:45]
	v_cvt_f16_f32_e32 v37, v47
	v_cvt_f16_f32_e32 v38, v44
	v_cvt_f16_f32_e32 v39, v45
	ds_write_b16 v178, v36 offset:22
	ds_write_b16 v178, v37 offset:62
	ds_write_b16 v178, v38 offset:5142
	s_waitcnt lgkmcnt(14)
	ds_write_b16 v178, v39 offset:5182
	s_nop 0
	s_waitcnt lgkmcnt(7)
	ds_write_b16 v178, v2 offset:10262
	v_perm_b32 v36, v62, v64, s82
	v_perm_b32 v37, v2, v60, s82
	ds_write_b64 v178, v[36:37] offset:10296

.LBB0_374:
	v_cmp_eq_u32_e32 vcc, 1, v176
	s_and_saveexec_b64 s[70:71], vcc
	s_cbranch_execz .LBB0_376
	v_lshl_add_u32 v253, v190, 1, v2
	ds_read2st64_b32 v[36:37], v253 offset0:64 offset1:80
	ds_read2st64_b32 v[46:47], v253 offset0:96 offset1:112
	v_lshl_add_u32 v50, v190, 1, v2
	s_nop 0
	s_nop 0
	ds_read_b32 v62, v50 offset:32768
	v_rcp_f32_e32 v42, v54
	v_rcp_f32_e32 v43, v55
	s_nop 0
	s_waitcnt lgkmcnt(1)
	v_cvt_f32_f16_e32 v58, v47
	v_cvt_f32_f16_e32 v52, v37
	v_cvt_f32_f16_sdwa v53, v37 dst_sel:DWORD dst_unused:UNUSED_PAD src0_sel:WORD_1
	v_cvt_f32_f16_sdwa v59, v47 dst_sel:DWORD dst_unused:UNUSED_PAD src0_sel:WORD_1
	v_lshl_add_u32 v253, v192, 1, v2
	ds_read2st64_b32 v[148:149], v253 offset0:64 offset1:80
	v_cvt_f32_f16_e32 v50, v36
	v_cvt_f32_f16_e32 v56, v46
	v_cvt_f32_f16_sdwa v57, v46 dst_sel:DWORD dst_unused:UNUSED_PAD src0_sel:WORD_1
	ds_read2st64_b32 v[240:241], v253 offset0:96 offset1:112
	v_cvt_f32_f16_sdwa v51, v36 dst_sel:DWORD dst_unused:UNUSED_PAD src0_sel:WORD_1
	v_pk_mul_f32 v[36:37], v[60:61], v[52:53]
	v_pk_mul_f32 v[46:47], v[54:55], v[58:59]
	v_pk_mul_f32 v[52:53], v[42:43], v[56:57]
	v_pk_mul_f32 v[42:43], v[42:43], v[50:51]
	v_pk_mul_f32 v[50:51], v[40:41], v[36:37]
	v_pk_mul_f32 v[56:57], v[40:41], v[46:47]
	v_cvt_pk_f16_f32 v36, v36, v37
	v_cvt_pk_f16_f32 v37, v46, v47
	v_pk_mul_f32 v[58:59], v[38:39], v[52:53]
	v_pk_mul_f32 v[60:61], v[38:39], v[42:43]
	ds_write2st64_b32 v191, v36, v37 offset1:18
	v_cvt_pk_f16_f32 v36, v50, v51
	v_cvt_pk_f16_f32 v37, v56, v57
	v_pk_mul_f32 v[52:53], v[0:1], v[52:53]
	ds_write2st64_b32 v191, v36, v37 offset0:36 offset1:54
	v_cvt_pk_f16_f32 v36, v58, v59
	v_cvt_pk_f16_f32 v37, v60, v61
	ds_write2st64_b32 v191, v36, v37 offset0:72 offset1:90
	v_cvt_f16_f32_e32 v36, v52
	v_pk_mul_f32 v[42:43], v[0:1], v[42:43]
	v_cvt_f16_f32_e32 v37, v53
	v_cvt_f16_f32_e32 v42, v42
	v_cvt_f16_f32_e32 v43, v43
	ds_write_b16 v178, v36 offset:8
	ds_write_b16 v178, v37 offset:48
	ds_write_b16 v178, v42 offset:5128
	ds_write_b16 v178, v43 offset:5168
	s_waitcnt lgkmcnt(9)
	ds_write_b16 v178, v62 offset:10248
	v_lshl_add_u32 v50, v192, 1, v2
	s_nop 0
	s_nop 0
	ds_read_b32 v60, v50 offset:32768
	v_rcp_f32_e32 v42, v48
	v_rcp_f32_e32 v43, v49
	s_waitcnt lgkmcnt(10)
	v_cvt_f32_f16_e32 v52, v149
	v_cvt_f32_f16_sdwa v53, v149 dst_sel:DWORD dst_unused:UNUSED_PAD src0_sel:WORD_1
	s_waitcnt lgkmcnt(9)
	v_cvt_f32_f16_e32 v58, v241
	v_cvt_f32_f16_sdwa v59, v241 dst_sel:DWORD dst_unused:UNUSED_PAD src0_sel:WORD_1
	v_cvt_f32_f16_e32 v50, v148
	v_lshl_add_u32 v253, v194, 1, v2
	ds_read2st64_b32 v[242:243], v253 offset0:64 offset1:80
	v_cvt_f32_f16_e32 v56, v240
	v_cvt_f32_f16_sdwa v57, v240 dst_sel:DWORD dst_unused:UNUSED_PAD src0_sel:WORD_1
	v_cvt_f32_f16_sdwa v51, v148 dst_sel:DWORD dst_unused:UNUSED_PAD src0_sel:WORD_1
	ds_read2st64_b32 v[148:149], v253 offset0:96 offset1:112
	v_pk_mul_f32 v[36:37], v[54:55], v[52:53]
	v_pk_mul_f32 v[46:47], v[48:49], v[58:59]
	v_pk_mul_f32 v[52:53], v[42:43], v[56:57]
	v_pk_mul_f32 v[42:43], v[42:43], v[50:51]
	v_pk_mul_f32 v[50:51], v[40:41], v[36:37]
	v_pk_mul_f32 v[54:55], v[40:41], v[46:47]
	v_cvt_pk_f16_f32 v36, v36, v37
	v_cvt_pk_f16_f32 v37, v46, v47
	v_pk_mul_f32 v[56:57], v[38:39], v[52:53]
	v_pk_mul_f32 v[58:59], v[38:39], v[42:43]
	ds_write2st64_b32 v193, v36, v37 offset1:18
	v_cvt_pk_f16_f32 v36, v50, v51
	v_cvt_pk_f16_f32 v37, v54, v55
	v_pk_mul_f32 v[52:53], v[0:1], v[52:53]
	ds_write2st64_b32 v193, v36, v37 offset0:36 offset1:54
	v_cvt_pk_f16_f32 v36, v56, v57
	v_cvt_pk_f16_f32 v37, v58, v59
	ds_write2st64_b32 v193, v36, v37 offset0:72 offset1:90
	v_cvt_f16_f32_e32 v36, v52
	v_pk_mul_f32 v[42:43], v[0:1], v[42:43]
	v_cvt_f16_f32_e32 v37, v53
	v_cvt_f16_f32_e32 v42, v42
	v_cvt_f16_f32_e32 v43, v43
	ds_write_b16 v178, v36 offset:10
	s_waitcnt lgkmcnt(14)
	ds_write_b16 v178, v37 offset:50
	s_waitcnt lgkmcnt(14)
	ds_write_b16 v178, v42 offset:5130
	s_waitcnt lgkmcnt(14)
	ds_write_b16 v178, v43 offset:5170
	s_waitcnt lgkmcnt(9)
	ds_write_b16 v178, v60 offset:10250
	v_lshl_add_u32 v50, v194, 1, v2
	s_nop 0
	s_nop 0
	ds_read_b32 v58, v50 offset:32768
	v_rcp_f32_e32 v42, v44
	v_rcp_f32_e32 v43, v45
	v_lshl_add_u32 v2, v196, 1, v2
	s_nop 0
	s_waitcnt lgkmcnt(10)
	v_cvt_f32_f16_e32 v52, v243
	v_cvt_f32_f16_sdwa v53, v243 dst_sel:DWORD dst_unused:UNUSED_PAD src0_sel:WORD_1
	ds_read2st64_b32 v[240:241], v2 offset0:64 offset1:80
	s_waitcnt lgkmcnt(10)
	v_cvt_f32_f16_e32 v56, v149
	v_cvt_f32_f16_sdwa v57, v149 dst_sel:DWORD dst_unused:UNUSED_PAD src0_sel:WORD_1
	ds_read2st64_b32 v[244:245], v2 offset0:96 offset1:112
	v_cvt_f32_f16_e32 v50, v242
	v_cvt_f32_f16_e32 v54, v148
	v_cvt_f32_f16_sdwa v55, v148 dst_sel:DWORD dst_unused:UNUSED_PAD src0_sel:WORD_1
	v_cvt_f32_f16_sdwa v51, v242 dst_sel:DWORD dst_unused:UNUSED_PAD src0_sel:WORD_1
	v_pk_mul_f32 v[36:37], v[48:49], v[52:53]
	v_pk_mul_f32 v[46:47], v[44:45], v[56:57]
	v_pk_mul_f32 v[48:49], v[42:43], v[54:55]
	v_pk_mul_f32 v[42:43], v[42:43], v[50:51]
	v_pk_mul_f32 v[50:51], v[40:41], v[36:37]
	v_pk_mul_f32 v[52:53], v[40:41], v[46:47]
	v_cvt_pk_f16_f32 v36, v36, v37
	v_cvt_pk_f16_f32 v37, v46, v47
	v_pk_mul_f32 v[54:55], v[38:39], v[48:49]
	v_pk_mul_f32 v[56:57], v[38:39], v[42:43]
	ds_write2st64_b32 v195, v36, v37 offset1:18
	v_cvt_pk_f16_f32 v36, v50, v51
	v_cvt_pk_f16_f32 v37, v52, v53
	v_pk_mul_f32 v[48:49], v[0:1], v[48:49]
	ds_write2st64_b32 v195, v36, v37 offset0:36 offset1:54
	v_cvt_pk_f16_f32 v36, v54, v55
	v_cvt_pk_f16_f32 v37, v56, v57
	ds_write2st64_b32 v195, v36, v37 offset0:72 offset1:90
	v_cvt_f16_f32_e32 v36, v48
	v_pk_mul_f32 v[42:43], v[0:1], v[42:43]
	v_cvt_f16_f32_e32 v37, v49
	v_cvt_f16_f32_e32 v42, v42
	v_cvt_f16_f32_e32 v43, v43
	ds_write_b16 v178, v36 offset:12
	s_waitcnt lgkmcnt(14)
	ds_write_b16 v178, v37 offset:52
	s_waitcnt lgkmcnt(14)
	ds_write_b16 v178, v42 offset:5132
	s_waitcnt lgkmcnt(14)
	ds_write_b16 v178, v43 offset:5172
	s_waitcnt lgkmcnt(9)
	ds_write_b16 v178, v58 offset:10252
	ds_read_b32 v2, v2 offset:32768
	s_waitcnt lgkmcnt(10)
	v_cvt_f32_f16_e32 v48, v241
	v_cvt_f32_f16_sdwa v49, v241 dst_sel:DWORD dst_unused:UNUSED_PAD src0_sel:WORD_1
	s_waitcnt lgkmcnt(9)
	v_cvt_f32_f16_e32 v52, v245
	v_cvt_f32_f16_sdwa v53, v245 dst_sel:DWORD dst_unused:UNUSED_PAD src0_sel:WORD_1
	v_cvt_f32_f16_e32 v46, v240
	v_cvt_f32_f16_e32 v50, v244
	v_cvt_f32_f16_sdwa v51, v244 dst_sel:DWORD dst_unused:UNUSED_PAD src0_sel:WORD_1
	v_cvt_f32_f16_sdwa v47, v240 dst_sel:DWORD dst_unused:UNUSED_PAD src0_sel:WORD_1
	v_pk_mul_f32 v[36:37], v[44:45], v[48:49]
	v_pk_mul_f32 v[42:43], v[38:39], v[52:53]
	v_pk_mul_f32 v[44:45], v[40:41], v[50:51]
	v_pk_mul_f32 v[46:47], v[40:41], v[46:47]
	v_pk_mul_f32 v[48:49], v[40:41], v[36:37]
	v_pk_mul_f32 v[40:41], v[40:41], v[42:43]
	v_cvt_pk_f16_f32 v36, v36, v37
	v_cvt_pk_f16_f32 v37, v42, v43
	v_pk_mul_f32 v[50:51], v[38:39], v[44:45]
	v_pk_mul_f32 v[38:39], v[38:39], v[46:47]
	ds_write2st64_b32 v197, v36, v37 offset1:18
	v_cvt_pk_f16_f32 v36, v48, v49
	v_cvt_pk_f16_f32 v37, v40, v41
	v_pk_mul_f32 v[44:45], v[0:1], v[44:45]
	ds_write2st64_b32 v197, v36, v37 offset0:36 offset1:54
	v_cvt_pk_f16_f32 v36, v50, v51
	v_cvt_pk_f16_f32 v37, v38, v39
	ds_write2st64_b32 v197, v36, v37 offset0:72 offset1:90
	v_cvt_f16_f32_e32 v36, v44
	v_pk_mul_f32 v[46:47], v[0:1], v[46:47]
	v_cvt_f16_f32_e32 v37, v45
	v_cvt_f16_f32_e32 v38, v46
	v_cvt_f16_f32_e32 v39, v47
	ds_write_b16 v178, v36 offset:14
	ds_write_b16 v178, v37 offset:54
	ds_write_b16 v178, v38 offset:5134
	s_waitcnt lgkmcnt(14)
	ds_write_b16 v178, v39 offset:5174
	s_nop 0
	s_waitcnt lgkmcnt(7)
	ds_write_b16 v178, v2 offset:10254
	v_perm_b32 v36, v60, v62, s82
	v_perm_b32 v37, v2, v58, s82
	ds_write_b64 v178, v[36:37] offset:10288

.LBB0_421:
	s_or_b64 exec, exec, s[0:1]
	s_nop 5
	v_cvt_f16_f32_e32 v65, v65
	v_cvt_f16_f32_e32 v64, v64
	s_add_i32 s30, s30, 1
	v_cndmask_b32_e64 v68, 0, v65, s[24:25]
	v_cvt_f16_f32_e32 v65, v66
	v_cvt_f16_f32_e32 v66, v67
	v_cndmask_b32_e64 v64, v64, 0, s[22:23]
	v_pack_b32_f16 v64, v64, v68
	v_cndmask_b32_e64 v65, v65, 0, s[26:27]
	v_cndmask_b32_e64 v66, v66, 0, s[28:29]
	v_pack_b32_f16 v65, v65, v66
	ds_write_b64 v115, v[64:65]
	s_waitcnt lgkmcnt(0)
	s_barrier
	ds_read_b128 v[118:121], v116 offset:55360
	ds_read_b128 v[122:125], v117
	ds_read_b128 v[142:145], v117 offset:64
	ds_read_b128 v[146:149], v117 offset:2304
	ds_read_b128 v[178:181], v117 offset:2368
	ds_read_b128 v[182:185], v117 offset:4608
	ds_read_b128 v[186:189], v117 offset:4672
	ds_read_b128 v[190:193], v117 offset:6912
	ds_read_b128 v[64:67], v116 offset:55296
	ds_read_b128 v[194:197], v117 offset:6976
	s_nop 0
	s_nop 0
	s_nop 0
	v_add_u32_e32 v253, 0x1e500, v87
	s_waitcnt lgkmcnt(1)
	v_mfma_f32_16x16x32_f16 v[52:55], v[64:67], v[122:125], v[52:55]
	ds_read_b128 v[198:201], v253
	s_nop 0
	v_add_u32_e32 v68, 0x1e500, v87
	s_nop 0
	v_mfma_f32_16x16x32_f16 v[52:55], v[118:121], v[142:145], v[52:55]
	s_nop 0
	ds_read_b128 v[142:145], v248 offset:46080
	s_nop 0
	v_mfma_f32_16x16x32_f16 v[56:59], v[64:67], v[146:149], v[56:59]
	s_nop 0
	s_nop 3
	ds_read_b128 v[146:149], v248 offset:46144
	v_cvt_pk_f16_f32 v55, v54, v55
	v_cvt_pk_f16_f32 v54, v52, v53
	s_nop 0
	ds_read_b128 v[202:205], v68 offset:64
	v_mfma_f32_16x16x32_f16 v[56:59], v[118:121], v[178:181], v[56:59]
	v_mfma_f32_16x16x32_f16 v[60:63], v[64:67], v[182:185], v[60:63]
	ds_read_b128 v[178:181], v249 offset:48384
	s_nop 0
	s_nop 0
	v_mfma_f32_16x16x32_f16 v[60:63], v[118:121], v[186:189], v[60:63]
	ds_read_b128 v[182:185], v249 offset:48448
	v_mfma_f32_16x16x32_f16 v[48:51], v[64:67], v[190:193], v[48:51]
	ds_read_b128 v[186:189], v68 offset:128
	s_nop 0
	s_nop 0
	s_waitcnt lgkmcnt(7)
	v_mfma_f32_16x16x32_f16 v[48:51], v[118:121], v[194:197], v[48:51]
	s_nop 0
	ds_read_b128 v[190:193], v248 offset:50688
	s_nop 0
	s_waitcnt lgkmcnt(7)
	v_pk_mul_f32 v[8:9], v[8:9], v[198:199]
	v_pk_mul_f32 v[10:11], v[10:11], v[200:201]
	ds_read_b128 v[194:197], v248 offset:50752
	s_nop 0
	s_nop 2
	v_cvt_pk_f16_f32 v51, v50, v51
	ds_read_b128 v[198:201], v68 offset:192
	s_waitcnt lgkmcnt(8)
	v_mfma_f32_16x16x32_f16 v[8:11], v[142:145], v[64:67], v[8:11]
	s_nop 0
	v_cvt_pk_f16_f32 v50, v48, v49
	s_nop 0
	s_waitcnt lgkmcnt(7)
	v_mfma_f32_16x16x32_f16 v[8:11], v[146:149], v[118:121], v[8:11]
	s_waitcnt lgkmcnt(6)
	v_pk_mul_f32 v[4:5], v[4:5], v[202:203]
	v_pk_mul_f32 v[6:7], v[6:7], v[204:205]
	s_nop 0
	s_nop 0
	s_waitcnt lgkmcnt(5)
	v_mfma_f32_16x16x32_f16 v[4:7], v[178:181], v[64:67], v[4:7]
	s_nop 0
	s_nop 0
	s_waitcnt lgkmcnt(4)
	v_mfma_f32_16x16x32_f16 v[4:7], v[182:185], v[118:121], v[4:7]
	s_waitcnt lgkmcnt(3)
	v_pk_mul_f32 v[16:17], v[16:17], v[186:187]
	v_pk_mul_f32 v[18:19], v[18:19], v[188:189]
	s_nop 0
	s_nop 0
	s_waitcnt lgkmcnt(2)
	v_mfma_f32_16x16x32_f16 v[16:19], v[190:193], v[64:67], v[16:19]
	s_nop 0
	s_nop 0
	s_waitcnt lgkmcnt(1)
	v_mfma_f32_16x16x32_f16 v[16:19], v[194:197], v[118:121], v[16:19]
	s_waitcnt lgkmcnt(0)
	v_pk_mul_f32 v[12:13], v[12:13], v[198:199]
	v_pk_mul_f32 v[14:15], v[14:15], v[200:201]
	ds_read_b128 v[122:125], v249 offset:52992
	s_nop 0
	s_waitcnt lgkmcnt(0)
	v_mfma_f32_16x16x32_f16 v[12:15], v[122:125], v[64:67], v[12:15]
	ds_read_b128 v[64:67], v249 offset:53056
	s_nop 0
	s_waitcnt lgkmcnt(0)
	v_mfma_f32_16x16x32_f16 v[12:15], v[64:67], v[118:121], v[12:15]
	v_add_u32_e32 v65, s79, v104
	v_add_u32_e32 v64, s78, v80
	v_add_u32_e32 v66, 0x7ff, v65
	v_cndmask_b32_e64 v66, v66, v64, s[2:3]
	v_add_u32_e32 v52, v66, v81
	v_mad_i64_i32 v[52:53], s[0:1], v52, s91, v[76:77]
	global_store_dwordx2 v[52:53], v[54:55], off
	v_add_u32_e32 v52, 16, v64
	v_add_u32_e32 v53, 0x7ef, v65
	v_cndmask_b32_e64 v54, v53, v52, s[2:3]
	v_add_u32_e32 v54, v54, v81
	v_cvt_pk_f16_f32 v53, v58, v59
	v_cvt_pk_f16_f32 v52, v56, v57
	v_mad_i64_i32 v[54:55], s[0:1], v54, s91, v[76:77]
	global_store_dwordx2 v[54:55], v[52:53], off
	v_add_u32_e32 v52, 32, v64
	v_add_u32_e32 v53, 0x7df, v65
	v_cndmask_b32_e64 v54, v53, v52, s[2:3]
	v_add_u32_e32 v54, v54, v81
	v_cvt_pk_f16_f32 v53, v62, v63
	v_cvt_pk_f16_f32 v52, v60, v61
	v_mad_i64_i32 v[54:55], s[0:1], v54, s91, v[76:77]
	global_store_dwordx2 v[54:55], v[52:53], off
	v_add_u32_e32 v52, 48, v64
	v_add_u32_e32 v53, 0x7cf, v65
	v_cndmask_b32_e64 v52, v53, v52, s[2:3]
	v_add_u32_e32 v48, v52, v81
	s_sub_i32 s79, s79, 64
	s_add_i32 s78, s78, 64
	v_mad_i64_i32 v[48:49], s[0:1], v48, s91, v[76:77]
	s_cmpk_lg_i32 s79, 0xf800
	global_store_dwordx2 v[48:49], v[50:51], off
	s_cbranch_scc0 .LBB0_438

.LBB0_434:
	s_or_b64 exec, exec, s[0:1]
	v_add_u32_e32 v57, s78, v82
	v_add_u32_e32 v56, 0x7ff, v56
	v_cndmask_b32_e64 v56, v56, v57, s[2:3]
	s_waitcnt lgkmcnt(0)
	s_barrier
	ds_read_b128 v[58:61], v83
	ds_read_b128 v[62:65], v88
	ds_read_b128 v[48:51], v83 offset:9216
	s_nop 0
	ds_read_b128 v[66:69], v85
	ds_read_b128 v[52:55], v88 offset:9216
	v_lshrrev_b32_e32 v57, 6, v56
	v_and_b32_e32 v56, 63, v56
	v_cndmask_b32_e64 v56, v56, v57, s[6:7]
	v_lshl_or_b32 v57, v56, 6, v112
	s_nop 0
	v_add_u32_e32 v253, s83, v57
	ds_read_b128 v[122:125], v253
	ds_read_b128 v[118:121], v250 offset:16
	v_add_u32_e32 v75, s83, v57
	s_add_i32 s0, 0, 0x1f600
	v_add_u32_e32 v252, s0, v57
	ds_read_b128 v[126:129], v252
	v_add_u32_e32 v79, s0, v57
	s_waitcnt lgkmcnt(6)
	v_cvt_f32_f16_sdwa v137, v62 dst_sel:DWORD dst_unused:UNUSED_PAD src0_sel:WORD_1
	v_cvt_f32_f16_e32 v136, v62
	v_or_b32_e32 v57, 16, v57
	v_cvt_f32_f16_sdwa v135, v58 dst_sel:DWORD dst_unused:UNUSED_PAD src0_sel:WORD_1
	v_cvt_f32_f16_e32 v134, v58
	s_nop 0
	s_waitcnt lgkmcnt(4)
	v_mul_f32_e32 v56, 0x3fb8aa3b, v66
	v_add_u32_e32 v140, s83, v57
	ds_read_b128 v[130:133], v93
	v_add_u32_e32 v141, s0, v57
	v_mul_f32_e32 v57, 0x3fb8aa3b, v67
	v_exp_f32_e32 v56, v56
	v_exp_f32_e32 v57, v57
	v_pk_mul_f32 v[136:137], v[136:137], s[68:69] op_sel_hi:[1,0]
	v_pk_mul_f32 v[134:135], v[134:135], s[68:69] op_sel_hi:[1,0]
	s_nop 0
	s_waitcnt lgkmcnt(1)
	v_pk_mul_f32 v[136:137], v[136:137], v[126:127]
	v_rcp_f32_e32 v66, v56
	v_cndmask_b32_e64 v137, v137, -v137, s[8:9]
	v_cndmask_b32_e64 v136, v136, -v136, s[8:9]
	v_pk_fma_f32 v[134:135], v[134:135], v[122:123], v[136:137]
	v_cvt_f32_f16_sdwa v137, v48 dst_sel:DWORD dst_unused:UNUSED_PAD src0_sel:WORD_1
	v_pk_mul_f32 v[138:139], v[134:135], v[56:57]
	v_cvt_f32_f16_sdwa v135, v52 dst_sel:DWORD dst_unused:UNUSED_PAD src0_sel:WORD_1
	v_cvt_f32_f16_e32 v134, v52
	v_cvt_f32_f16_e32 v136, v48
	s_nop 0
	v_rcp_f32_e32 v67, v57
	v_pk_mul_f32 v[126:127], v[126:127], v[134:135]
	v_add3_u32 v52, v72, v89, v247
	v_cndmask_b32_e64 v127, v127, -v127, s[8:9]
	v_cndmask_b32_e64 v126, v126, -v126, s[8:9]
	v_pk_fma_f32 v[122:123], v[122:123], v[136:137], v[126:127]
	ds_read_b128 v[134:137], v94
	v_pk_mul_f32 v[126:127], v[122:123], v[66:67]
	v_cvt_f32_f16_e32 v58, v63
	s_nop 0
	s_waitcnt lgkmcnt(1)
	v_fma_mixlo_f16 v48, v130, v126, 0
	ds_write_b16 v52, v48 offset:46080
	v_fma_mixlo_f16 v48, v131, v127, 0
	ds_write_b16 v113, v48 offset:46080
	v_mul_f32_e32 v48, 0x3fb8aa3b, v68
	v_exp_f32_e32 v66, v48
	v_mul_f32_e32 v48, 0x3fb8aa3b, v69
	v_cvt_f32_f16_sdwa v69, v59 dst_sel:DWORD dst_unused:UNUSED_PAD src0_sel:WORD_1
	v_cvt_f32_f16_e32 v68, v59
	v_cvt_f32_f16_sdwa v59, v63 dst_sel:DWORD dst_unused:UNUSED_PAD src0_sel:WORD_1
	v_exp_f32_e32 v67, v48
	v_cvt_f32_f16_e32 v52, v49
	v_pk_mul_f32 v[68:69], v[68:69], s[68:69] op_sel_hi:[1,0]
	v_pk_mul_f32 v[58:59], v[58:59], s[68:69] op_sel_hi:[1,0]
	v_rcp_f32_e32 v62, v66
	v_pk_mul_f32 v[58:59], v[58:59], v[128:129]
	v_rcp_f32_e32 v63, v67
	v_cndmask_b32_e64 v59, v59, -v59, s[8:9]
	v_cndmask_b32_e64 v58, v58, -v58, s[8:9]
	v_pk_fma_f32 v[58:59], v[68:69], v[124:125], v[58:59]
	v_cvt_pk_f16_f32 v56, v138, v139
	v_pk_mul_f32 v[130:131], v[58:59], v[66:67]
	v_cvt_f32_f16_sdwa v59, v53 dst_sel:DWORD dst_unused:UNUSED_PAD src0_sel:WORD_1
	v_cvt_f32_f16_e32 v58, v53
	v_cvt_f32_f16_sdwa v53, v49 dst_sel:DWORD dst_unused:UNUSED_PAD src0_sel:WORD_1
	v_cvt_pk_f16_f32 v57, v130, v131
	v_pk_mul_f32 v[48:49], v[128:129], v[58:59]
	s_nop 0
	v_cndmask_b32_e64 v49, v49, -v49, s[8:9]
	v_cndmask_b32_e64 v48, v48, -v48, s[8:9]
	v_pk_fma_f32 v[48:49], v[124:125], v[52:53], v[48:49]
	v_cvt_f32_f16_sdwa v59, v60 dst_sel:DWORD dst_unused:UNUSED_PAD src0_sel:WORD_1
	v_pk_mul_f32 v[48:49], v[48:49], v[62:63]
	v_cvt_f32_f16_sdwa v63, v64 dst_sel:DWORD dst_unused:UNUSED_PAD src0_sel:WORD_1
	v_fma_mixlo_f16 v52, v132, v48, 0
	ds_write_b16 v113, v52 offset:46224
	v_fma_mixlo_f16 v52, v133, v49, 0
	ds_write_b16 v113, v52 offset:46368
	ds_read_b128 v[122:125], v141
	ds_read_b128 v[66:69], v140
	v_cvt_f32_f16_e32 v62, v64
	v_cvt_f32_f16_e32 v58, v60
	v_mul_f32_e32 v52, 0x3fb8aa3b, v118
	v_mul_f32_e32 v53, 0x3fb8aa3b, v119
	v_pk_mul_f32 v[62:63], v[62:63], s[68:69] op_sel_hi:[1,0]
	v_exp_f32_e32 v52, v52
	s_nop 0
	s_waitcnt lgkmcnt(1)
	v_pk_mul_f32 v[62:63], v[62:63], v[122:123]
	v_exp_f32_e32 v53, v53
	v_pk_mul_f32 v[58:59], v[58:59], s[68:69] op_sel_hi:[1,0]
	v_cndmask_b32_e64 v63, v63, -v63, s[8:9]
	v_cndmask_b32_e64 v62, v62, -v62, s[8:9]
	s_waitcnt lgkmcnt(0)
	v_pk_fma_f32 v[58:59], v[58:59], v[66:67], v[62:63]
	v_cvt_f32_f16_sdwa v63, v54 dst_sel:DWORD dst_unused:UNUSED_PAD src0_sel:WORD_1
	v_cvt_f32_f16_e32 v62, v54
	v_cvt_f32_f16_sdwa v129, v50 dst_sel:DWORD dst_unused:UNUSED_PAD src0_sel:WORD_1
	v_cvt_f32_f16_e32 v128, v50
	v_rcp_f32_e32 v118, v52
	v_rcp_f32_e32 v119, v53
	v_pk_mul_f32 v[62:63], v[122:123], v[62:63]
	v_cvt_f32_f16_e32 v60, v65
	v_cndmask_b32_e64 v63, v63, -v63, s[8:9]
	v_cndmask_b32_e64 v62, v62, -v62, s[8:9]
	v_pk_fma_f32 v[62:63], v[66:67], v[128:129], v[62:63]
	v_pk_mul_f32 v[52:53], v[58:59], v[52:53]
	v_pk_mul_f32 v[66:67], v[62:63], v[118:119]
	v_cvt_f32_f16_sdwa v119, v61 dst_sel:DWORD dst_unused:UNUSED_PAD src0_sel:WORD_1
	v_fma_mixlo_f16 v50, v134, v66, 0
	v_cvt_f32_f16_e32 v118, v61
	v_cvt_f32_f16_sdwa v61, v65 dst_sel:DWORD dst_unused:UNUSED_PAD src0_sel:WORD_1
	ds_write_b16 v113, v50 offset:46512
	v_fma_mixlo_f16 v50, v135, v67, 0
	ds_write_b16 v113, v50 offset:46656
	v_mul_f32_e32 v50, 0x3fb8aa3b, v120
	v_exp_f32_e32 v62, v50
	v_mul_f32_e32 v50, 0x3fb8aa3b, v121
	v_exp_f32_e32 v63, v50
	v_pk_mul_f32 v[60:61], v[60:61], s[68:69] op_sel_hi:[1,0]
	v_pk_mul_f32 v[118:119], v[118:119], s[68:69] op_sel_hi:[1,0]
	v_pk_mul_f32 v[60:61], v[60:61], v[124:125]
	v_rcp_f32_e32 v64, v62
	v_cndmask_b32_e64 v61, v61, -v61, s[8:9]
	v_cndmask_b32_e64 v60, v60, -v60, s[8:9]
	v_pk_fma_f32 v[60:61], v[118:119], v[68:69], v[60:61]
	v_rcp_f32_e32 v65, v63
	v_pk_mul_f32 v[60:61], v[60:61], v[62:63]
	v_bfe_u32 v62, v131, 16, 1
	v_bfe_u32 v63, v130, 16, 1
	v_bfe_u32 v75, v53, 16, 1
	v_bfe_u32 v79, v52, 16, 1
	v_cvt_pk_f16_f32 v58, v52, v53
	v_bfe_u32 v50, v61, 16, 1
	v_add3_u32 v120, v130, v63, s34
	v_add3_u32 v62, v131, v62, s34
	v_add3_u32 v52, v52, v79, s34
	v_add3_u32 v53, v53, v75, s34
	v_cvt_pk_f16_f32 v59, v60, v61
	v_bfe_u32 v54, v60, 16, 1
	v_add3_u32 v50, v61, v50, s34
	v_perm_b32 v61, v62, v120, s82
	v_perm_b32 v62, v53, v52, s82
	v_cvt_f32_f16_sdwa v53, v55 dst_sel:DWORD dst_unused:UNUSED_PAD src0_sel:WORD_1
	v_cvt_f32_f16_e32 v52, v55
	v_add3_u32 v54, v60, v54, s34
	v_perm_b32 v63, v50, v54, s82
	v_cvt_f32_f16_sdwa v55, v51 dst_sel:DWORD dst_unused:UNUSED_PAD src0_sel:WORD_1
	v_cvt_f32_f16_e32 v54, v51
	v_pk_mul_f32 v[50:51], v[124:125], v[52:53]
	v_bfe_u32 v118, v139, 16, 1
	v_cndmask_b32_e64 v51, v51, -v51, s[8:9]
	v_cndmask_b32_e64 v50, v50, -v50, s[8:9]
	v_pk_fma_f32 v[50:51], v[68:69], v[54:55], v[50:51]
	v_bfe_u32 v119, v138, 16, 1
	v_pk_mul_f32 v[52:53], v[50:51], v[64:65]
	v_bfe_u32 v51, v48, 16, 1
	v_fma_mixlo_f16 v50, v136, v52, 0
	v_bfe_u32 v54, v53, 16, 1
	v_bfe_u32 v55, v52, 16, 1
	ds_write_b16 v113, v50 offset:46800
	v_bfe_u32 v50, v49, 16, 1
	v_bfe_u32 v64, v67, 16, 1
	v_bfe_u32 v65, v66, 16, 1
	v_bfe_u32 v68, v127, 16, 1
	v_bfe_u32 v69, v126, 16, 1
	v_add3_u32 v52, v52, v55, s34
	v_add3_u32 v54, v53, v54, s34
	v_add3_u32 v60, v138, v119, s34
	v_add3_u32 v118, v139, v118, s34
	v_add3_u32 v48, v48, v51, s34
	v_add3_u32 v49, v49, v50, s34
	v_add3_u32 v55, v126, v69, s34
	v_add3_u32 v68, v127, v68, s34
	v_add3_u32 v50, v66, v65, s34
	v_add3_u32 v64, v67, v64, s34
	v_perm_b32 v51, v54, v52, s82
	v_fma_mixlo_f16 v52, v137, v53, 0
	v_perm_b32 v60, v118, v60, s82
	v_perm_b32 v49, v49, v48, s82
	v_perm_b32 v50, v64, v50, s82
	v_perm_b32 v48, v68, v55, s82
	ds_write_b16 v113, v52 offset:46944
	ds_write_b128 v83, v[60:63] offset:18432
	ds_write_b128 v83, v[48:51] offset:27648
	ds_write_b128 v83, v[56:59] offset:36864
	v_add_u32_e32 v56, v73, v0
	s_nop 0
	s_barrier
	v_add_u32_e32 v253, v86, v95
	ds_read_b128 v[52:55], v253 offset:36864
	ds_read_b128 v[64:67], v56 offset:64
	ds_read_b128 v[142:145], v253 offset:36928
	ds_read_b128 v[60:63], v253 offset:39168
	ds_read_b128 v[118:121], v253 offset:39232
	ds_read_b128 v[122:125], v253 offset:41472
	ds_read_b128 v[126:129], v253 offset:41536
	ds_read_b128 v[130:133], v253 offset:43776
	ds_read_b128 v[134:137], v253 offset:43840
	ds_read_b128 v[48:51], v56
	v_add_u32_e32 v68, v86, v95
	s_waitcnt lgkmcnt(0)
	v_mfma_f32_16x16x32_f16 v[52:55], v[48:51], v[52:55], 0
	v_add_u32_e32 v75, v92, v0
	v_mov_b32_e32 v68, 0
	v_mov_b32_e32 v69, 0
	s_nop 0
	v_mfma_f32_16x16x32_f16 v[60:63], v[48:51], v[60:63], 0
	s_nop 0
	v_mfma_f32_16x16x32_f16 v[122:125], v[48:51], v[122:125], 0
	s_nop 0
	v_mfma_f32_16x16x32_f16 v[48:51], v[48:51], v[130:133], 0
	v_mfma_f32_16x16x32_f16 v[52:55], v[64:67], v[142:145], v[52:55]
	v_mfma_f32_16x16x32_f16 v[56:59], v[64:67], v[118:121], v[60:63]
	v_mfma_f32_16x16x32_f16 v[60:63], v[64:67], v[126:129], v[122:125]
	s_nop 0
	v_mfma_f32_16x16x32_f16 v[48:51], v[64:67], v[134:137], v[48:51]
	v_mov_b32_e32 v64, 0
	v_mov_b32_e32 v66, 0
	v_mov_b32_e32 v67, 0
	s_and_saveexec_b64 s[0:1], s[10:11]
	s_cbranch_execz .LBB0_436
	v_add_u32_e32 v253, v86, v98
	ds_read_b128 v[66:69], v75 offset:18432
	ds_read_b128 v[118:121], v253 offset:27648
	v_add_u32_e32 v65, v86, v98
	s_nop 0
	s_nop 0
	s_nop 0
	s_waitcnt lgkmcnt(0)
	v_mfma_f32_16x16x32_bf16 v[66:69], v[118:121], v[66:69], 0
	ds_read_b128 v[122:125], v65 offset:27712
	ds_read_b128 v[118:121], v75 offset:18496
	s_nop 0
	s_nop 0
	s_waitcnt lgkmcnt(0)
	v_mfma_f32_16x16x32_bf16 v[66:69], v[122:125], v[118:121], v[66:69]

.LBB0_455:
	s_andn2_b64 vcc, exec, s[24:25]
	s_mov_b64 s[26:27], -1
	s_cbranch_vccnz .LBB0_463
	s_and_b32 s26, s76, 1
	v_lshl_add_u32 v0, s26, 13, v227
	ds_read2_b64 v[36:39], v0 offset1:32
	v_mad_u32_u24 v2, s26, v165, v228
	s_waitcnt lgkmcnt(0)
	v_pk_mul_f32 v[66:67], v[36:37], v[38:39]
	ds_read2_b64 v[38:41], v0 offset0:64 offset1:96
	s_waitcnt lgkmcnt(0)
	v_pk_mul_f32 v[64:65], v[66:67], v[38:39]
	s_nop 0
	v_pk_mul_f32 v[60:61], v[64:65], v[40:41]
	ds_read2_b64 v[38:41], v0 offset0:128 offset1:160
	s_waitcnt lgkmcnt(0)
	v_pk_mul_f32 v[54:55], v[60:61], v[38:39]
	s_nop 0
	v_pk_mul_f32 v[48:49], v[54:55], v[40:41]
	ds_read2_b64 v[38:41], v0 offset0:192 offset1:224
	v_add_u32_e32 v0, 0x800, v0
	ds_read2_b64 v[68:71], v0 offset0:128 offset1:160
	s_waitcnt lgkmcnt(1)
	v_pk_mul_f32 v[44:45], v[48:49], v[38:39]
	s_nop 0
	v_pk_mul_f32 v[38:39], v[44:45], v[40:41]
	ds_read2_b64 v[40:43], v0 offset1:32
	s_waitcnt lgkmcnt(0)
	v_pk_mul_f32 v[58:59], v[38:39], v[40:41]
	s_nop 0
	v_pk_mul_f32 v[50:51], v[58:59], v[42:43]
	ds_read2_b64 v[40:43], v0 offset0:64 offset1:96
	s_waitcnt lgkmcnt(0)
	v_pk_mul_f32 v[46:47], v[50:51], v[40:41]
	s_nop 0
	v_pk_mul_f32 v[42:43], v[46:47], v[42:43]
	v_rcp_f32_e32 v40, v38
	v_pk_mul_f32 v[62:63], v[42:43], v[68:69]
	v_rcp_f32_e32 v41, v39
	v_pk_mul_f32 v[56:57], v[62:63], v[70:71]
	ds_read2_b64 v[68:71], v0 offset0:192 offset1:224
	s_waitcnt lgkmcnt(0)
	v_pk_mul_f32 v[52:53], v[56:57], v[68:69]
	s_nop 0
	v_pk_mul_f32 v[0:1], v[52:53], v[70:71]
	s_and_saveexec_b64 s[26:27], s[4:5]
	s_cbranch_execz .LBB0_458
	v_lshl_add_u32 v253, v173, 1, v2
	ds_read2st64_b32 v[72:73], v253 offset0:96 offset1:112
	ds_read2st64_b32 v[68:69], v253 offset0:64 offset1:80
	v_lshl_add_u32 v74, v173, 1, v2
	s_nop 0
	ds_read_b32 v84, v74 offset:32768
	s_nop 0
	v_rcp_f32_e32 v70, v36
	v_rcp_f32_e32 v71, v37
	s_nop 0
	s_nop 0
	s_waitcnt lgkmcnt(2)
	v_cvt_f32_f16_e32 v78, v73
	v_cvt_f32_f16_sdwa v79, v73 dst_sel:DWORD dst_unused:UNUSED_PAD src0_sel:WORD_1
	v_lshl_add_u32 v253, v180, 1, v2
	ds_read2st64_b32 v[146:147], v253 offset0:64 offset1:80
	s_waitcnt lgkmcnt(2)
	v_cvt_f32_f16_e32 v74, v68
	v_cvt_f32_f16_sdwa v75, v68 dst_sel:DWORD dst_unused:UNUSED_PAD src0_sel:WORD_1
	v_cvt_f32_f16_e32 v76, v72
	ds_read2st64_b32 v[148:149], v253 offset0:96 offset1:112
	v_cvt_f32_f16_sdwa v77, v72 dst_sel:DWORD dst_unused:UNUSED_PAD src0_sel:WORD_1
	v_cvt_f32_f16_e32 v72, v69
	v_cvt_f32_f16_sdwa v73, v69 dst_sel:DWORD dst_unused:UNUSED_PAD src0_sel:WORD_1
	v_pk_mul_f32 v[78:79], v[36:37], v[78:79]
	v_pk_mul_f32 v[76:77], v[70:71], v[76:77]
	v_pk_mul_f32 v[70:71], v[70:71], v[74:75]
	v_pk_mul_f32 v[72:73], v[40:41], v[72:73]
	v_pk_mul_f32 v[74:75], v[40:41], v[78:79]
	v_cvt_pk_f16_f32 v68, v78, v79
	v_pk_mul_f32 v[80:81], v[38:39], v[76:77]
	v_pk_mul_f32 v[82:83], v[38:39], v[70:71]
	ds_write2st64_b32 v179, v69, v68 offset1:18
	v_cvt_pk_f16_f32 v68, v72, v73
	v_cvt_pk_f16_f32 v69, v74, v75
	v_pk_mul_f32 v[76:77], v[0:1], v[76:77]
	ds_write2st64_b32 v179, v68, v69 offset0:36 offset1:54
	v_cvt_pk_f16_f32 v68, v80, v81
	v_cvt_pk_f16_f32 v69, v82, v83
	ds_write2st64_b32 v179, v68, v69 offset0:72 offset1:90
	v_cvt_f16_f32_e32 v68, v76
	v_pk_mul_f32 v[70:71], v[0:1], v[70:71]
	v_cvt_f16_f32_e32 v69, v77
	v_cvt_f16_f32_e32 v70, v70
	v_cvt_f16_f32_e32 v71, v71
	ds_write_b16 v174, v68
	ds_write_b16 v174, v69 offset:40
	ds_write_b16 v174, v70 offset:5120
	ds_write_b16 v174, v71 offset:5160
	s_waitcnt lgkmcnt(9)
	ds_write_b16 v174, v84 offset:10240
	v_lshl_add_u32 v74, v180, 1, v2
	s_nop 0
	s_nop 0
	ds_read_b32 v82, v74 offset:32768
	v_rcp_f32_e32 v70, v66
	v_rcp_f32_e32 v71, v67
	s_waitcnt lgkmcnt(10)
	v_cvt_f32_f16_e32 v76, v147
	v_cvt_f32_f16_sdwa v77, v147 dst_sel:DWORD dst_unused:UNUSED_PAD src0_sel:WORD_1
	s_waitcnt lgkmcnt(9)
	v_cvt_f32_f16_e32 v80, v149
	v_cvt_f32_f16_sdwa v81, v149 dst_sel:DWORD dst_unused:UNUSED_PAD src0_sel:WORD_1
	v_lshl_add_u32 v253, v182, 1, v2
	ds_read2st64_b32 v[232:233], v253 offset0:64 offset1:80
	v_cvt_f32_f16_e32 v74, v146
	v_cvt_f32_f16_e32 v78, v148
	v_cvt_f32_f16_sdwa v79, v148 dst_sel:DWORD dst_unused:UNUSED_PAD src0_sel:WORD_1
	ds_read2st64_b32 v[148:149], v253 offset0:96 offset1:112
	v_cvt_f32_f16_sdwa v75, v146 dst_sel:DWORD dst_unused:UNUSED_PAD src0_sel:WORD_1
	v_pk_mul_f32 v[36:37], v[36:37], v[76:77]
	v_pk_mul_f32 v[68:69], v[66:67], v[80:81]
	v_pk_mul_f32 v[72:73], v[70:71], v[78:79]
	v_pk_mul_f32 v[70:71], v[70:71], v[74:75]
	v_pk_mul_f32 v[74:75], v[40:41], v[36:37]
	v_pk_mul_f32 v[76:77], v[40:41], v[68:69]
	v_cvt_pk_f16_f32 v36, v36, v37
	v_cvt_pk_f16_f32 v37, v68, v69
	v_pk_mul_f32 v[78:79], v[38:39], v[72:73]
	v_pk_mul_f32 v[80:81], v[38:39], v[70:71]
	ds_write2st64_b32 v181, v36, v37 offset1:18
	v_cvt_pk_f16_f32 v36, v74, v75
	v_cvt_pk_f16_f32 v37, v76, v77
	v_pk_mul_f32 v[72:73], v[0:1], v[72:73]
	ds_write2st64_b32 v181, v36, v37 offset0:36 offset1:54
	v_cvt_pk_f16_f32 v36, v78, v79
	v_cvt_pk_f16_f32 v37, v80, v81
	ds_write2st64_b32 v181, v36, v37 offset0:72 offset1:90
	v_cvt_f16_f32_e32 v36, v72
	v_pk_mul_f32 v[70:71], v[0:1], v[70:71]
	v_cvt_f16_f32_e32 v37, v73
	v_cvt_f16_f32_e32 v68, v70
	v_cvt_f16_f32_e32 v69, v71
	ds_write_b16 v174, v36 offset:2
	s_waitcnt lgkmcnt(14)
	ds_write_b16 v174, v37 offset:42
	s_waitcnt lgkmcnt(14)
	ds_write_b16 v174, v68 offset:5122
	s_waitcnt lgkmcnt(14)
	ds_write_b16 v174, v69 offset:5162
	s_waitcnt lgkmcnt(9)
	ds_write_b16 v174, v82 offset:10242
	v_lshl_add_u32 v72, v182, 1, v2
	s_nop 0
	s_nop 0
	ds_read_b32 v80, v72 offset:32768
	v_rcp_f32_e32 v68, v64
	v_rcp_f32_e32 v69, v65
	s_waitcnt lgkmcnt(10)
	v_cvt_f32_f16_e32 v74, v233
	v_cvt_f32_f16_sdwa v75, v233 dst_sel:DWORD dst_unused:UNUSED_PAD src0_sel:WORD_1
	s_waitcnt lgkmcnt(9)
	v_cvt_f32_f16_e32 v78, v149
	v_cvt_f32_f16_sdwa v79, v149 dst_sel:DWORD dst_unused:UNUSED_PAD src0_sel:WORD_1
	v_lshl_add_u32 v253, v184, 1, v2
	ds_read2st64_b32 v[146:147], v253 offset0:64 offset1:80
	v_cvt_f32_f16_e32 v72, v232
	v_cvt_f32_f16_e32 v76, v148
	v_cvt_f32_f16_sdwa v77, v148 dst_sel:DWORD dst_unused:UNUSED_PAD src0_sel:WORD_1
	ds_read2st64_b32 v[148:149], v253 offset0:96 offset1:112
	v_cvt_f32_f16_sdwa v73, v232 dst_sel:DWORD dst_unused:UNUSED_PAD src0_sel:WORD_1
	v_pk_mul_f32 v[36:37], v[66:67], v[74:75]
	v_pk_mul_f32 v[66:67], v[64:65], v[78:79]
	v_pk_mul_f32 v[70:71], v[68:69], v[76:77]
	v_pk_mul_f32 v[68:69], v[68:69], v[72:73]
	v_pk_mul_f32 v[72:73], v[40:41], v[36:37]
	v_pk_mul_f32 v[74:75], v[40:41], v[66:67]
	v_cvt_pk_f16_f32 v36, v36, v37
	v_cvt_pk_f16_f32 v37, v66, v67
	v_pk_mul_f32 v[76:77], v[38:39], v[70:71]
	v_pk_mul_f32 v[78:79], v[38:39], v[68:69]
	ds_write2st64_b32 v183, v36, v37 offset1:18
	v_cvt_pk_f16_f32 v36, v72, v73
	v_cvt_pk_f16_f32 v37, v74, v75
	v_pk_mul_f32 v[70:71], v[0:1], v[70:71]
	ds_write2st64_b32 v183, v36, v37 offset0:36 offset1:54
	v_cvt_pk_f16_f32 v36, v76, v77
	v_cvt_pk_f16_f32 v37, v78, v79
	ds_write2st64_b32 v183, v36, v37 offset0:72 offset1:90
	v_cvt_f16_f32_e32 v36, v70
	v_pk_mul_f32 v[68:69], v[0:1], v[68:69]
	v_cvt_f16_f32_e32 v37, v71
	v_cvt_f16_f32_e32 v66, v68
	v_cvt_f16_f32_e32 v67, v69
	ds_write_b16 v174, v36 offset:4
	s_waitcnt lgkmcnt(14)
	ds_write_b16 v174, v37 offset:44
	s_waitcnt lgkmcnt(14)
	ds_write_b16 v174, v66 offset:5124
	s_waitcnt lgkmcnt(14)
	ds_write_b16 v174, v67 offset:5164
	s_waitcnt lgkmcnt(9)
	ds_write_b16 v174, v80 offset:10244
	v_lshl_add_u32 v70, v184, 1, v2
	s_nop 0
	s_nop 0
	ds_read_b32 v78, v70 offset:32768
	v_rcp_f32_e32 v66, v60
	v_rcp_f32_e32 v67, v61
	s_waitcnt lgkmcnt(10)
	v_cvt_f32_f16_e32 v72, v147
	v_cvt_f32_f16_sdwa v73, v147 dst_sel:DWORD dst_unused:UNUSED_PAD src0_sel:WORD_1
	s_waitcnt lgkmcnt(9)
	v_cvt_f32_f16_e32 v76, v149
	v_cvt_f32_f16_sdwa v77, v149 dst_sel:DWORD dst_unused:UNUSED_PAD src0_sel:WORD_1
	v_cvt_f32_f16_e32 v70, v146
	v_cvt_f32_f16_e32 v74, v148
	v_cvt_f32_f16_sdwa v75, v148 dst_sel:DWORD dst_unused:UNUSED_PAD src0_sel:WORD_1
	v_cvt_f32_f16_sdwa v71, v146 dst_sel:DWORD dst_unused:UNUSED_PAD src0_sel:WORD_1
	v_pk_mul_f32 v[36:37], v[64:65], v[72:73]
	v_pk_mul_f32 v[64:65], v[60:61], v[76:77]
	v_pk_mul_f32 v[68:69], v[66:67], v[74:75]
	v_pk_mul_f32 v[66:67], v[66:67], v[70:71]
	v_pk_mul_f32 v[70:71], v[40:41], v[36:37]
	v_pk_mul_f32 v[72:73], v[40:41], v[64:65]
	v_cvt_pk_f16_f32 v36, v36, v37
	v_cvt_pk_f16_f32 v37, v64, v65
	v_pk_mul_f32 v[74:75], v[38:39], v[68:69]
	v_pk_mul_f32 v[76:77], v[38:39], v[66:67]
	ds_write2st64_b32 v185, v36, v37 offset1:18
	v_cvt_pk_f16_f32 v36, v70, v71
	v_cvt_pk_f16_f32 v37, v72, v73
	v_pk_mul_f32 v[68:69], v[0:1], v[68:69]
	ds_write2st64_b32 v185, v36, v37 offset0:36 offset1:54
	v_cvt_pk_f16_f32 v36, v74, v75
	v_cvt_pk_f16_f32 v37, v76, v77
	ds_write2st64_b32 v185, v36, v37 offset0:72 offset1:90
	v_cvt_f16_f32_e32 v36, v68
	v_pk_mul_f32 v[66:67], v[0:1], v[66:67]
	v_cvt_f16_f32_e32 v37, v69
	v_cvt_f16_f32_e32 v64, v66
	v_cvt_f16_f32_e32 v65, v67
	ds_write_b16 v174, v36 offset:6
	ds_write_b16 v174, v37 offset:46
	ds_write_b16 v174, v64 offset:5126
	s_waitcnt lgkmcnt(14)
	ds_write_b16 v174, v65 offset:5166
	s_nop 0
	s_waitcnt lgkmcnt(7)
	ds_write_b16 v174, v78 offset:10246
	v_perm_b32 v36, v82, v84, s82
	v_perm_b32 v37, v78, v80, s82
	ds_write_b64 v174, v[36:37] offset:10280

.LBB0_468:
	v_cmp_lt_i32_e32 vcc, 2, v172
	s_and_saveexec_b64 s[28:29], vcc
	s_xor_b64 s[28:29], exec, s[28:29]
	s_cbranch_execz .LBB0_470
	v_lshl_add_u32 v253, v202, 1, v2
	ds_read2st64_b32 v[36:37], v253 offset0:64 offset1:80
	ds_read2st64_b32 v[46:47], v253 offset0:96 offset1:112
	v_lshl_add_u32 v48, v202, 1, v2
	s_nop 0
	s_nop 0
	ds_read_b32 v60, v48 offset:32768
	v_rcp_f32_e32 v44, v62
	v_rcp_f32_e32 v45, v63
	s_nop 0
	s_waitcnt lgkmcnt(1)
	v_cvt_f32_f16_e32 v58, v47
	v_cvt_f32_f16_e32 v50, v37
	v_cvt_f32_f16_sdwa v51, v37 dst_sel:DWORD dst_unused:UNUSED_PAD src0_sel:WORD_1
	v_cvt_f32_f16_sdwa v59, v47 dst_sel:DWORD dst_unused:UNUSED_PAD src0_sel:WORD_1
	v_lshl_add_u32 v253, v204, 1, v2
	ds_read2st64_b32 v[146:147], v253 offset0:64 offset1:80
	v_cvt_f32_f16_e32 v48, v36
	v_cvt_f32_f16_e32 v54, v46
	v_cvt_f32_f16_sdwa v55, v46 dst_sel:DWORD dst_unused:UNUSED_PAD src0_sel:WORD_1
	ds_read2st64_b32 v[148:149], v253 offset0:96 offset1:112
	v_cvt_f32_f16_sdwa v49, v36 dst_sel:DWORD dst_unused:UNUSED_PAD src0_sel:WORD_1
	v_pk_mul_f32 v[36:37], v[42:43], v[50:51]
	v_pk_mul_f32 v[42:43], v[62:63], v[58:59]
	v_pk_mul_f32 v[46:47], v[44:45], v[54:55]
	v_pk_mul_f32 v[44:45], v[44:45], v[48:49]
	v_pk_mul_f32 v[48:49], v[40:41], v[36:37]
	v_pk_mul_f32 v[50:51], v[40:41], v[42:43]
	v_cvt_pk_f16_f32 v36, v36, v37
	v_cvt_pk_f16_f32 v37, v42, v43
	v_pk_mul_f32 v[54:55], v[38:39], v[46:47]
	v_pk_mul_f32 v[58:59], v[38:39], v[44:45]
	ds_write2st64_b32 v203, v36, v37 offset1:18
	v_cvt_pk_f16_f32 v36, v48, v49
	v_cvt_pk_f16_f32 v37, v50, v51
	v_pk_mul_f32 v[46:47], v[0:1], v[46:47]
	ds_write2st64_b32 v203, v36, v37 offset0:36 offset1:54
	v_cvt_pk_f16_f32 v36, v54, v55
	v_cvt_pk_f16_f32 v37, v58, v59
	ds_write2st64_b32 v203, v36, v37 offset0:72 offset1:90
	v_cvt_f16_f32_e32 v36, v46
	v_pk_mul_f32 v[44:45], v[0:1], v[44:45]
	v_cvt_f16_f32_e32 v37, v47
	v_cvt_f16_f32_e32 v42, v44
	v_cvt_f16_f32_e32 v43, v45
	ds_write_b16 v174, v36 offset:24
	ds_write_b16 v174, v37 offset:64
	ds_write_b16 v174, v42 offset:5144
	ds_write_b16 v174, v43 offset:5184
	s_waitcnt lgkmcnt(9)
	ds_write_b16 v174, v60 offset:10264
	v_lshl_add_u32 v46, v204, 1, v2
	s_nop 0
	s_nop 0
	ds_read_b32 v61, v46 offset:32768
	v_rcp_f32_e32 v42, v56
	v_rcp_f32_e32 v43, v57
	s_waitcnt lgkmcnt(10)
	v_cvt_f32_f16_e32 v48, v147
	v_cvt_f32_f16_sdwa v49, v147 dst_sel:DWORD dst_unused:UNUSED_PAD src0_sel:WORD_1
	s_waitcnt lgkmcnt(9)
	v_cvt_f32_f16_e32 v54, v149
	v_cvt_f32_f16_sdwa v55, v149 dst_sel:DWORD dst_unused:UNUSED_PAD src0_sel:WORD_1
	v_cvt_f32_f16_e32 v46, v146
	v_lshl_add_u32 v253, v206, 1, v2
	ds_read2st64_b32 v[232:233], v253 offset0:64 offset1:80
	v_cvt_f32_f16_e32 v50, v148
	v_cvt_f32_f16_sdwa v51, v148 dst_sel:DWORD dst_unused:UNUSED_PAD src0_sel:WORD_1
	v_cvt_f32_f16_sdwa v47, v146 dst_sel:DWORD dst_unused:UNUSED_PAD src0_sel:WORD_1
	ds_read2st64_b32 v[146:147], v253 offset0:96 offset1:112
	v_pk_mul_f32 v[36:37], v[62:63], v[48:49]
	v_pk_mul_f32 v[44:45], v[56:57], v[54:55]
	v_pk_mul_f32 v[48:49], v[42:43], v[50:51]
	v_pk_mul_f32 v[42:43], v[42:43], v[46:47]
	v_pk_mul_f32 v[46:47], v[40:41], v[36:37]
	v_pk_mul_f32 v[50:51], v[40:41], v[44:45]
	v_cvt_pk_f16_f32 v36, v36, v37
	v_cvt_pk_f16_f32 v37, v44, v45
	v_pk_mul_f32 v[54:55], v[38:39], v[48:49]
	v_pk_mul_f32 v[58:59], v[38:39], v[42:43]
	ds_write2st64_b32 v205, v36, v37 offset1:18
	v_cvt_pk_f16_f32 v36, v46, v47
	v_cvt_pk_f16_f32 v37, v50, v51
	v_pk_mul_f32 v[48:49], v[0:1], v[48:49]
	ds_write2st64_b32 v205, v36, v37 offset0:36 offset1:54
	v_cvt_pk_f16_f32 v36, v54, v55
	v_cvt_pk_f16_f32 v37, v58, v59
	ds_write2st64_b32 v205, v36, v37 offset0:72 offset1:90
	v_cvt_f16_f32_e32 v36, v48
	v_pk_mul_f32 v[42:43], v[0:1], v[42:43]
	v_cvt_f16_f32_e32 v37, v49
	v_cvt_f16_f32_e32 v42, v42
	v_cvt_f16_f32_e32 v43, v43
	ds_write_b16 v174, v36 offset:26
	s_waitcnt lgkmcnt(14)
	ds_write_b16 v174, v37 offset:66
	s_waitcnt lgkmcnt(14)
	ds_write_b16 v174, v42 offset:5146
	s_waitcnt lgkmcnt(14)
	ds_write_b16 v174, v43 offset:5186
	s_waitcnt lgkmcnt(9)
	ds_write_b16 v174, v61 offset:10266
	v_lshl_add_u32 v46, v206, 1, v2
	s_nop 0
	s_nop 0
	ds_read_b32 v58, v46 offset:32768
	v_rcp_f32_e32 v42, v52
	v_rcp_f32_e32 v43, v53
	v_lshl_add_u32 v2, v208, 1, v2
	s_nop 0
	s_waitcnt lgkmcnt(10)
	v_cvt_f32_f16_e32 v48, v233
	v_cvt_f32_f16_sdwa v49, v233 dst_sel:DWORD dst_unused:UNUSED_PAD src0_sel:WORD_1
	s_nop 0
	s_waitcnt lgkmcnt(9)
	v_cvt_f32_f16_e32 v54, v147
	ds_read2st64_b32 v[148:149], v2 offset0:64 offset1:80
	v_cvt_f32_f16_sdwa v55, v147 dst_sel:DWORD dst_unused:UNUSED_PAD src0_sel:WORD_1
	v_cvt_f32_f16_e32 v46, v232
	v_cvt_f32_f16_e32 v50, v146
	ds_read2st64_b32 v[234:235], v2 offset0:96 offset1:112
	v_cvt_f32_f16_sdwa v51, v146 dst_sel:DWORD dst_unused:UNUSED_PAD src0_sel:WORD_1
	v_cvt_f32_f16_sdwa v47, v232 dst_sel:DWORD dst_unused:UNUSED_PAD src0_sel:WORD_1
	v_pk_mul_f32 v[36:37], v[56:57], v[48:49]
	v_pk_mul_f32 v[44:45], v[52:53], v[54:55]
	v_pk_mul_f32 v[48:49], v[42:43], v[50:51]
	v_pk_mul_f32 v[42:43], v[42:43], v[46:47]
	v_pk_mul_f32 v[46:47], v[40:41], v[36:37]
	v_pk_mul_f32 v[50:51], v[40:41], v[44:45]
	v_cvt_pk_f16_f32 v36, v36, v37
	v_cvt_pk_f16_f32 v37, v44, v45
	v_pk_mul_f32 v[54:55], v[38:39], v[48:49]
	v_pk_mul_f32 v[56:57], v[38:39], v[42:43]
	ds_write2st64_b32 v207, v36, v37 offset1:18
	v_cvt_pk_f16_f32 v36, v46, v47
	v_cvt_pk_f16_f32 v37, v50, v51
	v_pk_mul_f32 v[48:49], v[0:1], v[48:49]
	ds_write2st64_b32 v207, v36, v37 offset0:36 offset1:54
	v_cvt_pk_f16_f32 v36, v54, v55
	v_cvt_pk_f16_f32 v37, v56, v57
	ds_write2st64_b32 v207, v36, v37 offset0:72 offset1:90
	v_cvt_f16_f32_e32 v36, v48
	v_pk_mul_f32 v[42:43], v[0:1], v[42:43]
	v_cvt_f16_f32_e32 v37, v49
	v_cvt_f16_f32_e32 v42, v42
	v_cvt_f16_f32_e32 v43, v43
	ds_write_b16 v174, v36 offset:28
	s_waitcnt lgkmcnt(14)
	ds_write_b16 v174, v37 offset:68
	s_waitcnt lgkmcnt(14)
	ds_write_b16 v174, v42 offset:5148
	s_waitcnt lgkmcnt(14)
	ds_write_b16 v174, v43 offset:5188
	s_waitcnt lgkmcnt(9)
	ds_write_b16 v174, v58 offset:10268
	ds_read_b32 v2, v2 offset:32768
	v_rcp_f32_e32 v42, v0
	v_rcp_f32_e32 v43, v1
	s_waitcnt lgkmcnt(10)
	v_cvt_f32_f16_e32 v48, v149
	v_cvt_f32_f16_sdwa v49, v149 dst_sel:DWORD dst_unused:UNUSED_PAD src0_sel:WORD_1
	s_waitcnt lgkmcnt(9)
	v_cvt_f32_f16_e32 v54, v235
	v_cvt_f32_f16_sdwa v55, v235 dst_sel:DWORD dst_unused:UNUSED_PAD src0_sel:WORD_1
	v_cvt_f32_f16_e32 v46, v148
	v_cvt_f32_f16_e32 v50, v234
	v_cvt_f32_f16_sdwa v51, v234 dst_sel:DWORD dst_unused:UNUSED_PAD src0_sel:WORD_1
	v_cvt_f32_f16_sdwa v47, v148 dst_sel:DWORD dst_unused:UNUSED_PAD src0_sel:WORD_1
	v_pk_mul_f32 v[36:37], v[52:53], v[48:49]
	v_pk_mul_f32 v[44:45], v[0:1], v[54:55]
	v_pk_mul_f32 v[48:49], v[42:43], v[50:51]
	v_pk_mul_f32 v[42:43], v[42:43], v[46:47]
	v_pk_mul_f32 v[46:47], v[40:41], v[36:37]
	v_pk_mul_f32 v[40:41], v[40:41], v[44:45]
	v_cvt_pk_f16_f32 v36, v36, v37
	v_cvt_pk_f16_f32 v37, v44, v45
	v_pk_mul_f32 v[50:51], v[38:39], v[48:49]
	v_pk_mul_f32 v[38:39], v[38:39], v[42:43]
	ds_write2st64_b32 v209, v36, v37 offset1:18
	v_cvt_pk_f16_f32 v36, v46, v47
	v_cvt_pk_f16_f32 v37, v40, v41
	v_pk_mul_f32 v[48:49], v[0:1], v[48:49]
	ds_write2st64_b32 v209, v36, v37 offset0:36 offset1:54
	v_cvt_pk_f16_f32 v36, v50, v51
	v_cvt_pk_f16_f32 v37, v38, v39
	ds_write2st64_b32 v209, v36, v37 offset0:72 offset1:90
	v_cvt_f16_f32_e32 v36, v48
	v_pk_mul_f32 v[42:43], v[0:1], v[42:43]
	v_cvt_f16_f32_e32 v37, v49
	v_cvt_f16_f32_e32 v38, v42
	v_cvt_f16_f32_e32 v39, v43
	ds_write_b16 v174, v36 offset:30
	ds_write_b16 v174, v37 offset:70
	ds_write_b16 v174, v38 offset:5150
	s_waitcnt lgkmcnt(14)
	ds_write_b16 v174, v39 offset:5190
	s_nop 0
	s_waitcnt lgkmcnt(7)
	ds_write_b16 v174, v2 offset:10270
	v_perm_b32 v36, v61, v60, s82
	v_perm_b32 v37, v2, v58, s82
	ds_write_b64 v174, v[36:37] offset:10304
.LBB0_470:
	s_andn2_saveexec_b64 s[28:29], s[28:29]
	s_cbranch_execz .LBB0_472
	v_lshl_add_u32 v253, v194, 1, v2
	ds_read2st64_b32 v[36:37], v253 offset0:64 offset1:80
	ds_read2st64_b32 v[48:49], v253 offset0:96 offset1:112
	v_lshl_add_u32 v52, v194, 1, v2
	s_nop 0
	s_nop 0
	ds_read_b32 v64, v52 offset:32768
	v_rcp_f32_e32 v44, v58
	v_rcp_f32_e32 v45, v59
	s_nop 0
	s_waitcnt lgkmcnt(1)
	v_cvt_f32_f16_e32 v60, v49
	v_cvt_f32_f16_e32 v54, v37
	v_cvt_f32_f16_sdwa v55, v37 dst_sel:DWORD dst_unused:UNUSED_PAD src0_sel:WORD_1
	v_cvt_f32_f16_sdwa v61, v49 dst_sel:DWORD dst_unused:UNUSED_PAD src0_sel:WORD_1
	v_lshl_add_u32 v253, v196, 1, v2
	ds_read2st64_b32 v[146:147], v253 offset0:64 offset1:80
	v_cvt_f32_f16_e32 v52, v36
	v_cvt_f32_f16_e32 v56, v48
	v_cvt_f32_f16_sdwa v57, v48 dst_sel:DWORD dst_unused:UNUSED_PAD src0_sel:WORD_1
	ds_read2st64_b32 v[148:149], v253 offset0:96 offset1:112
	v_cvt_f32_f16_sdwa v53, v36 dst_sel:DWORD dst_unused:UNUSED_PAD src0_sel:WORD_1
	v_pk_mul_f32 v[36:37], v[38:39], v[54:55]
	v_pk_mul_f32 v[48:49], v[58:59], v[60:61]
	v_pk_mul_f32 v[54:55], v[44:45], v[56:57]
	v_pk_mul_f32 v[44:45], v[44:45], v[52:53]
	v_pk_mul_f32 v[52:53], v[40:41], v[36:37]
	v_pk_mul_f32 v[56:57], v[40:41], v[48:49]
	v_cvt_pk_f16_f32 v36, v36, v37
	v_cvt_pk_f16_f32 v37, v48, v49
	v_pk_mul_f32 v[60:61], v[38:39], v[54:55]
	v_pk_mul_f32 v[62:63], v[38:39], v[44:45]
	ds_write2st64_b32 v195, v36, v37 offset1:18
	v_cvt_pk_f16_f32 v36, v52, v53
	v_cvt_pk_f16_f32 v37, v56, v57
	v_pk_mul_f32 v[54:55], v[0:1], v[54:55]
	ds_write2st64_b32 v195, v36, v37 offset0:36 offset1:54
	v_cvt_pk_f16_f32 v36, v60, v61
	v_cvt_pk_f16_f32 v37, v62, v63
	ds_write2st64_b32 v195, v36, v37 offset0:72 offset1:90
	v_cvt_f16_f32_e32 v36, v54
	v_pk_mul_f32 v[44:45], v[0:1], v[44:45]
	v_cvt_f16_f32_e32 v37, v55
	v_cvt_f16_f32_e32 v44, v44
	v_cvt_f16_f32_e32 v45, v45
	ds_write_b16 v174, v36 offset:16
	ds_write_b16 v174, v37 offset:56
	ds_write_b16 v174, v44 offset:5136
	ds_write_b16 v174, v45 offset:5176
	s_waitcnt lgkmcnt(9)
	ds_write_b16 v174, v64 offset:10256
	v_lshl_add_u32 v52, v196, 1, v2
	s_nop 0
	s_nop 0
	ds_read_b32 v62, v52 offset:32768
	v_rcp_f32_e32 v44, v50
	v_rcp_f32_e32 v45, v51
	s_waitcnt lgkmcnt(10)
	v_cvt_f32_f16_e32 v54, v147
	v_cvt_f32_f16_sdwa v55, v147 dst_sel:DWORD dst_unused:UNUSED_PAD src0_sel:WORD_1
	s_waitcnt lgkmcnt(9)
	v_cvt_f32_f16_e32 v60, v149
	v_cvt_f32_f16_sdwa v61, v149 dst_sel:DWORD dst_unused:UNUSED_PAD src0_sel:WORD_1
	v_cvt_f32_f16_e32 v52, v146
	v_lshl_add_u32 v253, v198, 1, v2
	ds_read2st64_b32 v[232:233], v253 offset0:64 offset1:80
	v_cvt_f32_f16_e32 v56, v148
	v_cvt_f32_f16_sdwa v57, v148 dst_sel:DWORD dst_unused:UNUSED_PAD src0_sel:WORD_1
	v_cvt_f32_f16_sdwa v53, v146 dst_sel:DWORD dst_unused:UNUSED_PAD src0_sel:WORD_1
	ds_read2st64_b32 v[146:147], v253 offset0:96 offset1:112
	v_pk_mul_f32 v[36:37], v[58:59], v[54:55]
	v_pk_mul_f32 v[48:49], v[50:51], v[60:61]
	v_pk_mul_f32 v[54:55], v[44:45], v[56:57]
	v_pk_mul_f32 v[44:45], v[44:45], v[52:53]
	v_pk_mul_f32 v[52:53], v[40:41], v[36:37]
	v_pk_mul_f32 v[56:57], v[40:41], v[48:49]
	v_cvt_pk_f16_f32 v36, v36, v37
	v_cvt_pk_f16_f32 v37, v48, v49
	v_pk_mul_f32 v[58:59], v[38:39], v[54:55]
	v_pk_mul_f32 v[60:61], v[38:39], v[44:45]
	ds_write2st64_b32 v197, v36, v37 offset1:18
	v_cvt_pk_f16_f32 v36, v52, v53
	v_cvt_pk_f16_f32 v37, v56, v57
	v_pk_mul_f32 v[54:55], v[0:1], v[54:55]
	ds_write2st64_b32 v197, v36, v37 offset0:36 offset1:54
	v_cvt_pk_f16_f32 v36, v58, v59
	v_cvt_pk_f16_f32 v37, v60, v61
	ds_write2st64_b32 v197, v36, v37 offset0:72 offset1:90
	v_cvt_f16_f32_e32 v36, v54
	v_pk_mul_f32 v[44:45], v[0:1], v[44:45]
	v_cvt_f16_f32_e32 v37, v55
	v_cvt_f16_f32_e32 v44, v44
	v_cvt_f16_f32_e32 v45, v45
	ds_write_b16 v174, v36 offset:18
	s_waitcnt lgkmcnt(14)
	ds_write_b16 v174, v37 offset:58
	s_waitcnt lgkmcnt(14)
	ds_write_b16 v174, v44 offset:5138
	s_waitcnt lgkmcnt(14)
	ds_write_b16 v174, v45 offset:5178
	s_waitcnt lgkmcnt(9)
	ds_write_b16 v174, v62 offset:10258
	v_lshl_add_u32 v52, v198, 1, v2
	s_nop 0
	s_nop 0
	ds_read_b32 v60, v52 offset:32768
	v_rcp_f32_e32 v44, v46
	v_rcp_f32_e32 v45, v47
	v_lshl_add_u32 v2, v200, 1, v2
	s_nop 0
	s_waitcnt lgkmcnt(10)
	v_cvt_f32_f16_e32 v54, v233
	v_cvt_f32_f16_sdwa v55, v233 dst_sel:DWORD dst_unused:UNUSED_PAD src0_sel:WORD_1
	s_nop 0
	s_waitcnt lgkmcnt(9)
	v_cvt_f32_f16_e32 v58, v147
	ds_read2st64_b32 v[148:149], v2 offset0:64 offset1:80
	v_cvt_f32_f16_sdwa v59, v147 dst_sel:DWORD dst_unused:UNUSED_PAD src0_sel:WORD_1
	v_cvt_f32_f16_e32 v52, v232
	v_cvt_f32_f16_e32 v56, v146
	ds_read2st64_b32 v[234:235], v2 offset0:96 offset1:112
	v_cvt_f32_f16_sdwa v57, v146 dst_sel:DWORD dst_unused:UNUSED_PAD src0_sel:WORD_1
	v_cvt_f32_f16_sdwa v53, v232 dst_sel:DWORD dst_unused:UNUSED_PAD src0_sel:WORD_1
	v_pk_mul_f32 v[36:37], v[50:51], v[54:55]
	v_pk_mul_f32 v[48:49], v[46:47], v[58:59]
	v_pk_mul_f32 v[50:51], v[44:45], v[56:57]
	v_pk_mul_f32 v[44:45], v[44:45], v[52:53]
	v_pk_mul_f32 v[52:53], v[40:41], v[36:37]
	v_pk_mul_f32 v[54:55], v[40:41], v[48:49]
	v_cvt_pk_f16_f32 v36, v36, v37
	v_cvt_pk_f16_f32 v37, v48, v49
	v_pk_mul_f32 v[56:57], v[38:39], v[50:51]
	v_pk_mul_f32 v[58:59], v[38:39], v[44:45]
	ds_write2st64_b32 v199, v36, v37 offset1:18
	v_cvt_pk_f16_f32 v36, v52, v53
	v_cvt_pk_f16_f32 v37, v54, v55
	v_pk_mul_f32 v[50:51], v[0:1], v[50:51]
	ds_write2st64_b32 v199, v36, v37 offset0:36 offset1:54
	v_cvt_pk_f16_f32 v36, v56, v57
	v_cvt_pk_f16_f32 v37, v58, v59
	ds_write2st64_b32 v199, v36, v37 offset0:72 offset1:90
	v_cvt_f16_f32_e32 v36, v50
	v_pk_mul_f32 v[44:45], v[0:1], v[44:45]
	v_cvt_f16_f32_e32 v37, v51
	v_cvt_f16_f32_e32 v44, v44
	v_cvt_f16_f32_e32 v45, v45
	ds_write_b16 v174, v36 offset:20
	s_waitcnt lgkmcnt(14)
	ds_write_b16 v174, v37 offset:60
	s_waitcnt lgkmcnt(14)
	ds_write_b16 v174, v44 offset:5140
	s_waitcnt lgkmcnt(14)
	ds_write_b16 v174, v45 offset:5180
	s_waitcnt lgkmcnt(9)
	ds_write_b16 v174, v60 offset:10260
	ds_read_b32 v2, v2 offset:32768
	v_rcp_f32_e32 v44, v42
	v_rcp_f32_e32 v45, v43
	s_waitcnt lgkmcnt(10)
	v_cvt_f32_f16_e32 v52, v149
	v_cvt_f32_f16_sdwa v53, v149 dst_sel:DWORD dst_unused:UNUSED_PAD src0_sel:WORD_1
	s_waitcnt lgkmcnt(9)
	v_cvt_f32_f16_e32 v56, v235
	v_cvt_f32_f16_sdwa v57, v235 dst_sel:DWORD dst_unused:UNUSED_PAD src0_sel:WORD_1
	v_cvt_f32_f16_e32 v50, v148
	v_cvt_f32_f16_e32 v54, v234
	v_cvt_f32_f16_sdwa v55, v234 dst_sel:DWORD dst_unused:UNUSED_PAD src0_sel:WORD_1
	v_cvt_f32_f16_sdwa v51, v148 dst_sel:DWORD dst_unused:UNUSED_PAD src0_sel:WORD_1
	v_pk_mul_f32 v[36:37], v[46:47], v[52:53]
	v_pk_mul_f32 v[42:43], v[42:43], v[56:57]
	v_pk_mul_f32 v[46:47], v[44:45], v[54:55]
	v_pk_mul_f32 v[44:45], v[44:45], v[50:51]
	v_pk_mul_f32 v[48:49], v[40:41], v[36:37]
	v_pk_mul_f32 v[40:41], v[40:41], v[42:43]
	v_cvt_pk_f16_f32 v36, v36, v37
	v_cvt_pk_f16_f32 v37, v42, v43
	v_pk_mul_f32 v[50:51], v[38:39], v[46:47]
	v_pk_mul_f32 v[38:39], v[38:39], v[44:45]
	ds_write2st64_b32 v201, v36, v37 offset1:18
	v_cvt_pk_f16_f32 v36, v48, v49
	v_cvt_pk_f16_f32 v37, v40, v41
	v_pk_mul_f32 v[46:47], v[0:1], v[46:47]
	ds_write2st64_b32 v201, v36, v37 offset0:36 offset1:54
	v_cvt_pk_f16_f32 v36, v50, v51
	v_cvt_pk_f16_f32 v37, v38, v39
	ds_write2st64_b32 v201, v36, v37 offset0:72 offset1:90
	v_cvt_f16_f32_e32 v36, v46
	v_pk_mul_f32 v[44:45], v[0:1], v[44:45]
	v_cvt_f16_f32_e32 v37, v47
	v_cvt_f16_f32_e32 v38, v44
	v_cvt_f16_f32_e32 v39, v45
	ds_write_b16 v174, v36 offset:22
	ds_write_b16 v174, v37 offset:62
	ds_write_b16 v174, v38 offset:5142
	s_waitcnt lgkmcnt(14)
	ds_write_b16 v174, v39 offset:5182
	s_nop 0
	s_waitcnt lgkmcnt(7)
	ds_write_b16 v174, v2 offset:10262
	v_perm_b32 v36, v62, v64, s82
	v_perm_b32 v37, v2, v60, s82
	ds_write_b64 v174, v[36:37] offset:10296

.LBB0_473:
	v_cmp_eq_u32_e32 vcc, 1, v172
	s_and_saveexec_b64 s[28:29], vcc
	s_cbranch_execz .LBB0_475
	v_lshl_add_u32 v253, v186, 1, v2
	ds_read2st64_b32 v[36:37], v253 offset0:64 offset1:80
	ds_read2st64_b32 v[46:47], v253 offset0:96 offset1:112
	v_lshl_add_u32 v50, v186, 1, v2
	s_nop 0
	s_nop 0
	ds_read_b32 v62, v50 offset:32768
	v_rcp_f32_e32 v42, v54
	v_rcp_f32_e32 v43, v55
	s_nop 0
	s_waitcnt lgkmcnt(1)
	v_cvt_f32_f16_e32 v58, v47
	v_cvt_f32_f16_e32 v52, v37
	v_cvt_f32_f16_sdwa v53, v37 dst_sel:DWORD dst_unused:UNUSED_PAD src0_sel:WORD_1
	v_cvt_f32_f16_sdwa v59, v47 dst_sel:DWORD dst_unused:UNUSED_PAD src0_sel:WORD_1
	v_lshl_add_u32 v253, v188, 1, v2
	ds_read2st64_b32 v[146:147], v253 offset0:64 offset1:80
	v_cvt_f32_f16_e32 v50, v36
	v_cvt_f32_f16_e32 v56, v46
	v_cvt_f32_f16_sdwa v57, v46 dst_sel:DWORD dst_unused:UNUSED_PAD src0_sel:WORD_1
	ds_read2st64_b32 v[148:149], v253 offset0:96 offset1:112
	v_cvt_f32_f16_sdwa v51, v36 dst_sel:DWORD dst_unused:UNUSED_PAD src0_sel:WORD_1
	v_pk_mul_f32 v[36:37], v[60:61], v[52:53]
	v_pk_mul_f32 v[46:47], v[54:55], v[58:59]
	v_pk_mul_f32 v[52:53], v[42:43], v[56:57]
	v_pk_mul_f32 v[42:43], v[42:43], v[50:51]
	v_pk_mul_f32 v[50:51], v[40:41], v[36:37]
	v_pk_mul_f32 v[56:57], v[40:41], v[46:47]
	v_cvt_pk_f16_f32 v36, v36, v37
	v_cvt_pk_f16_f32 v37, v46, v47
	v_pk_mul_f32 v[58:59], v[38:39], v[52:53]
	v_pk_mul_f32 v[60:61], v[38:39], v[42:43]
	ds_write2st64_b32 v187, v36, v37 offset1:18
	v_cvt_pk_f16_f32 v36, v50, v51
	v_cvt_pk_f16_f32 v37, v56, v57
	v_pk_mul_f32 v[52:53], v[0:1], v[52:53]
	ds_write2st64_b32 v187, v36, v37 offset0:36 offset1:54
	v_cvt_pk_f16_f32 v36, v58, v59
	v_cvt_pk_f16_f32 v37, v60, v61
	ds_write2st64_b32 v187, v36, v37 offset0:72 offset1:90
	v_cvt_f16_f32_e32 v36, v52
	v_pk_mul_f32 v[42:43], v[0:1], v[42:43]
	v_cvt_f16_f32_e32 v37, v53
	v_cvt_f16_f32_e32 v42, v42
	v_cvt_f16_f32_e32 v43, v43
	ds_write_b16 v174, v36 offset:8
	ds_write_b16 v174, v37 offset:48
	ds_write_b16 v174, v42 offset:5128
	ds_write_b16 v174, v43 offset:5168
	s_waitcnt lgkmcnt(9)
	ds_write_b16 v174, v62 offset:10248
	v_lshl_add_u32 v50, v188, 1, v2
	s_nop 0
	s_nop 0
	ds_read_b32 v60, v50 offset:32768
	v_rcp_f32_e32 v42, v48
	v_rcp_f32_e32 v43, v49
	s_waitcnt lgkmcnt(10)
	v_cvt_f32_f16_e32 v52, v147
	v_cvt_f32_f16_sdwa v53, v147 dst_sel:DWORD dst_unused:UNUSED_PAD src0_sel:WORD_1
	s_waitcnt lgkmcnt(9)
	v_cvt_f32_f16_e32 v58, v149
	v_cvt_f32_f16_sdwa v59, v149 dst_sel:DWORD dst_unused:UNUSED_PAD src0_sel:WORD_1
	v_cvt_f32_f16_e32 v50, v146
	v_lshl_add_u32 v253, v190, 1, v2
	ds_read2st64_b32 v[232:233], v253 offset0:64 offset1:80
	v_cvt_f32_f16_e32 v56, v148
	v_cvt_f32_f16_sdwa v57, v148 dst_sel:DWORD dst_unused:UNUSED_PAD src0_sel:WORD_1
	v_cvt_f32_f16_sdwa v51, v146 dst_sel:DWORD dst_unused:UNUSED_PAD src0_sel:WORD_1
	ds_read2st64_b32 v[146:147], v253 offset0:96 offset1:112
	v_pk_mul_f32 v[36:37], v[54:55], v[52:53]
	v_pk_mul_f32 v[46:47], v[48:49], v[58:59]
	v_pk_mul_f32 v[52:53], v[42:43], v[56:57]
	v_pk_mul_f32 v[42:43], v[42:43], v[50:51]
	v_pk_mul_f32 v[50:51], v[40:41], v[36:37]
	v_pk_mul_f32 v[54:55], v[40:41], v[46:47]
	v_cvt_pk_f16_f32 v36, v36, v37
	v_cvt_pk_f16_f32 v37, v46, v47
	v_pk_mul_f32 v[56:57], v[38:39], v[52:53]
	v_pk_mul_f32 v[58:59], v[38:39], v[42:43]
	ds_write2st64_b32 v189, v36, v37 offset1:18
	v_cvt_pk_f16_f32 v36, v50, v51
	v_cvt_pk_f16_f32 v37, v54, v55
	v_pk_mul_f32 v[52:53], v[0:1], v[52:53]
	ds_write2st64_b32 v189, v36, v37 offset0:36 offset1:54
	v_cvt_pk_f16_f32 v36, v56, v57
	v_cvt_pk_f16_f32 v37, v58, v59
	ds_write2st64_b32 v189, v36, v37 offset0:72 offset1:90
	v_cvt_f16_f32_e32 v36, v52
	v_pk_mul_f32 v[42:43], v[0:1], v[42:43]
	v_cvt_f16_f32_e32 v37, v53
	v_cvt_f16_f32_e32 v42, v42
	v_cvt_f16_f32_e32 v43, v43
	ds_write_b16 v174, v36 offset:10
	s_waitcnt lgkmcnt(14)
	ds_write_b16 v174, v37 offset:50
	s_waitcnt lgkmcnt(14)
	ds_write_b16 v174, v42 offset:5130
	s_waitcnt lgkmcnt(14)
	ds_write_b16 v174, v43 offset:5170
	s_waitcnt lgkmcnt(9)
	ds_write_b16 v174, v60 offset:10250
	v_lshl_add_u32 v50, v190, 1, v2
	s_nop 0
	s_nop 0
	ds_read_b32 v58, v50 offset:32768
	v_rcp_f32_e32 v42, v44
	v_rcp_f32_e32 v43, v45
	v_lshl_add_u32 v2, v192, 1, v2
	s_nop 0
	s_waitcnt lgkmcnt(10)
	v_cvt_f32_f16_e32 v52, v233
	v_cvt_f32_f16_sdwa v53, v233 dst_sel:DWORD dst_unused:UNUSED_PAD src0_sel:WORD_1
	ds_read2st64_b32 v[148:149], v2 offset0:64 offset1:80
	s_waitcnt lgkmcnt(10)
	v_cvt_f32_f16_e32 v56, v147
	v_cvt_f32_f16_sdwa v57, v147 dst_sel:DWORD dst_unused:UNUSED_PAD src0_sel:WORD_1
	ds_read2st64_b32 v[234:235], v2 offset0:96 offset1:112
	v_cvt_f32_f16_e32 v50, v232
	v_cvt_f32_f16_e32 v54, v146
	v_cvt_f32_f16_sdwa v55, v146 dst_sel:DWORD dst_unused:UNUSED_PAD src0_sel:WORD_1
	v_cvt_f32_f16_sdwa v51, v232 dst_sel:DWORD dst_unused:UNUSED_PAD src0_sel:WORD_1
	v_pk_mul_f32 v[36:37], v[48:49], v[52:53]
	v_pk_mul_f32 v[46:47], v[44:45], v[56:57]
	v_pk_mul_f32 v[48:49], v[42:43], v[54:55]
	v_pk_mul_f32 v[42:43], v[42:43], v[50:51]
	v_pk_mul_f32 v[50:51], v[40:41], v[36:37]
	v_pk_mul_f32 v[52:53], v[40:41], v[46:47]
	v_cvt_pk_f16_f32 v36, v36, v37
	v_cvt_pk_f16_f32 v37, v46, v47
	v_pk_mul_f32 v[54:55], v[38:39], v[48:49]
	v_pk_mul_f32 v[56:57], v[38:39], v[42:43]
	ds_write2st64_b32 v191, v36, v37 offset1:18
	v_cvt_pk_f16_f32 v36, v50, v51
	v_cvt_pk_f16_f32 v37, v52, v53
	v_pk_mul_f32 v[48:49], v[0:1], v[48:49]
	ds_write2st64_b32 v191, v36, v37 offset0:36 offset1:54
	v_cvt_pk_f16_f32 v36, v54, v55
	v_cvt_pk_f16_f32 v37, v56, v57
	ds_write2st64_b32 v191, v36, v37 offset0:72 offset1:90
	v_cvt_f16_f32_e32 v36, v48
	v_pk_mul_f32 v[42:43], v[0:1], v[42:43]
	v_cvt_f16_f32_e32 v37, v49
	v_cvt_f16_f32_e32 v42, v42
	v_cvt_f16_f32_e32 v43, v43
	ds_write_b16 v174, v36 offset:12
	s_waitcnt lgkmcnt(14)
	ds_write_b16 v174, v37 offset:52
	s_waitcnt lgkmcnt(14)
	ds_write_b16 v174, v42 offset:5132
	s_waitcnt lgkmcnt(14)
	ds_write_b16 v174, v43 offset:5172
	s_waitcnt lgkmcnt(9)
	ds_write_b16 v174, v58 offset:10252
	ds_read_b32 v2, v2 offset:32768
	s_waitcnt lgkmcnt(10)
	v_cvt_f32_f16_e32 v48, v149
	v_cvt_f32_f16_sdwa v49, v149 dst_sel:DWORD dst_unused:UNUSED_PAD src0_sel:WORD_1
	s_waitcnt lgkmcnt(9)
	v_cvt_f32_f16_e32 v52, v235
	v_cvt_f32_f16_sdwa v53, v235 dst_sel:DWORD dst_unused:UNUSED_PAD src0_sel:WORD_1
	v_cvt_f32_f16_e32 v46, v148
	v_cvt_f32_f16_e32 v50, v234
	v_cvt_f32_f16_sdwa v51, v234 dst_sel:DWORD dst_unused:UNUSED_PAD src0_sel:WORD_1
	v_cvt_f32_f16_sdwa v47, v148 dst_sel:DWORD dst_unused:UNUSED_PAD src0_sel:WORD_1
	v_pk_mul_f32 v[36:37], v[44:45], v[48:49]
	v_pk_mul_f32 v[42:43], v[38:39], v[52:53]
	v_pk_mul_f32 v[44:45], v[40:41], v[50:51]
	v_pk_mul_f32 v[46:47], v[40:41], v[46:47]
	v_pk_mul_f32 v[48:49], v[40:41], v[36:37]
	v_pk_mul_f32 v[40:41], v[40:41], v[42:43]
	v_cvt_pk_f16_f32 v36, v36, v37
	v_cvt_pk_f16_f32 v37, v42, v43
	v_pk_mul_f32 v[50:51], v[38:39], v[44:45]
	v_pk_mul_f32 v[38:39], v[38:39], v[46:47]
	ds_write2st64_b32 v193, v36, v37 offset1:18
	v_cvt_pk_f16_f32 v36, v48, v49
	v_cvt_pk_f16_f32 v37, v40, v41
	v_pk_mul_f32 v[44:45], v[0:1], v[44:45]
	ds_write2st64_b32 v193, v36, v37 offset0:36 offset1:54
	v_cvt_pk_f16_f32 v36, v50, v51
	v_cvt_pk_f16_f32 v37, v38, v39
	ds_write2st64_b32 v193, v36, v37 offset0:72 offset1:90
	v_cvt_f16_f32_e32 v36, v44
	v_pk_mul_f32 v[46:47], v[0:1], v[46:47]
	v_cvt_f16_f32_e32 v37, v45
	v_cvt_f16_f32_e32 v38, v46
	v_cvt_f16_f32_e32 v39, v47
	ds_write_b16 v174, v36 offset:14
	ds_write_b16 v174, v37 offset:54
	ds_write_b16 v174, v38 offset:5134
	s_waitcnt lgkmcnt(14)
	ds_write_b16 v174, v39 offset:5174
	s_nop 0
	s_waitcnt lgkmcnt(7)
	ds_write_b16 v174, v2 offset:10254
	v_perm_b32 v36, v60, v62, s82
	v_perm_b32 v37, v2, v58, s82
	ds_write_b64 v174, v[36:37] offset:10288

.LBB0_900:
	s_or_b64 exec, exec, s[0:1]
	s_nop 5
	v_cvt_f16_f32_e32 v2, v52
	v_cvt_f16_f32_e32 v52, v53
	v_cvt_f16_f32_e32 v53, v54
	v_cvt_f16_f32_e32 v54, v55
	v_cndmask_b32_e64 v2, v2, 0, s[18:19]
	v_cndmask_b32_e64 v52, 0, v52, s[20:21]
	v_cndmask_b32_e64 v53, v53, 0, s[22:23]
	v_cndmask_b32_e64 v54, v54, 0, s[24:25]
	v_pack_b32_f16 v53, v53, v54
	v_pack_b32_f16 v52, v2, v52
	ds_write_b64 v123, v[52:53]
	s_waitcnt lgkmcnt(0)
	s_barrier
	ds_read_b128 v[126:129], v124 offset:55360
	ds_read_b128 v[52:55], v125
	ds_read_b128 v[134:137], v125 offset:64
	ds_read_b128 v[138:141], v125 offset:2304
	ds_read_b128 v[142:145], v125 offset:2368
	ds_read_b128 v[146:149], v125 offset:4608
	ds_read_b128 v[162:165], v125 offset:4672
	ds_read_b128 v[68:71], v124 offset:55296
	s_nop 0
	s_nop 0
	ds_read_b128 v[178:181], v125 offset:6912
	s_nop 0
	s_waitcnt lgkmcnt(1)
	v_mfma_f32_16x16x32_f16 v[48:51], v[68:71], v[52:55], v[48:51]
	s_nop 0
	v_add_u32_e32 v2, 0x1e500, v96
	ds_read_b128 v[182:185], v125 offset:6976
	s_add_i32 s28, s28, 1
	s_nop 0
	v_mfma_f32_16x16x32_f16 v[52:55], v[126:129], v[134:137], v[48:51]
	ds_read_b128 v[134:137], v2
	s_nop 2
	s_nop 0
	s_nop 0
	v_mfma_f32_16x16x32_f16 v[48:51], v[68:71], v[138:141], v[56:59]
	s_nop 2
	s_nop 0
	ds_read_b128 v[138:141], v248 offset:46080
	v_cvt_pk_f16_f32 v55, v54, v55
	v_cvt_pk_f16_f32 v54, v52, v53
	s_nop 0
	v_mfma_f32_16x16x32_f16 v[56:59], v[126:129], v[142:145], v[48:51]
	ds_read_b128 v[142:145], v248 offset:46144
	s_nop 2
	s_nop 0
	s_nop 0
	ds_read_b128 v[186:189], v2 offset:64
	v_mfma_f32_16x16x32_f16 v[48:51], v[68:71], v[146:149], v[60:63]
	s_nop 2
	s_nop 0
	s_nop 0
	ds_read_b128 v[146:149], v249 offset:48384
	v_mfma_f32_16x16x32_f16 v[60:63], v[126:129], v[162:165], v[48:51]
	s_nop 2
	s_nop 0
	ds_read_b128 v[162:165], v249 offset:48448
	s_nop 0
	s_waitcnt lgkmcnt(7)
	v_mfma_f32_16x16x32_f16 v[48:51], v[68:71], v[178:181], v[64:67]
	s_nop 2
	ds_read_b128 v[178:181], v2 offset:128
	s_nop 0
	s_nop 0
	s_waitcnt lgkmcnt(7)
	v_mfma_f32_16x16x32_f16 v[48:51], v[126:129], v[182:185], v[48:51]
	s_nop 0
	ds_read_b128 v[182:185], v248 offset:50688
	s_nop 0
	s_waitcnt lgkmcnt(7)
	v_pk_mul_f32 v[44:45], v[44:45], v[134:135]
	v_pk_mul_f32 v[46:47], v[46:47], v[136:137]
	ds_read_b128 v[134:137], v248 offset:50752
	s_nop 0
	s_nop 2
	v_cvt_pk_f16_f32 v51, v50, v51
	s_nop 0
	s_waitcnt lgkmcnt(7)
	v_mfma_f32_16x16x32_f16 v[44:47], v[138:141], v[68:71], v[44:47]
	ds_read_b128 v[138:141], v2 offset:192
	s_nop 0
	v_cvt_pk_f16_f32 v50, v48, v49
	s_nop 0
	s_waitcnt lgkmcnt(7)
	v_mfma_f32_16x16x32_f16 v[44:47], v[142:145], v[126:129], v[44:47]
	ds_read_b128 v[142:145], v249 offset:52992
	s_waitcnt lgkmcnt(7)
	v_pk_mul_f32 v[32:33], v[32:33], v[186:187]
	v_pk_mul_f32 v[34:35], v[34:35], v[188:189]
	s_nop 0
	s_nop 0
	s_waitcnt lgkmcnt(6)
	v_mfma_f32_16x16x32_f16 v[32:35], v[146:149], v[68:71], v[32:35]
	s_nop 0
	s_nop 0
	s_waitcnt lgkmcnt(5)
	v_mfma_f32_16x16x32_f16 v[32:35], v[162:165], v[126:129], v[32:35]
	s_waitcnt lgkmcnt(4)
	v_pk_mul_f32 v[40:41], v[40:41], v[178:179]
	v_pk_mul_f32 v[42:43], v[42:43], v[180:181]
	s_nop 0
	s_nop 0
	s_waitcnt lgkmcnt(3)
	v_mfma_f32_16x16x32_f16 v[40:43], v[182:185], v[68:71], v[40:43]
	s_nop 0
	s_nop 0
	s_waitcnt lgkmcnt(2)
	v_mfma_f32_16x16x32_f16 v[40:43], v[134:137], v[126:129], v[40:43]
	v_add_u32_e32 v2, s26, v91
	s_add_i32 s26, s26, 64
	s_waitcnt lgkmcnt(1)
	v_pk_mul_f32 v[36:37], v[36:37], v[138:139]
	v_pk_mul_f32 v[38:39], v[38:39], v[140:141]
	s_nop 0
	s_nop 0
	s_waitcnt lgkmcnt(0)
	v_mfma_f32_16x16x32_f16 v[36:39], v[142:145], v[68:71], v[36:39]
	ds_read_b128 v[64:67], v249 offset:53056
	s_nop 0
	s_waitcnt lgkmcnt(0)
	v_mfma_f32_16x16x32_f16 v[36:39], v[64:67], v[126:129], v[36:39]
	v_add_u32_e32 v64, s27, v112
	v_add_u32_e32 v65, 0xff, v64
	v_cndmask_b32_e64 v65, v65, v2, s[2:3]
	v_add_u32_e32 v52, v65, v89
	v_mad_i64_i32 v[52:53], s[0:1], v52, s88, v[82:83]
	global_store_dwordx2 v[52:53], v[54:55], off
	v_add_u32_e32 v52, 16, v2
	v_add_u32_e32 v53, 0xef, v64
	v_cndmask_b32_e64 v54, v53, v52, s[2:3]
	v_add_u32_e32 v54, v54, v89
	v_cvt_pk_f16_f32 v53, v58, v59
	v_cvt_pk_f16_f32 v52, v56, v57
	v_mad_i64_i32 v[54:55], s[0:1], v54, s88, v[82:83]
	global_store_dwordx2 v[54:55], v[52:53], off
	v_add_u32_e32 v52, 32, v2
	v_add_u32_e32 v53, 0xdf, v64
	v_cndmask_b32_e64 v54, v53, v52, s[2:3]
	v_add_u32_e32 v54, v54, v89
	v_cvt_pk_f16_f32 v53, v62, v63
	v_cvt_pk_f16_f32 v52, v60, v61
	v_mad_i64_i32 v[54:55], s[0:1], v54, s88, v[82:83]
	global_store_dwordx2 v[54:55], v[52:53], off
	v_add_u32_e32 v2, 48, v2
	v_add_u32_e32 v52, 0xcf, v64
	v_cndmask_b32_e64 v2, v52, v2, s[2:3]
	v_add_u32_e32 v2, v2, v89
	s_sub_i32 s27, s27, 64
	v_mad_i64_i32 v[48:49], s[0:1], v2, s88, v[82:83]
	s_cmpk_lg_i32 s27, 0xff00
	global_store_dwordx2 v[48:49], v[50:51], off
	s_cbranch_scc0 .LBB0_1058

.LBB0_913:
	s_or_b64 exec, exec, s[0:1]
	s_waitcnt lgkmcnt(0)
	s_barrier
	ds_read_b128 v[52:55], v92 offset:9216
	ds_read_b128 v[60:63], v94
	ds_read_b128 v[48:51], v92
	s_nop 0
	s_nop 0
	ds_read_b128 v[68:71], v101
	ds_read_b128 v[56:59], v250 offset:16
	s_nop 0
	v_add_u32_e32 v81, v95, v103
	s_nop 0
	s_waitcnt lgkmcnt(4)
	v_cvt_f32_f16_sdwa v67, v52 dst_sel:DWORD dst_unused:UNUSED_PAD src0_sel:WORD_1
	s_nop 0
	s_waitcnt lgkmcnt(3)
	v_mul_f32_e32 v2, 0x3fb8aa3b, v60
	v_exp_f32_e32 v60, v2
	v_mul_f32_e32 v2, 0x3fb8aa3b, v61
	v_exp_f32_e32 v61, v2
	v_cvt_f32_f16_e32 v66, v52
	v_rcp_f32_e32 v64, v60
	v_add3_u32 v52, v78, v97, v247
	v_rcp_f32_e32 v65, v61
	v_cvt_f32_f16_sdwa v127, v54 dst_sel:DWORD dst_unused:UNUSED_PAD src0_sel:WORD_1
	v_cvt_f32_f16_e32 v126, v54
	v_pk_mul_f32 v[66:67], v[64:65], v[66:67]
	s_waitcnt lgkmcnt(2)
	v_cvt_f32_f16_sdwa v65, v48 dst_sel:DWORD dst_unused:UNUSED_PAD src0_sel:WORD_1
	v_cvt_f32_f16_e32 v64, v48
	s_nop 0
	s_waitcnt lgkmcnt(1)
	v_fma_mixlo_f16 v2, v68, v66, 0
	ds_write_b16 v52, v2 offset:46080
	v_fma_mixlo_f16 v2, v69, v67, 0
	v_pk_mul_f32 v[64:65], v[64:65], s[72:73] op_sel_hi:[1,0]
	ds_write_b16 v121, v2 offset:46080
	v_mul_f32_e32 v2, 0x3fb8aa3b, v62
	v_pk_mul_f32 v[64:65], v[64:65], v[60:61]
	v_exp_f32_e32 v60, v2
	v_mul_f32_e32 v2, 0x3fb8aa3b, v63
	v_exp_f32_e32 v61, v2
	v_cvt_f32_f16_sdwa v69, v53 dst_sel:DWORD dst_unused:UNUSED_PAD src0_sel:WORD_1
	v_rcp_f32_e32 v62, v60
	v_cvt_f32_f16_e32 v68, v53
	v_rcp_f32_e32 v63, v61
	v_cvt_f32_f16_sdwa v53, v49 dst_sel:DWORD dst_unused:UNUSED_PAD src0_sel:WORD_1
	v_cvt_f32_f16_e32 v52, v49
	v_cvt_pk_f16_f32 v48, v64, v65
	v_pk_mul_f32 v[68:69], v[62:63], v[68:69]
	v_pk_mul_f32 v[52:53], v[52:53], s[72:73] op_sel_hi:[1,0]
	v_fma_mixlo_f16 v2, v70, v68, 0
	ds_write_b16 v121, v2 offset:46224
	v_fma_mixlo_f16 v2, v71, v69, 0
	ds_write_b16 v121, v2 offset:46368
	s_waitcnt lgkmcnt(4)
	v_mul_f32_e32 v2, 0x3fb8aa3b, v56
	v_exp_f32_e32 v56, v2
	v_mul_f32_e32 v2, 0x3fb8aa3b, v57
	v_exp_f32_e32 v57, v2
	v_pk_mul_f32 v[52:53], v[52:53], v[60:61]
	ds_read_b128 v[60:63], v102
	v_rcp_f32_e32 v70, v56
	s_nop 0
	v_rcp_f32_e32 v71, v57
	v_cvt_pk_f16_f32 v49, v52, v53
	v_pk_mul_f32 v[70:71], v[70:71], v[126:127]
	s_nop 0
	s_waitcnt lgkmcnt(0)
	v_fma_mixlo_f16 v2, v60, v70, 0
	ds_write_b16 v121, v2 offset:46512
	v_fma_mixlo_f16 v2, v61, v71, 0
	ds_write_b16 v121, v2 offset:46656
	v_mul_f32_e32 v2, 0x3fb8aa3b, v58
	v_cvt_f32_f16_sdwa v127, v50 dst_sel:DWORD dst_unused:UNUSED_PAD src0_sel:WORD_1
	v_cvt_f32_f16_e32 v126, v50
	v_exp_f32_e32 v58, v2
	v_mul_f32_e32 v2, 0x3fb8aa3b, v59
	v_exp_f32_e32 v59, v2
	v_pk_mul_f32 v[126:127], v[126:127], s[72:73] op_sel_hi:[1,0]
	v_cvt_f32_f16_sdwa v61, v55 dst_sel:DWORD dst_unused:UNUSED_PAD src0_sel:WORD_1
	v_pk_mul_f32 v[126:127], v[126:127], v[56:57]
	v_rcp_f32_e32 v56, v58
	v_rcp_f32_e32 v57, v59
	v_cvt_f32_f16_e32 v60, v55
	v_bfe_u32 v55, v71, 16, 1
	v_add3_u32 v55, v71, v55, s34
	v_cvt_pk_f16_f32 v50, v126, v127
	v_pk_mul_f32 v[128:129], v[56:57], v[60:61]
	v_bfe_u32 v56, v70, 16, 1
	v_fma_mixlo_f16 v2, v62, v128, 0
	ds_write_b16 v121, v2 offset:46800
	v_bfe_u32 v2, v129, 16, 1
	v_bfe_u32 v54, v128, 16, 1
	v_bfe_u32 v57, v69, 16, 1
	v_bfe_u32 v60, v68, 16, 1
	v_bfe_u32 v61, v67, 16, 1
	v_bfe_u32 v62, v66, 16, 1
	v_add3_u32 v62, v66, v62, s34
	v_add3_u32 v61, v67, v61, s34
	v_add3_u32 v60, v68, v60, s34
	v_add3_u32 v66, v69, v57, s34
	v_add3_u32 v56, v70, v56, s34
	v_add3_u32 v54, v128, v54, s34
	v_add3_u32 v2, v129, v2, s34
	v_perm_b32 v57, v2, v54, s35
	v_perm_b32 v56, v55, v56, s35
	v_perm_b32 v55, v66, v60, s35
	v_perm_b32 v54, v61, v62, s35
	v_cvt_f32_f16_sdwa v61, v51 dst_sel:DWORD dst_unused:UNUSED_PAD src0_sel:WORD_1
	v_cvt_f32_f16_e32 v60, v51
	v_bfe_u32 v62, v126, 16, 1
	v_bfe_u32 v66, v53, 16, 1
	v_bfe_u32 v67, v52, 16, 1
	v_pk_mul_f32 v[60:61], v[60:61], s[72:73] op_sel_hi:[1,0]
	v_bfe_u32 v68, v65, 16, 1
	v_pk_mul_f32 v[58:59], v[60:61], v[58:59]
	v_bfe_u32 v61, v127, 16, 1
	v_bfe_u32 v2, v59, 16, 1
	v_bfe_u32 v60, v58, 16, 1
	v_cvt_pk_f16_f32 v51, v58, v59
	v_bfe_u32 v69, v64, 16, 1
	v_add3_u32 v58, v58, v60, s34
	v_add3_u32 v2, v59, v2, s34
	v_add3_u32 v64, v64, v69, s34
	v_add3_u32 v65, v65, v68, s34
	v_add3_u32 v52, v52, v67, s34
	v_add3_u32 v53, v53, v66, s34
	v_add3_u32 v62, v126, v62, s34
	v_add3_u32 v66, v127, v61, s34
	v_perm_b32 v61, v2, v58, s35
	v_fma_mixlo_f16 v2, v63, v129, 0
	v_perm_b32 v60, v66, v62, s35
	v_perm_b32 v59, v53, v52, s35
	v_perm_b32 v58, v65, v64, s35
	ds_write_b16 v121, v2 offset:46944
	ds_write_b128 v92, v[58:61] offset:18432
	ds_write_b128 v92, v[54:57] offset:27648
	ds_write_b128 v92, v[48:51] offset:36864
	v_add_u32_e32 v2, v79, v72
	s_nop 0
	s_barrier
	ds_read_b128 v[52:55], v81 offset:36864
	ds_read_b128 v[56:59], v81 offset:39168
	ds_read_b128 v[60:63], v81 offset:41472
	ds_read_b128 v[64:67], v81 offset:43776
	ds_read_b128 v[68:71], v2 offset:64
	ds_read_b128 v[134:137], v81 offset:36928
	ds_read_b128 v[138:141], v81 offset:39232
	ds_read_b128 v[142:145], v81 offset:41536
	ds_read_b128 v[48:51], v2
	s_nop 0
	s_nop 0
	s_nop 0
	s_nop 0
	s_nop 0
	s_waitcnt lgkmcnt(0)
	v_mfma_f32_16x16x32_f16 v[52:55], v[48:51], v[52:55], 0
	s_nop 0
	v_mfma_f32_16x16x32_f16 v[56:59], v[48:51], v[56:59], 0
	s_nop 0
	v_mfma_f32_16x16x32_f16 v[60:63], v[48:51], v[60:63], 0
	s_nop 0
	v_mfma_f32_16x16x32_f16 v[64:67], v[48:51], v[64:67], 0
	s_nop 0
	s_nop 0
	v_add_u32_e32 v2, v100, v72
	s_nop 0
	v_mfma_f32_16x16x32_f16 v[48:51], v[68:71], v[134:137], v[52:55]
	s_nop 2
	s_nop 0
	s_nop 0
	v_mfma_f32_16x16x32_f16 v[56:59], v[68:71], v[138:141], v[56:59]
	s_nop 0
	s_nop 0
	v_mfma_f32_16x16x32_f16 v[60:63], v[68:71], v[142:145], v[60:63]
	ds_read_b128 v[52:55], v81 offset:43840
	s_nop 0
	s_waitcnt lgkmcnt(0)
	v_mfma_f32_16x16x32_f16 v[64:67], v[68:71], v[52:55], v[64:67]
	v_mov_b32_e32 v52, 0
	v_mov_b32_e32 v68, 0
	v_mov_b32_e32 v69, 0
	v_mov_b32_e32 v70, 0
	v_mov_b32_e32 v71, 0
	s_and_saveexec_b64 s[0:1], s[6:7]
	s_cbranch_execz .LBB0_915
	v_add_u32_e32 v251, v95, v106
	ds_read_b128 v[68:71], v2 offset:18432
	ds_read_b128 v[126:129], v251 offset:27648
	v_add_u32_e32 v53, v95, v106
	s_nop 0
	s_nop 0
	s_nop 0
	s_waitcnt lgkmcnt(0)
	v_mfma_f32_16x16x32_bf16 v[68:71], v[126:129], v[68:71], 0
	ds_read_b128 v[130:133], v53 offset:27712
	ds_read_b128 v[126:129], v2 offset:18496
	s_nop 0
	s_nop 0
	s_waitcnt lgkmcnt(0)
	v_mfma_f32_16x16x32_bf16 v[68:71], v[130:133], v[126:129], v[68:71]

.LBB0_929:
	s_and_b32 s27, s26, 1
	v_lshl_add_u32 v0, s27, 13, v234
	ds_read2_b64 v[36:39], v0 offset1:32
	v_mad_u32_u24 v2, s27, v167, v235
	s_waitcnt lgkmcnt(0)
	v_pk_mul_f32 v[66:67], v[36:37], v[38:39]
	ds_read2_b64 v[38:41], v0 offset0:64 offset1:96
	s_waitcnt lgkmcnt(0)
	v_pk_mul_f32 v[64:65], v[66:67], v[38:39]
	s_nop 0
	v_pk_mul_f32 v[60:61], v[64:65], v[40:41]
	ds_read2_b64 v[38:41], v0 offset0:128 offset1:160
	s_waitcnt lgkmcnt(0)
	v_pk_mul_f32 v[54:55], v[60:61], v[38:39]
	s_nop 0
	v_pk_mul_f32 v[48:49], v[54:55], v[40:41]
	ds_read2_b64 v[38:41], v0 offset0:192 offset1:224
	v_add_u32_e32 v0, 0x800, v0
	ds_read2_b64 v[68:71], v0 offset0:128 offset1:160
	s_waitcnt lgkmcnt(1)
	v_pk_mul_f32 v[44:45], v[48:49], v[38:39]
	s_nop 0
	v_pk_mul_f32 v[38:39], v[44:45], v[40:41]
	ds_read2_b64 v[40:43], v0 offset1:32
	s_waitcnt lgkmcnt(0)
	v_pk_mul_f32 v[58:59], v[38:39], v[40:41]
	s_nop 0
	v_pk_mul_f32 v[50:51], v[58:59], v[42:43]
	ds_read2_b64 v[40:43], v0 offset0:64 offset1:96
	s_waitcnt lgkmcnt(0)
	v_pk_mul_f32 v[46:47], v[50:51], v[40:41]
	s_nop 0
	v_pk_mul_f32 v[42:43], v[46:47], v[42:43]
	v_rcp_f32_e32 v40, v38
	v_pk_mul_f32 v[62:63], v[42:43], v[68:69]
	v_rcp_f32_e32 v41, v39
	v_pk_mul_f32 v[56:57], v[62:63], v[70:71]
	ds_read2_b64 v[68:71], v0 offset0:192 offset1:224
	s_waitcnt lgkmcnt(0)
	v_pk_mul_f32 v[52:53], v[56:57], v[68:69]
	s_nop 0
	v_pk_mul_f32 v[0:1], v[52:53], v[70:71]
	s_and_saveexec_b64 s[28:29], s[4:5]
	s_cbranch_execz .LBB0_931
	v_lshl_add_u32 v251, v179, 1, v2
	ds_read2st64_b32 v[72:73], v251 offset0:96 offset1:112
	ds_read2st64_b32 v[68:69], v251 offset0:64 offset1:80
	v_lshl_add_u32 v74, v179, 1, v2
	s_nop 0
	ds_read_b32 v84, v74 offset:32768
	s_nop 0
	v_rcp_f32_e32 v70, v36
	v_rcp_f32_e32 v71, v37
	s_nop 0
	s_nop 0
	s_waitcnt lgkmcnt(2)
	v_cvt_f32_f16_e32 v78, v73
	v_cvt_f32_f16_sdwa v79, v73 dst_sel:DWORD dst_unused:UNUSED_PAD src0_sel:WORD_1
	v_lshl_add_u32 v251, v186, 1, v2
	ds_read2st64_b32 v[148:149], v251 offset0:64 offset1:80
	s_waitcnt lgkmcnt(2)
	v_cvt_f32_f16_e32 v74, v68
	v_cvt_f32_f16_sdwa v75, v68 dst_sel:DWORD dst_unused:UNUSED_PAD src0_sel:WORD_1
	v_cvt_f32_f16_e32 v76, v72
	ds_read2st64_b32 v[162:163], v251 offset0:96 offset1:112
	v_cvt_f32_f16_sdwa v77, v72 dst_sel:DWORD dst_unused:UNUSED_PAD src0_sel:WORD_1
	v_cvt_f32_f16_e32 v72, v69
	v_cvt_f32_f16_sdwa v73, v69 dst_sel:DWORD dst_unused:UNUSED_PAD src0_sel:WORD_1
	v_pk_mul_f32 v[78:79], v[36:37], v[78:79]
	v_pk_mul_f32 v[76:77], v[70:71], v[76:77]
	v_pk_mul_f32 v[70:71], v[70:71], v[74:75]
	v_pk_mul_f32 v[72:73], v[40:41], v[72:73]
	v_pk_mul_f32 v[74:75], v[40:41], v[78:79]
	v_cvt_pk_f16_f32 v68, v78, v79
	v_pk_mul_f32 v[80:81], v[38:39], v[76:77]
	v_pk_mul_f32 v[82:83], v[38:39], v[70:71]
	ds_write2st64_b32 v185, v69, v68 offset1:18
	v_cvt_pk_f16_f32 v68, v72, v73
	v_cvt_pk_f16_f32 v69, v74, v75
	v_pk_mul_f32 v[76:77], v[0:1], v[76:77]
	ds_write2st64_b32 v185, v68, v69 offset0:36 offset1:54
	v_cvt_pk_f16_f32 v68, v80, v81
	v_cvt_pk_f16_f32 v69, v82, v83
	ds_write2st64_b32 v185, v68, v69 offset0:72 offset1:90
	v_cvt_f16_f32_e32 v68, v76
	v_pk_mul_f32 v[70:71], v[0:1], v[70:71]
	v_cvt_f16_f32_e32 v69, v77
	v_cvt_f16_f32_e32 v70, v70
	v_cvt_f16_f32_e32 v71, v71
	ds_write_b16 v180, v68
	ds_write_b16 v180, v69 offset:40
	ds_write_b16 v180, v70 offset:5120
	ds_write_b16 v180, v71 offset:5160
	s_waitcnt lgkmcnt(9)
	ds_write_b16 v180, v84 offset:10240
	v_lshl_add_u32 v74, v186, 1, v2
	s_nop 0
	s_nop 0
	ds_read_b32 v82, v74 offset:32768
	v_rcp_f32_e32 v70, v66
	v_rcp_f32_e32 v71, v67
	s_waitcnt lgkmcnt(10)
	v_cvt_f32_f16_e32 v76, v149
	v_cvt_f32_f16_sdwa v77, v149 dst_sel:DWORD dst_unused:UNUSED_PAD src0_sel:WORD_1
	s_waitcnt lgkmcnt(9)
	v_cvt_f32_f16_e32 v80, v163
	v_cvt_f32_f16_sdwa v81, v163 dst_sel:DWORD dst_unused:UNUSED_PAD src0_sel:WORD_1
	v_lshl_add_u32 v251, v188, 1, v2
	ds_read2st64_b32 v[164:165], v251 offset0:64 offset1:80
	v_cvt_f32_f16_e32 v74, v148
	v_cvt_f32_f16_e32 v78, v162
	v_cvt_f32_f16_sdwa v79, v162 dst_sel:DWORD dst_unused:UNUSED_PAD src0_sel:WORD_1
	ds_read2st64_b32 v[162:163], v251 offset0:96 offset1:112
	v_cvt_f32_f16_sdwa v75, v148 dst_sel:DWORD dst_unused:UNUSED_PAD src0_sel:WORD_1
	v_pk_mul_f32 v[36:37], v[36:37], v[76:77]
	v_pk_mul_f32 v[68:69], v[66:67], v[80:81]
	v_pk_mul_f32 v[72:73], v[70:71], v[78:79]
	v_pk_mul_f32 v[70:71], v[70:71], v[74:75]
	v_pk_mul_f32 v[74:75], v[40:41], v[36:37]
	v_pk_mul_f32 v[76:77], v[40:41], v[68:69]
	v_cvt_pk_f16_f32 v36, v36, v37
	v_cvt_pk_f16_f32 v37, v68, v69
	v_pk_mul_f32 v[78:79], v[38:39], v[72:73]
	v_pk_mul_f32 v[80:81], v[38:39], v[70:71]
	ds_write2st64_b32 v187, v36, v37 offset1:18
	v_cvt_pk_f16_f32 v36, v74, v75
	v_cvt_pk_f16_f32 v37, v76, v77
	v_pk_mul_f32 v[72:73], v[0:1], v[72:73]
	ds_write2st64_b32 v187, v36, v37 offset0:36 offset1:54
	v_cvt_pk_f16_f32 v36, v78, v79
	v_cvt_pk_f16_f32 v37, v80, v81
	ds_write2st64_b32 v187, v36, v37 offset0:72 offset1:90
	v_cvt_f16_f32_e32 v36, v72
	v_pk_mul_f32 v[70:71], v[0:1], v[70:71]
	v_cvt_f16_f32_e32 v37, v73
	v_cvt_f16_f32_e32 v68, v70
	v_cvt_f16_f32_e32 v69, v71
	ds_write_b16 v180, v36 offset:2
	s_waitcnt lgkmcnt(14)
	ds_write_b16 v180, v37 offset:42
	s_waitcnt lgkmcnt(14)
	ds_write_b16 v180, v68 offset:5122
	s_waitcnt lgkmcnt(14)
	ds_write_b16 v180, v69 offset:5162
	s_waitcnt lgkmcnt(9)
	ds_write_b16 v180, v82 offset:10242
	v_lshl_add_u32 v72, v188, 1, v2
	s_nop 0
	s_nop 0
	ds_read_b32 v80, v72 offset:32768
	v_rcp_f32_e32 v68, v64
	v_rcp_f32_e32 v69, v65
	s_waitcnt lgkmcnt(10)
	v_cvt_f32_f16_e32 v74, v165
	v_cvt_f32_f16_sdwa v75, v165 dst_sel:DWORD dst_unused:UNUSED_PAD src0_sel:WORD_1
	s_waitcnt lgkmcnt(9)
	v_cvt_f32_f16_e32 v78, v163
	v_cvt_f32_f16_sdwa v79, v163 dst_sel:DWORD dst_unused:UNUSED_PAD src0_sel:WORD_1
	v_lshl_add_u32 v251, v190, 1, v2
	ds_read2st64_b32 v[148:149], v251 offset0:64 offset1:80
	v_cvt_f32_f16_e32 v72, v164
	v_cvt_f32_f16_e32 v76, v162
	v_cvt_f32_f16_sdwa v77, v162 dst_sel:DWORD dst_unused:UNUSED_PAD src0_sel:WORD_1
	ds_read2st64_b32 v[162:163], v251 offset0:96 offset1:112
	v_cvt_f32_f16_sdwa v73, v164 dst_sel:DWORD dst_unused:UNUSED_PAD src0_sel:WORD_1
	v_pk_mul_f32 v[36:37], v[66:67], v[74:75]
	v_pk_mul_f32 v[66:67], v[64:65], v[78:79]
	v_pk_mul_f32 v[70:71], v[68:69], v[76:77]
	v_pk_mul_f32 v[68:69], v[68:69], v[72:73]
	v_pk_mul_f32 v[72:73], v[40:41], v[36:37]
	v_pk_mul_f32 v[74:75], v[40:41], v[66:67]
	v_cvt_pk_f16_f32 v36, v36, v37
	v_cvt_pk_f16_f32 v37, v66, v67
	v_pk_mul_f32 v[76:77], v[38:39], v[70:71]
	v_pk_mul_f32 v[78:79], v[38:39], v[68:69]
	ds_write2st64_b32 v189, v36, v37 offset1:18
	v_cvt_pk_f16_f32 v36, v72, v73
	v_cvt_pk_f16_f32 v37, v74, v75
	v_pk_mul_f32 v[70:71], v[0:1], v[70:71]
	ds_write2st64_b32 v189, v36, v37 offset0:36 offset1:54
	v_cvt_pk_f16_f32 v36, v76, v77
	v_cvt_pk_f16_f32 v37, v78, v79
	ds_write2st64_b32 v189, v36, v37 offset0:72 offset1:90
	v_cvt_f16_f32_e32 v36, v70
	v_pk_mul_f32 v[68:69], v[0:1], v[68:69]
	v_cvt_f16_f32_e32 v37, v71
	v_cvt_f16_f32_e32 v66, v68
	v_cvt_f16_f32_e32 v67, v69
	ds_write_b16 v180, v36 offset:4
	s_waitcnt lgkmcnt(14)
	ds_write_b16 v180, v37 offset:44
	s_waitcnt lgkmcnt(14)
	ds_write_b16 v180, v66 offset:5124
	s_waitcnt lgkmcnt(14)
	ds_write_b16 v180, v67 offset:5164
	s_waitcnt lgkmcnt(9)
	ds_write_b16 v180, v80 offset:10244
	v_lshl_add_u32 v70, v190, 1, v2
	s_nop 0
	s_nop 0
	ds_read_b32 v78, v70 offset:32768
	v_rcp_f32_e32 v66, v60
	v_rcp_f32_e32 v67, v61
	s_waitcnt lgkmcnt(10)
	v_cvt_f32_f16_e32 v72, v149
	v_cvt_f32_f16_sdwa v73, v149 dst_sel:DWORD dst_unused:UNUSED_PAD src0_sel:WORD_1
	s_waitcnt lgkmcnt(9)
	v_cvt_f32_f16_e32 v76, v163
	v_cvt_f32_f16_sdwa v77, v163 dst_sel:DWORD dst_unused:UNUSED_PAD src0_sel:WORD_1
	v_cvt_f32_f16_e32 v70, v148
	v_cvt_f32_f16_e32 v74, v162
	v_cvt_f32_f16_sdwa v75, v162 dst_sel:DWORD dst_unused:UNUSED_PAD src0_sel:WORD_1
	v_cvt_f32_f16_sdwa v71, v148 dst_sel:DWORD dst_unused:UNUSED_PAD src0_sel:WORD_1
	v_pk_mul_f32 v[36:37], v[64:65], v[72:73]
	v_pk_mul_f32 v[64:65], v[60:61], v[76:77]
	v_pk_mul_f32 v[68:69], v[66:67], v[74:75]
	v_pk_mul_f32 v[66:67], v[66:67], v[70:71]
	v_pk_mul_f32 v[70:71], v[40:41], v[36:37]
	v_pk_mul_f32 v[72:73], v[40:41], v[64:65]
	v_cvt_pk_f16_f32 v36, v36, v37
	v_cvt_pk_f16_f32 v37, v64, v65
	v_pk_mul_f32 v[74:75], v[38:39], v[68:69]
	v_pk_mul_f32 v[76:77], v[38:39], v[66:67]
	ds_write2st64_b32 v191, v36, v37 offset1:18
	v_cvt_pk_f16_f32 v36, v70, v71
	v_cvt_pk_f16_f32 v37, v72, v73
	v_pk_mul_f32 v[68:69], v[0:1], v[68:69]
	ds_write2st64_b32 v191, v36, v37 offset0:36 offset1:54
	v_cvt_pk_f16_f32 v36, v74, v75
	v_cvt_pk_f16_f32 v37, v76, v77
	ds_write2st64_b32 v191, v36, v37 offset0:72 offset1:90
	v_cvt_f16_f32_e32 v36, v68
	v_pk_mul_f32 v[66:67], v[0:1], v[66:67]
	v_cvt_f16_f32_e32 v37, v69
	v_cvt_f16_f32_e32 v64, v66
	v_cvt_f16_f32_e32 v65, v67
	ds_write_b16 v180, v36 offset:6
	ds_write_b16 v180, v37 offset:46
	ds_write_b16 v180, v64 offset:5126
	s_waitcnt lgkmcnt(14)
	ds_write_b16 v180, v65 offset:5166
	s_nop 0
	s_waitcnt lgkmcnt(7)
	ds_write_b16 v180, v78 offset:10246
	v_perm_b32 v36, v82, v84, s35
	v_perm_b32 v37, v78, v80, s35
	ds_write_b64 v180, v[36:37] offset:10280

.LBB0_942:
	v_cmp_lt_i32_e32 vcc, 2, v178
	s_and_saveexec_b64 s[30:31], vcc
	s_xor_b64 s[68:69], exec, s[30:31]
	s_cbranch_execz .LBB0_944
	v_lshl_add_u32 v251, v208, 1, v2
	ds_read2st64_b32 v[36:37], v251 offset0:64 offset1:80
	ds_read2st64_b32 v[46:47], v251 offset0:96 offset1:112
	v_lshl_add_u32 v48, v208, 1, v2
	s_nop 0
	s_nop 0
	ds_read_b32 v60, v48 offset:32768
	v_rcp_f32_e32 v44, v62
	v_rcp_f32_e32 v45, v63
	s_nop 0
	s_waitcnt lgkmcnt(1)
	v_cvt_f32_f16_e32 v58, v47
	v_cvt_f32_f16_e32 v50, v37
	v_cvt_f32_f16_sdwa v51, v37 dst_sel:DWORD dst_unused:UNUSED_PAD src0_sel:WORD_1
	v_cvt_f32_f16_sdwa v59, v47 dst_sel:DWORD dst_unused:UNUSED_PAD src0_sel:WORD_1
	v_lshl_add_u32 v251, v210, 1, v2
	ds_read2st64_b32 v[148:149], v251 offset0:64 offset1:80
	v_cvt_f32_f16_e32 v48, v36
	v_cvt_f32_f16_e32 v54, v46
	v_cvt_f32_f16_sdwa v55, v46 dst_sel:DWORD dst_unused:UNUSED_PAD src0_sel:WORD_1
	ds_read2st64_b32 v[162:163], v251 offset0:96 offset1:112
	v_cvt_f32_f16_sdwa v49, v36 dst_sel:DWORD dst_unused:UNUSED_PAD src0_sel:WORD_1
	v_pk_mul_f32 v[36:37], v[42:43], v[50:51]
	v_pk_mul_f32 v[42:43], v[62:63], v[58:59]
	v_pk_mul_f32 v[46:47], v[44:45], v[54:55]
	v_pk_mul_f32 v[44:45], v[44:45], v[48:49]
	v_pk_mul_f32 v[48:49], v[40:41], v[36:37]
	v_pk_mul_f32 v[50:51], v[40:41], v[42:43]
	v_cvt_pk_f16_f32 v36, v36, v37
	v_cvt_pk_f16_f32 v37, v42, v43
	v_pk_mul_f32 v[54:55], v[38:39], v[46:47]
	v_pk_mul_f32 v[58:59], v[38:39], v[44:45]
	ds_write2st64_b32 v209, v36, v37 offset1:18
	v_cvt_pk_f16_f32 v36, v48, v49
	v_cvt_pk_f16_f32 v37, v50, v51
	v_pk_mul_f32 v[46:47], v[0:1], v[46:47]
	ds_write2st64_b32 v209, v36, v37 offset0:36 offset1:54
	v_cvt_pk_f16_f32 v36, v54, v55
	v_cvt_pk_f16_f32 v37, v58, v59
	ds_write2st64_b32 v209, v36, v37 offset0:72 offset1:90
	v_cvt_f16_f32_e32 v36, v46
	v_pk_mul_f32 v[44:45], v[0:1], v[44:45]
	v_cvt_f16_f32_e32 v37, v47
	v_cvt_f16_f32_e32 v42, v44
	v_cvt_f16_f32_e32 v43, v45
	ds_write_b16 v180, v36 offset:24
	ds_write_b16 v180, v37 offset:64
	ds_write_b16 v180, v42 offset:5144
	ds_write_b16 v180, v43 offset:5184
	s_waitcnt lgkmcnt(9)
	ds_write_b16 v180, v60 offset:10264
	v_lshl_add_u32 v46, v210, 1, v2
	s_nop 0
	s_nop 0
	ds_read_b32 v61, v46 offset:32768
	v_rcp_f32_e32 v42, v56
	v_rcp_f32_e32 v43, v57
	s_waitcnt lgkmcnt(10)
	v_cvt_f32_f16_e32 v48, v149
	v_cvt_f32_f16_sdwa v49, v149 dst_sel:DWORD dst_unused:UNUSED_PAD src0_sel:WORD_1
	s_waitcnt lgkmcnt(9)
	v_cvt_f32_f16_e32 v54, v163
	v_cvt_f32_f16_sdwa v55, v163 dst_sel:DWORD dst_unused:UNUSED_PAD src0_sel:WORD_1
	v_cvt_f32_f16_e32 v46, v148
	v_lshl_add_u32 v251, v212, 1, v2
	ds_read2st64_b32 v[164:165], v251 offset0:64 offset1:80
	v_cvt_f32_f16_e32 v50, v162
	v_cvt_f32_f16_sdwa v51, v162 dst_sel:DWORD dst_unused:UNUSED_PAD src0_sel:WORD_1
	v_cvt_f32_f16_sdwa v47, v148 dst_sel:DWORD dst_unused:UNUSED_PAD src0_sel:WORD_1
	ds_read2st64_b32 v[148:149], v251 offset0:96 offset1:112
	v_pk_mul_f32 v[36:37], v[62:63], v[48:49]
	v_pk_mul_f32 v[44:45], v[56:57], v[54:55]
	v_pk_mul_f32 v[48:49], v[42:43], v[50:51]
	v_pk_mul_f32 v[42:43], v[42:43], v[46:47]
	v_pk_mul_f32 v[46:47], v[40:41], v[36:37]
	v_pk_mul_f32 v[50:51], v[40:41], v[44:45]
	v_cvt_pk_f16_f32 v36, v36, v37
	v_cvt_pk_f16_f32 v37, v44, v45
	v_pk_mul_f32 v[54:55], v[38:39], v[48:49]
	v_pk_mul_f32 v[58:59], v[38:39], v[42:43]
	ds_write2st64_b32 v211, v36, v37 offset1:18
	v_cvt_pk_f16_f32 v36, v46, v47
	v_cvt_pk_f16_f32 v37, v50, v51
	v_pk_mul_f32 v[48:49], v[0:1], v[48:49]
	ds_write2st64_b32 v211, v36, v37 offset0:36 offset1:54
	v_cvt_pk_f16_f32 v36, v54, v55
	v_cvt_pk_f16_f32 v37, v58, v59
	ds_write2st64_b32 v211, v36, v37 offset0:72 offset1:90
	v_cvt_f16_f32_e32 v36, v48
	v_pk_mul_f32 v[42:43], v[0:1], v[42:43]
	v_cvt_f16_f32_e32 v37, v49
	v_cvt_f16_f32_e32 v42, v42
	v_cvt_f16_f32_e32 v43, v43
	ds_write_b16 v180, v36 offset:26
	s_waitcnt lgkmcnt(14)
	ds_write_b16 v180, v37 offset:66
	s_waitcnt lgkmcnt(14)
	ds_write_b16 v180, v42 offset:5146
	s_waitcnt lgkmcnt(14)
	ds_write_b16 v180, v43 offset:5186
	s_waitcnt lgkmcnt(9)
	ds_write_b16 v180, v61 offset:10266
	v_lshl_add_u32 v46, v212, 1, v2
	s_nop 0
	s_nop 0
	ds_read_b32 v58, v46 offset:32768
	v_rcp_f32_e32 v42, v52
	v_rcp_f32_e32 v43, v53
	v_lshl_add_u32 v2, v214, 1, v2
	s_nop 0
	s_waitcnt lgkmcnt(10)
	v_cvt_f32_f16_e32 v48, v165
	v_cvt_f32_f16_sdwa v49, v165 dst_sel:DWORD dst_unused:UNUSED_PAD src0_sel:WORD_1
	s_nop 0
	s_waitcnt lgkmcnt(9)
	v_cvt_f32_f16_e32 v54, v149
	ds_read2st64_b32 v[162:163], v2 offset0:64 offset1:80
	v_cvt_f32_f16_sdwa v55, v149 dst_sel:DWORD dst_unused:UNUSED_PAD src0_sel:WORD_1
	v_cvt_f32_f16_e32 v46, v164
	v_cvt_f32_f16_e32 v50, v148
	ds_read2st64_b32 v[242:243], v2 offset0:96 offset1:112
	v_cvt_f32_f16_sdwa v51, v148 dst_sel:DWORD dst_unused:UNUSED_PAD src0_sel:WORD_1
	v_cvt_f32_f16_sdwa v47, v164 dst_sel:DWORD dst_unused:UNUSED_PAD src0_sel:WORD_1
	v_pk_mul_f32 v[36:37], v[56:57], v[48:49]
	v_pk_mul_f32 v[44:45], v[52:53], v[54:55]
	v_pk_mul_f32 v[48:49], v[42:43], v[50:51]
	v_pk_mul_f32 v[42:43], v[42:43], v[46:47]
	v_pk_mul_f32 v[46:47], v[40:41], v[36:37]
	v_pk_mul_f32 v[50:51], v[40:41], v[44:45]
	v_cvt_pk_f16_f32 v36, v36, v37
	v_cvt_pk_f16_f32 v37, v44, v45
	v_pk_mul_f32 v[54:55], v[38:39], v[48:49]
	v_pk_mul_f32 v[56:57], v[38:39], v[42:43]
	ds_write2st64_b32 v213, v36, v37 offset1:18
	v_cvt_pk_f16_f32 v36, v46, v47
	v_cvt_pk_f16_f32 v37, v50, v51
	v_pk_mul_f32 v[48:49], v[0:1], v[48:49]
	ds_write2st64_b32 v213, v36, v37 offset0:36 offset1:54
	v_cvt_pk_f16_f32 v36, v54, v55
	v_cvt_pk_f16_f32 v37, v56, v57
	ds_write2st64_b32 v213, v36, v37 offset0:72 offset1:90
	v_cvt_f16_f32_e32 v36, v48
	v_pk_mul_f32 v[42:43], v[0:1], v[42:43]
	v_cvt_f16_f32_e32 v37, v49
	v_cvt_f16_f32_e32 v42, v42
	v_cvt_f16_f32_e32 v43, v43
	ds_write_b16 v180, v36 offset:28
	s_waitcnt lgkmcnt(14)
	ds_write_b16 v180, v37 offset:68
	s_waitcnt lgkmcnt(14)
	ds_write_b16 v180, v42 offset:5148
	s_waitcnt lgkmcnt(14)
	ds_write_b16 v180, v43 offset:5188
	s_waitcnt lgkmcnt(9)
	ds_write_b16 v180, v58 offset:10268
	ds_read_b32 v2, v2 offset:32768
	v_rcp_f32_e32 v42, v0
	v_rcp_f32_e32 v43, v1
	s_waitcnt lgkmcnt(10)
	v_cvt_f32_f16_e32 v48, v163
	v_cvt_f32_f16_sdwa v49, v163 dst_sel:DWORD dst_unused:UNUSED_PAD src0_sel:WORD_1
	s_waitcnt lgkmcnt(9)
	v_cvt_f32_f16_e32 v54, v243
	v_cvt_f32_f16_sdwa v55, v243 dst_sel:DWORD dst_unused:UNUSED_PAD src0_sel:WORD_1
	v_cvt_f32_f16_e32 v46, v162
	v_cvt_f32_f16_e32 v50, v242
	v_cvt_f32_f16_sdwa v51, v242 dst_sel:DWORD dst_unused:UNUSED_PAD src0_sel:WORD_1
	v_cvt_f32_f16_sdwa v47, v162 dst_sel:DWORD dst_unused:UNUSED_PAD src0_sel:WORD_1
	v_pk_mul_f32 v[36:37], v[52:53], v[48:49]
	v_pk_mul_f32 v[44:45], v[0:1], v[54:55]
	v_pk_mul_f32 v[48:49], v[42:43], v[50:51]
	v_pk_mul_f32 v[42:43], v[42:43], v[46:47]
	v_pk_mul_f32 v[46:47], v[40:41], v[36:37]
	v_pk_mul_f32 v[40:41], v[40:41], v[44:45]
	v_cvt_pk_f16_f32 v36, v36, v37
	v_cvt_pk_f16_f32 v37, v44, v45
	v_pk_mul_f32 v[50:51], v[38:39], v[48:49]
	v_pk_mul_f32 v[38:39], v[38:39], v[42:43]
	ds_write2st64_b32 v215, v36, v37 offset1:18
	v_cvt_pk_f16_f32 v36, v46, v47
	v_cvt_pk_f16_f32 v37, v40, v41
	v_pk_mul_f32 v[48:49], v[0:1], v[48:49]
	ds_write2st64_b32 v215, v36, v37 offset0:36 offset1:54
	v_cvt_pk_f16_f32 v36, v50, v51
	v_cvt_pk_f16_f32 v37, v38, v39
	ds_write2st64_b32 v215, v36, v37 offset0:72 offset1:90
	v_cvt_f16_f32_e32 v36, v48
	v_pk_mul_f32 v[42:43], v[0:1], v[42:43]
	v_cvt_f16_f32_e32 v37, v49
	v_cvt_f16_f32_e32 v38, v42
	v_cvt_f16_f32_e32 v39, v43
	ds_write_b16 v180, v36 offset:30
	ds_write_b16 v180, v37 offset:70
	ds_write_b16 v180, v38 offset:5150
	s_waitcnt lgkmcnt(14)
	ds_write_b16 v180, v39 offset:5190
	s_nop 0
	s_waitcnt lgkmcnt(7)
	ds_write_b16 v180, v2 offset:10270
	v_perm_b32 v36, v61, v60, s35
	v_perm_b32 v37, v2, v58, s35
	ds_write_b64 v180, v[36:37] offset:10304
.LBB0_944:
	s_andn2_saveexec_b64 s[68:69], s[68:69]
	s_cbranch_execz .LBB0_946
	v_lshl_add_u32 v251, v200, 1, v2
	ds_read2st64_b32 v[36:37], v251 offset0:64 offset1:80
	ds_read2st64_b32 v[48:49], v251 offset0:96 offset1:112
	v_lshl_add_u32 v52, v200, 1, v2
	s_nop 0
	s_nop 0
	ds_read_b32 v64, v52 offset:32768
	v_rcp_f32_e32 v44, v58
	v_rcp_f32_e32 v45, v59
	s_nop 0
	s_waitcnt lgkmcnt(1)
	v_cvt_f32_f16_e32 v60, v49
	v_cvt_f32_f16_e32 v54, v37
	v_cvt_f32_f16_sdwa v55, v37 dst_sel:DWORD dst_unused:UNUSED_PAD src0_sel:WORD_1
	v_cvt_f32_f16_sdwa v61, v49 dst_sel:DWORD dst_unused:UNUSED_PAD src0_sel:WORD_1
	v_lshl_add_u32 v251, v202, 1, v2
	ds_read2st64_b32 v[148:149], v251 offset0:64 offset1:80
	v_cvt_f32_f16_e32 v52, v36
	v_cvt_f32_f16_e32 v56, v48
	v_cvt_f32_f16_sdwa v57, v48 dst_sel:DWORD dst_unused:UNUSED_PAD src0_sel:WORD_1
	ds_read2st64_b32 v[162:163], v251 offset0:96 offset1:112
	v_cvt_f32_f16_sdwa v53, v36 dst_sel:DWORD dst_unused:UNUSED_PAD src0_sel:WORD_1
	v_pk_mul_f32 v[36:37], v[38:39], v[54:55]
	v_pk_mul_f32 v[48:49], v[58:59], v[60:61]
	v_pk_mul_f32 v[54:55], v[44:45], v[56:57]
	v_pk_mul_f32 v[44:45], v[44:45], v[52:53]
	v_pk_mul_f32 v[52:53], v[40:41], v[36:37]
	v_pk_mul_f32 v[56:57], v[40:41], v[48:49]
	v_cvt_pk_f16_f32 v36, v36, v37
	v_cvt_pk_f16_f32 v37, v48, v49
	v_pk_mul_f32 v[60:61], v[38:39], v[54:55]
	v_pk_mul_f32 v[62:63], v[38:39], v[44:45]
	ds_write2st64_b32 v201, v36, v37 offset1:18
	v_cvt_pk_f16_f32 v36, v52, v53
	v_cvt_pk_f16_f32 v37, v56, v57
	v_pk_mul_f32 v[54:55], v[0:1], v[54:55]
	ds_write2st64_b32 v201, v36, v37 offset0:36 offset1:54
	v_cvt_pk_f16_f32 v36, v60, v61
	v_cvt_pk_f16_f32 v37, v62, v63
	ds_write2st64_b32 v201, v36, v37 offset0:72 offset1:90
	v_cvt_f16_f32_e32 v36, v54
	v_pk_mul_f32 v[44:45], v[0:1], v[44:45]
	v_cvt_f16_f32_e32 v37, v55
	v_cvt_f16_f32_e32 v44, v44
	v_cvt_f16_f32_e32 v45, v45
	ds_write_b16 v180, v36 offset:16
	ds_write_b16 v180, v37 offset:56
	ds_write_b16 v180, v44 offset:5136
	ds_write_b16 v180, v45 offset:5176
	s_waitcnt lgkmcnt(9)
	ds_write_b16 v180, v64 offset:10256
	v_lshl_add_u32 v52, v202, 1, v2
	s_nop 0
	s_nop 0
	ds_read_b32 v62, v52 offset:32768
	v_rcp_f32_e32 v44, v50
	v_rcp_f32_e32 v45, v51
	s_waitcnt lgkmcnt(10)
	v_cvt_f32_f16_e32 v54, v149
	v_cvt_f32_f16_sdwa v55, v149 dst_sel:DWORD dst_unused:UNUSED_PAD src0_sel:WORD_1
	s_waitcnt lgkmcnt(9)
	v_cvt_f32_f16_e32 v60, v163
	v_cvt_f32_f16_sdwa v61, v163 dst_sel:DWORD dst_unused:UNUSED_PAD src0_sel:WORD_1
	v_cvt_f32_f16_e32 v52, v148
	v_lshl_add_u32 v251, v204, 1, v2
	ds_read2st64_b32 v[164:165], v251 offset0:64 offset1:80
	v_cvt_f32_f16_e32 v56, v162
	v_cvt_f32_f16_sdwa v57, v162 dst_sel:DWORD dst_unused:UNUSED_PAD src0_sel:WORD_1
	v_cvt_f32_f16_sdwa v53, v148 dst_sel:DWORD dst_unused:UNUSED_PAD src0_sel:WORD_1
	ds_read2st64_b32 v[148:149], v251 offset0:96 offset1:112
	v_pk_mul_f32 v[36:37], v[58:59], v[54:55]
	v_pk_mul_f32 v[48:49], v[50:51], v[60:61]
	v_pk_mul_f32 v[54:55], v[44:45], v[56:57]
	v_pk_mul_f32 v[44:45], v[44:45], v[52:53]
	v_pk_mul_f32 v[52:53], v[40:41], v[36:37]
	v_pk_mul_f32 v[56:57], v[40:41], v[48:49]
	v_cvt_pk_f16_f32 v36, v36, v37
	v_cvt_pk_f16_f32 v37, v48, v49
	v_pk_mul_f32 v[58:59], v[38:39], v[54:55]
	v_pk_mul_f32 v[60:61], v[38:39], v[44:45]
	ds_write2st64_b32 v203, v36, v37 offset1:18
	v_cvt_pk_f16_f32 v36, v52, v53
	v_cvt_pk_f16_f32 v37, v56, v57
	v_pk_mul_f32 v[54:55], v[0:1], v[54:55]
	ds_write2st64_b32 v203, v36, v37 offset0:36 offset1:54
	v_cvt_pk_f16_f32 v36, v58, v59
	v_cvt_pk_f16_f32 v37, v60, v61
	ds_write2st64_b32 v203, v36, v37 offset0:72 offset1:90
	v_cvt_f16_f32_e32 v36, v54
	v_pk_mul_f32 v[44:45], v[0:1], v[44:45]
	v_cvt_f16_f32_e32 v37, v55
	v_cvt_f16_f32_e32 v44, v44
	v_cvt_f16_f32_e32 v45, v45
	ds_write_b16 v180, v36 offset:18
	s_waitcnt lgkmcnt(14)
	ds_write_b16 v180, v37 offset:58
	s_waitcnt lgkmcnt(14)
	ds_write_b16 v180, v44 offset:5138
	s_waitcnt lgkmcnt(14)
	ds_write_b16 v180, v45 offset:5178
	s_waitcnt lgkmcnt(9)
	ds_write_b16 v180, v62 offset:10258
	v_lshl_add_u32 v52, v204, 1, v2
	s_nop 0
	s_nop 0
	ds_read_b32 v60, v52 offset:32768
	v_rcp_f32_e32 v44, v46
	v_rcp_f32_e32 v45, v47
	v_lshl_add_u32 v2, v206, 1, v2
	s_nop 0
	s_waitcnt lgkmcnt(10)
	v_cvt_f32_f16_e32 v54, v165
	v_cvt_f32_f16_sdwa v55, v165 dst_sel:DWORD dst_unused:UNUSED_PAD src0_sel:WORD_1
	s_nop 0
	s_waitcnt lgkmcnt(9)
	v_cvt_f32_f16_e32 v58, v149
	ds_read2st64_b32 v[162:163], v2 offset0:64 offset1:80
	v_cvt_f32_f16_sdwa v59, v149 dst_sel:DWORD dst_unused:UNUSED_PAD src0_sel:WORD_1
	v_cvt_f32_f16_e32 v52, v164
	v_cvt_f32_f16_e32 v56, v148
	ds_read2st64_b32 v[242:243], v2 offset0:96 offset1:112
	v_cvt_f32_f16_sdwa v57, v148 dst_sel:DWORD dst_unused:UNUSED_PAD src0_sel:WORD_1
	v_cvt_f32_f16_sdwa v53, v164 dst_sel:DWORD dst_unused:UNUSED_PAD src0_sel:WORD_1
	v_pk_mul_f32 v[36:37], v[50:51], v[54:55]
	v_pk_mul_f32 v[48:49], v[46:47], v[58:59]
	v_pk_mul_f32 v[50:51], v[44:45], v[56:57]
	v_pk_mul_f32 v[44:45], v[44:45], v[52:53]
	v_pk_mul_f32 v[52:53], v[40:41], v[36:37]
	v_pk_mul_f32 v[54:55], v[40:41], v[48:49]
	v_cvt_pk_f16_f32 v36, v36, v37
	v_cvt_pk_f16_f32 v37, v48, v49
	v_pk_mul_f32 v[56:57], v[38:39], v[50:51]
	v_pk_mul_f32 v[58:59], v[38:39], v[44:45]
	ds_write2st64_b32 v205, v36, v37 offset1:18
	v_cvt_pk_f16_f32 v36, v52, v53
	v_cvt_pk_f16_f32 v37, v54, v55
	v_pk_mul_f32 v[50:51], v[0:1], v[50:51]
	ds_write2st64_b32 v205, v36, v37 offset0:36 offset1:54
	v_cvt_pk_f16_f32 v36, v56, v57
	v_cvt_pk_f16_f32 v37, v58, v59
	ds_write2st64_b32 v205, v36, v37 offset0:72 offset1:90
	v_cvt_f16_f32_e32 v36, v50
	v_pk_mul_f32 v[44:45], v[0:1], v[44:45]
	v_cvt_f16_f32_e32 v37, v51
	v_cvt_f16_f32_e32 v44, v44
	v_cvt_f16_f32_e32 v45, v45
	ds_write_b16 v180, v36 offset:20
	s_waitcnt lgkmcnt(14)
	ds_write_b16 v180, v37 offset:60
	s_waitcnt lgkmcnt(14)
	ds_write_b16 v180, v44 offset:5140
	s_waitcnt lgkmcnt(14)
	ds_write_b16 v180, v45 offset:5180
	s_waitcnt lgkmcnt(9)
	ds_write_b16 v180, v60 offset:10260
	ds_read_b32 v2, v2 offset:32768
	v_rcp_f32_e32 v44, v42
	v_rcp_f32_e32 v45, v43
	s_waitcnt lgkmcnt(10)
	v_cvt_f32_f16_e32 v52, v163
	v_cvt_f32_f16_sdwa v53, v163 dst_sel:DWORD dst_unused:UNUSED_PAD src0_sel:WORD_1
	s_waitcnt lgkmcnt(9)
	v_cvt_f32_f16_e32 v56, v243
	v_cvt_f32_f16_sdwa v57, v243 dst_sel:DWORD dst_unused:UNUSED_PAD src0_sel:WORD_1
	v_cvt_f32_f16_e32 v50, v162
	v_cvt_f32_f16_e32 v54, v242
	v_cvt_f32_f16_sdwa v55, v242 dst_sel:DWORD dst_unused:UNUSED_PAD src0_sel:WORD_1
	v_cvt_f32_f16_sdwa v51, v162 dst_sel:DWORD dst_unused:UNUSED_PAD src0_sel:WORD_1
	v_pk_mul_f32 v[36:37], v[46:47], v[52:53]
	v_pk_mul_f32 v[42:43], v[42:43], v[56:57]
	v_pk_mul_f32 v[46:47], v[44:45], v[54:55]
	v_pk_mul_f32 v[44:45], v[44:45], v[50:51]
	v_pk_mul_f32 v[48:49], v[40:41], v[36:37]
	v_pk_mul_f32 v[40:41], v[40:41], v[42:43]
	v_cvt_pk_f16_f32 v36, v36, v37
	v_cvt_pk_f16_f32 v37, v42, v43
	v_pk_mul_f32 v[50:51], v[38:39], v[46:47]
	v_pk_mul_f32 v[38:39], v[38:39], v[44:45]
	ds_write2st64_b32 v207, v36, v37 offset1:18
	v_cvt_pk_f16_f32 v36, v48, v49
	v_cvt_pk_f16_f32 v37, v40, v41
	v_pk_mul_f32 v[46:47], v[0:1], v[46:47]
	ds_write2st64_b32 v207, v36, v37 offset0:36 offset1:54
	v_cvt_pk_f16_f32 v36, v50, v51
	v_cvt_pk_f16_f32 v37, v38, v39
	ds_write2st64_b32 v207, v36, v37 offset0:72 offset1:90
	v_cvt_f16_f32_e32 v36, v46
	v_pk_mul_f32 v[44:45], v[0:1], v[44:45]
	v_cvt_f16_f32_e32 v37, v47
	v_cvt_f16_f32_e32 v38, v44
	v_cvt_f16_f32_e32 v39, v45
	ds_write_b16 v180, v36 offset:22
	ds_write_b16 v180, v37 offset:62
	ds_write_b16 v180, v38 offset:5142
	s_waitcnt lgkmcnt(14)
	ds_write_b16 v180, v39 offset:5182
	s_nop 0
	s_waitcnt lgkmcnt(7)
	ds_write_b16 v180, v2 offset:10262
	v_perm_b32 v36, v62, v64, s35
	v_perm_b32 v37, v2, v60, s35
	ds_write_b64 v180, v[36:37] offset:10296

.LBB0_947:
	v_cmp_eq_u32_e32 vcc, 1, v178
	s_and_saveexec_b64 s[68:69], vcc
	s_cbranch_execz .LBB0_949
	v_lshl_add_u32 v251, v192, 1, v2
	ds_read2st64_b32 v[36:37], v251 offset0:64 offset1:80
	ds_read2st64_b32 v[46:47], v251 offset0:96 offset1:112
	v_lshl_add_u32 v50, v192, 1, v2
	s_nop 0
	s_nop 0
	ds_read_b32 v62, v50 offset:32768
	v_rcp_f32_e32 v42, v54
	v_rcp_f32_e32 v43, v55
	s_nop 0
	s_waitcnt lgkmcnt(1)
	v_cvt_f32_f16_e32 v58, v47
	v_cvt_f32_f16_e32 v52, v37
	v_cvt_f32_f16_sdwa v53, v37 dst_sel:DWORD dst_unused:UNUSED_PAD src0_sel:WORD_1
	v_cvt_f32_f16_sdwa v59, v47 dst_sel:DWORD dst_unused:UNUSED_PAD src0_sel:WORD_1
	v_lshl_add_u32 v251, v194, 1, v2
	ds_read2st64_b32 v[148:149], v251 offset0:64 offset1:80
	v_cvt_f32_f16_e32 v50, v36
	v_cvt_f32_f16_e32 v56, v46
	v_cvt_f32_f16_sdwa v57, v46 dst_sel:DWORD dst_unused:UNUSED_PAD src0_sel:WORD_1
	ds_read2st64_b32 v[162:163], v251 offset0:96 offset1:112
	v_cvt_f32_f16_sdwa v51, v36 dst_sel:DWORD dst_unused:UNUSED_PAD src0_sel:WORD_1
	v_pk_mul_f32 v[36:37], v[60:61], v[52:53]
	v_pk_mul_f32 v[46:47], v[54:55], v[58:59]
	v_pk_mul_f32 v[52:53], v[42:43], v[56:57]
	v_pk_mul_f32 v[42:43], v[42:43], v[50:51]
	v_pk_mul_f32 v[50:51], v[40:41], v[36:37]
	v_pk_mul_f32 v[56:57], v[40:41], v[46:47]
	v_cvt_pk_f16_f32 v36, v36, v37
	v_cvt_pk_f16_f32 v37, v46, v47
	v_pk_mul_f32 v[58:59], v[38:39], v[52:53]
	v_pk_mul_f32 v[60:61], v[38:39], v[42:43]
	ds_write2st64_b32 v193, v36, v37 offset1:18
	v_cvt_pk_f16_f32 v36, v50, v51
	v_cvt_pk_f16_f32 v37, v56, v57
	v_pk_mul_f32 v[52:53], v[0:1], v[52:53]
	ds_write2st64_b32 v193, v36, v37 offset0:36 offset1:54
	v_cvt_pk_f16_f32 v36, v58, v59
	v_cvt_pk_f16_f32 v37, v60, v61
	ds_write2st64_b32 v193, v36, v37 offset0:72 offset1:90
	v_cvt_f16_f32_e32 v36, v52
	v_pk_mul_f32 v[42:43], v[0:1], v[42:43]
	v_cvt_f16_f32_e32 v37, v53
	v_cvt_f16_f32_e32 v42, v42
	v_cvt_f16_f32_e32 v43, v43
	ds_write_b16 v180, v36 offset:8
	ds_write_b16 v180, v37 offset:48
	ds_write_b16 v180, v42 offset:5128
	ds_write_b16 v180, v43 offset:5168
	s_waitcnt lgkmcnt(9)
	ds_write_b16 v180, v62 offset:10248
	v_lshl_add_u32 v50, v194, 1, v2
	s_nop 0
	s_nop 0
	ds_read_b32 v60, v50 offset:32768
	v_rcp_f32_e32 v42, v48
	v_rcp_f32_e32 v43, v49
	s_waitcnt lgkmcnt(10)
	v_cvt_f32_f16_e32 v52, v149
	v_cvt_f32_f16_sdwa v53, v149 dst_sel:DWORD dst_unused:UNUSED_PAD src0_sel:WORD_1
	s_waitcnt lgkmcnt(9)
	v_cvt_f32_f16_e32 v58, v163
	v_cvt_f32_f16_sdwa v59, v163 dst_sel:DWORD dst_unused:UNUSED_PAD src0_sel:WORD_1
	v_cvt_f32_f16_e32 v50, v148
	v_lshl_add_u32 v251, v196, 1, v2
	ds_read2st64_b32 v[164:165], v251 offset0:64 offset1:80
	v_cvt_f32_f16_e32 v56, v162
	v_cvt_f32_f16_sdwa v57, v162 dst_sel:DWORD dst_unused:UNUSED_PAD src0_sel:WORD_1
	v_cvt_f32_f16_sdwa v51, v148 dst_sel:DWORD dst_unused:UNUSED_PAD src0_sel:WORD_1
	ds_read2st64_b32 v[148:149], v251 offset0:96 offset1:112
	v_pk_mul_f32 v[36:37], v[54:55], v[52:53]
	v_pk_mul_f32 v[46:47], v[48:49], v[58:59]
	v_pk_mul_f32 v[52:53], v[42:43], v[56:57]
	v_pk_mul_f32 v[42:43], v[42:43], v[50:51]
	v_pk_mul_f32 v[50:51], v[40:41], v[36:37]
	v_pk_mul_f32 v[54:55], v[40:41], v[46:47]
	v_cvt_pk_f16_f32 v36, v36, v37
	v_cvt_pk_f16_f32 v37, v46, v47
	v_pk_mul_f32 v[56:57], v[38:39], v[52:53]
	v_pk_mul_f32 v[58:59], v[38:39], v[42:43]
	ds_write2st64_b32 v195, v36, v37 offset1:18
	v_cvt_pk_f16_f32 v36, v50, v51
	v_cvt_pk_f16_f32 v37, v54, v55
	v_pk_mul_f32 v[52:53], v[0:1], v[52:53]
	ds_write2st64_b32 v195, v36, v37 offset0:36 offset1:54
	v_cvt_pk_f16_f32 v36, v56, v57
	v_cvt_pk_f16_f32 v37, v58, v59
	ds_write2st64_b32 v195, v36, v37 offset0:72 offset1:90
	v_cvt_f16_f32_e32 v36, v52
	v_pk_mul_f32 v[42:43], v[0:1], v[42:43]
	v_cvt_f16_f32_e32 v37, v53
	v_cvt_f16_f32_e32 v42, v42
	v_cvt_f16_f32_e32 v43, v43
	ds_write_b16 v180, v36 offset:10
	s_waitcnt lgkmcnt(14)
	ds_write_b16 v180, v37 offset:50
	s_waitcnt lgkmcnt(14)
	ds_write_b16 v180, v42 offset:5130
	s_waitcnt lgkmcnt(14)
	ds_write_b16 v180, v43 offset:5170
	s_waitcnt lgkmcnt(9)
	ds_write_b16 v180, v60 offset:10250
	v_lshl_add_u32 v50, v196, 1, v2
	s_nop 0
	s_nop 0
	ds_read_b32 v58, v50 offset:32768
	v_rcp_f32_e32 v42, v44
	v_rcp_f32_e32 v43, v45
	v_lshl_add_u32 v2, v198, 1, v2
	s_nop 0
	s_waitcnt lgkmcnt(10)
	v_cvt_f32_f16_e32 v52, v165
	v_cvt_f32_f16_sdwa v53, v165 dst_sel:DWORD dst_unused:UNUSED_PAD src0_sel:WORD_1
	ds_read2st64_b32 v[162:163], v2 offset0:64 offset1:80
	s_waitcnt lgkmcnt(10)
	v_cvt_f32_f16_e32 v56, v149
	v_cvt_f32_f16_sdwa v57, v149 dst_sel:DWORD dst_unused:UNUSED_PAD src0_sel:WORD_1
	ds_read2st64_b32 v[242:243], v2 offset0:96 offset1:112
	v_cvt_f32_f16_e32 v50, v164
	v_cvt_f32_f16_e32 v54, v148
	v_cvt_f32_f16_sdwa v55, v148 dst_sel:DWORD dst_unused:UNUSED_PAD src0_sel:WORD_1
	v_cvt_f32_f16_sdwa v51, v164 dst_sel:DWORD dst_unused:UNUSED_PAD src0_sel:WORD_1
	v_pk_mul_f32 v[36:37], v[48:49], v[52:53]
	v_pk_mul_f32 v[46:47], v[44:45], v[56:57]
	v_pk_mul_f32 v[48:49], v[42:43], v[54:55]
	v_pk_mul_f32 v[42:43], v[42:43], v[50:51]
	v_pk_mul_f32 v[50:51], v[40:41], v[36:37]
	v_pk_mul_f32 v[52:53], v[40:41], v[46:47]
	v_cvt_pk_f16_f32 v36, v36, v37
	v_cvt_pk_f16_f32 v37, v46, v47
	v_pk_mul_f32 v[54:55], v[38:39], v[48:49]
	v_pk_mul_f32 v[56:57], v[38:39], v[42:43]
	ds_write2st64_b32 v197, v36, v37 offset1:18
	v_cvt_pk_f16_f32 v36, v50, v51
	v_cvt_pk_f16_f32 v37, v52, v53
	v_pk_mul_f32 v[48:49], v[0:1], v[48:49]
	ds_write2st64_b32 v197, v36, v37 offset0:36 offset1:54
	v_cvt_pk_f16_f32 v36, v54, v55
	v_cvt_pk_f16_f32 v37, v56, v57
	ds_write2st64_b32 v197, v36, v37 offset0:72 offset1:90
	v_cvt_f16_f32_e32 v36, v48
	v_pk_mul_f32 v[42:43], v[0:1], v[42:43]
	v_cvt_f16_f32_e32 v37, v49
	v_cvt_f16_f32_e32 v42, v42
	v_cvt_f16_f32_e32 v43, v43
	ds_write_b16 v180, v36 offset:12
	s_waitcnt lgkmcnt(14)
	ds_write_b16 v180, v37 offset:52
	s_waitcnt lgkmcnt(14)
	ds_write_b16 v180, v42 offset:5132
	s_waitcnt lgkmcnt(14)
	ds_write_b16 v180, v43 offset:5172
	s_waitcnt lgkmcnt(9)
	ds_write_b16 v180, v58 offset:10252
	ds_read_b32 v2, v2 offset:32768
	s_waitcnt lgkmcnt(10)
	v_cvt_f32_f16_e32 v48, v163
	v_cvt_f32_f16_sdwa v49, v163 dst_sel:DWORD dst_unused:UNUSED_PAD src0_sel:WORD_1
	s_waitcnt lgkmcnt(9)
	v_cvt_f32_f16_e32 v52, v243
	v_cvt_f32_f16_sdwa v53, v243 dst_sel:DWORD dst_unused:UNUSED_PAD src0_sel:WORD_1
	v_cvt_f32_f16_e32 v46, v162
	v_cvt_f32_f16_e32 v50, v242
	v_cvt_f32_f16_sdwa v51, v242 dst_sel:DWORD dst_unused:UNUSED_PAD src0_sel:WORD_1
	v_cvt_f32_f16_sdwa v47, v162 dst_sel:DWORD dst_unused:UNUSED_PAD src0_sel:WORD_1
	v_pk_mul_f32 v[36:37], v[44:45], v[48:49]
	v_pk_mul_f32 v[42:43], v[38:39], v[52:53]
	v_pk_mul_f32 v[44:45], v[40:41], v[50:51]
	v_pk_mul_f32 v[46:47], v[40:41], v[46:47]
	v_pk_mul_f32 v[48:49], v[40:41], v[36:37]
	v_pk_mul_f32 v[40:41], v[40:41], v[42:43]
	v_cvt_pk_f16_f32 v36, v36, v37
	v_cvt_pk_f16_f32 v37, v42, v43
	v_pk_mul_f32 v[50:51], v[38:39], v[44:45]
	v_pk_mul_f32 v[38:39], v[38:39], v[46:47]
	ds_write2st64_b32 v199, v36, v37 offset1:18
	v_cvt_pk_f16_f32 v36, v48, v49
	v_cvt_pk_f16_f32 v37, v40, v41
	v_pk_mul_f32 v[44:45], v[0:1], v[44:45]
	ds_write2st64_b32 v199, v36, v37 offset0:36 offset1:54
	v_cvt_pk_f16_f32 v36, v50, v51
	v_cvt_pk_f16_f32 v37, v38, v39
	ds_write2st64_b32 v199, v36, v37 offset0:72 offset1:90
	v_cvt_f16_f32_e32 v36, v44
	v_pk_mul_f32 v[46:47], v[0:1], v[46:47]
	v_cvt_f16_f32_e32 v37, v45
	v_cvt_f16_f32_e32 v38, v46
	v_cvt_f16_f32_e32 v39, v47
	ds_write_b16 v180, v36 offset:14
	ds_write_b16 v180, v37 offset:54
	ds_write_b16 v180, v38 offset:5134
	s_waitcnt lgkmcnt(14)
	ds_write_b16 v180, v39 offset:5174
	s_nop 0
	s_waitcnt lgkmcnt(7)
	ds_write_b16 v180, v2 offset:10254
	v_perm_b32 v36, v60, v62, s35
	v_perm_b32 v37, v2, v58, s35
	ds_write_b64 v180, v[36:37] offset:10288

.LBB0_994:
	s_or_b64 exec, exec, s[0:1]
	s_nop 5
	v_cvt_f16_f32_e32 v65, v65
	v_cvt_f16_f32_e32 v64, v64
	s_add_i32 s30, s30, 1
	v_cndmask_b32_e64 v68, 0, v65, s[24:25]
	v_cvt_f16_f32_e32 v65, v66
	v_cvt_f16_f32_e32 v66, v67
	v_cndmask_b32_e64 v64, v64, 0, s[22:23]
	v_pack_b32_f16 v64, v64, v68
	v_cndmask_b32_e64 v65, v65, 0, s[26:27]
	v_cndmask_b32_e64 v66, v66, 0, s[28:29]
	v_pack_b32_f16 v65, v65, v66
	ds_write_b64 v115, v[64:65]
	s_waitcnt lgkmcnt(0)
	s_barrier
	ds_read_b128 v[118:121], v116 offset:55360
	ds_read_b128 v[122:125], v117
	ds_read_b128 v[142:145], v117 offset:64
	ds_read_b128 v[146:149], v117 offset:2304
	ds_read_b128 v[162:165], v117 offset:2368
	ds_read_b128 v[178:181], v117 offset:4608
	ds_read_b128 v[182:185], v117 offset:4672
	ds_read_b128 v[186:189], v117 offset:6912
	ds_read_b128 v[64:67], v116 offset:55296
	ds_read_b128 v[190:193], v117 offset:6976
	s_nop 0
	s_nop 0
	s_nop 0
	v_add_u32_e32 v251, 0x1e500, v87
	s_waitcnt lgkmcnt(1)
	v_mfma_f32_16x16x32_f16 v[52:55], v[64:67], v[122:125], v[52:55]
	ds_read_b128 v[194:197], v251
	s_nop 0
	v_add_u32_e32 v68, 0x1e500, v87
	s_nop 0
	v_mfma_f32_16x16x32_f16 v[52:55], v[118:121], v[142:145], v[52:55]
	s_nop 0
	ds_read_b128 v[142:145], v248 offset:46080
	s_nop 0
	v_mfma_f32_16x16x32_f16 v[56:59], v[64:67], v[146:149], v[56:59]
	s_nop 0
	s_nop 3
	ds_read_b128 v[146:149], v248 offset:46144
	v_cvt_pk_f16_f32 v55, v54, v55
	v_cvt_pk_f16_f32 v54, v52, v53
	s_nop 0
	ds_read_b128 v[198:201], v68 offset:64
	v_mfma_f32_16x16x32_f16 v[56:59], v[118:121], v[162:165], v[56:59]
	v_mfma_f32_16x16x32_f16 v[60:63], v[64:67], v[178:181], v[60:63]
	ds_read_b128 v[162:165], v249 offset:48384
	s_nop 0
	s_nop 0
	v_mfma_f32_16x16x32_f16 v[60:63], v[118:121], v[182:185], v[60:63]
	ds_read_b128 v[178:181], v249 offset:48448
	v_mfma_f32_16x16x32_f16 v[48:51], v[64:67], v[186:189], v[48:51]
	ds_read_b128 v[182:185], v68 offset:128
	s_nop 0
	s_nop 0
	s_waitcnt lgkmcnt(7)
	v_mfma_f32_16x16x32_f16 v[48:51], v[118:121], v[190:193], v[48:51]
	s_nop 0
	ds_read_b128 v[186:189], v248 offset:50688
	s_nop 0
	s_waitcnt lgkmcnt(7)
	v_pk_mul_f32 v[8:9], v[8:9], v[194:195]
	v_pk_mul_f32 v[10:11], v[10:11], v[196:197]
	ds_read_b128 v[190:193], v248 offset:50752
	s_nop 0
	s_nop 2
	v_cvt_pk_f16_f32 v51, v50, v51
	ds_read_b128 v[194:197], v68 offset:192
	s_waitcnt lgkmcnt(8)
	v_mfma_f32_16x16x32_f16 v[8:11], v[142:145], v[64:67], v[8:11]
	s_nop 0
	v_cvt_pk_f16_f32 v50, v48, v49
	s_nop 0
	s_waitcnt lgkmcnt(7)
	v_mfma_f32_16x16x32_f16 v[8:11], v[146:149], v[118:121], v[8:11]
	s_waitcnt lgkmcnt(6)
	v_pk_mul_f32 v[4:5], v[4:5], v[198:199]
	v_pk_mul_f32 v[6:7], v[6:7], v[200:201]
	s_nop 0
	s_nop 0
	s_waitcnt lgkmcnt(5)
	v_mfma_f32_16x16x32_f16 v[4:7], v[162:165], v[64:67], v[4:7]
	s_nop 0
	s_nop 0
	s_waitcnt lgkmcnt(4)
	v_mfma_f32_16x16x32_f16 v[4:7], v[178:181], v[118:121], v[4:7]
	s_waitcnt lgkmcnt(3)
	v_pk_mul_f32 v[16:17], v[16:17], v[182:183]
	v_pk_mul_f32 v[18:19], v[18:19], v[184:185]
	s_nop 0
	s_nop 0
	s_waitcnt lgkmcnt(2)
	v_mfma_f32_16x16x32_f16 v[16:19], v[186:189], v[64:67], v[16:19]
	s_nop 0
	s_nop 0
	s_waitcnt lgkmcnt(1)
	v_mfma_f32_16x16x32_f16 v[16:19], v[190:193], v[118:121], v[16:19]
	s_waitcnt lgkmcnt(0)
	v_pk_mul_f32 v[12:13], v[12:13], v[194:195]
	v_pk_mul_f32 v[14:15], v[14:15], v[196:197]
	ds_read_b128 v[122:125], v249 offset:52992
	s_nop 0
	s_waitcnt lgkmcnt(0)
	v_mfma_f32_16x16x32_f16 v[12:15], v[122:125], v[64:67], v[12:15]
	ds_read_b128 v[64:67], v249 offset:53056
	s_nop 0
	s_waitcnt lgkmcnt(0)
	v_mfma_f32_16x16x32_f16 v[12:15], v[64:67], v[118:121], v[12:15]
	v_add_u32_e32 v65, s96, v104
	v_add_u32_e32 v64, s80, v80
	v_add_u32_e32 v66, 0x7ff, v65
	v_cndmask_b32_e64 v66, v66, v64, s[2:3]
	v_add_u32_e32 v52, v66, v81
	v_mad_i64_i32 v[52:53], s[0:1], v52, s88, v[76:77]
	global_store_dwordx2 v[52:53], v[54:55], off
	v_add_u32_e32 v52, 16, v64
	v_add_u32_e32 v53, 0x7ef, v65
	v_cndmask_b32_e64 v54, v53, v52, s[2:3]
	v_add_u32_e32 v54, v54, v81
	v_cvt_pk_f16_f32 v53, v58, v59
	v_cvt_pk_f16_f32 v52, v56, v57
	v_mad_i64_i32 v[54:55], s[0:1], v54, s88, v[76:77]
	global_store_dwordx2 v[54:55], v[52:53], off
	v_add_u32_e32 v52, 32, v64
	v_add_u32_e32 v53, 0x7df, v65
	v_cndmask_b32_e64 v54, v53, v52, s[2:3]
	v_add_u32_e32 v54, v54, v81
	v_cvt_pk_f16_f32 v53, v62, v63
	v_cvt_pk_f16_f32 v52, v60, v61
	v_mad_i64_i32 v[54:55], s[0:1], v54, s88, v[76:77]
	global_store_dwordx2 v[54:55], v[52:53], off
	v_add_u32_e32 v52, 48, v64
	v_add_u32_e32 v53, 0x7cf, v65
	v_cndmask_b32_e64 v52, v53, v52, s[2:3]
	v_add_u32_e32 v48, v52, v81
	s_sub_i32 s96, s96, 64
	s_add_i32 s80, s80, 64
	v_mad_i64_i32 v[48:49], s[0:1], v48, s88, v[76:77]
	s_cmpk_lg_i32 s96, 0xf800
	global_store_dwordx2 v[48:49], v[50:51], off
	s_cbranch_scc0 .LBB0_1011

.LBB0_1007:
	s_or_b64 exec, exec, s[0:1]
	v_add_u32_e32 v57, s80, v82
	v_add_u32_e32 v56, 0x7ff, v56
	v_cndmask_b32_e64 v56, v56, v57, s[2:3]
	s_waitcnt lgkmcnt(0)
	s_barrier
	ds_read_b128 v[58:61], v83
	ds_read_b128 v[62:65], v88
	ds_read_b128 v[48:51], v83 offset:9216
	s_nop 0
	ds_read_b128 v[66:69], v85
	ds_read_b128 v[52:55], v88 offset:9216
	v_lshrrev_b32_e32 v57, 6, v56
	v_and_b32_e32 v56, 63, v56
	v_cndmask_b32_e64 v56, v56, v57, s[6:7]
	v_lshl_or_b32 v57, v56, 6, v112
	s_nop 0
	v_add_u32_e32 v251, s81, v57
	ds_read_b128 v[122:125], v251
	ds_read_b128 v[118:121], v250 offset:16
	v_add_u32_e32 v75, s81, v57
	s_add_i32 s0, 0, 0x1f600
	v_add_u32_e32 v246, s0, v57
	ds_read_b128 v[126:129], v246
	v_add_u32_e32 v79, s0, v57
	s_waitcnt lgkmcnt(6)
	v_cvt_f32_f16_sdwa v137, v62 dst_sel:DWORD dst_unused:UNUSED_PAD src0_sel:WORD_1
	v_cvt_f32_f16_e32 v136, v62
	v_or_b32_e32 v57, 16, v57
	v_cvt_f32_f16_sdwa v135, v58 dst_sel:DWORD dst_unused:UNUSED_PAD src0_sel:WORD_1
	v_cvt_f32_f16_e32 v134, v58
	s_nop 0
	s_waitcnt lgkmcnt(4)
	v_mul_f32_e32 v56, 0x3fb8aa3b, v66
	v_add_u32_e32 v140, s81, v57
	ds_read_b128 v[130:133], v93
	v_add_u32_e32 v141, s0, v57
	v_mul_f32_e32 v57, 0x3fb8aa3b, v67
	v_exp_f32_e32 v56, v56
	v_exp_f32_e32 v57, v57
	v_pk_mul_f32 v[136:137], v[136:137], s[72:73] op_sel_hi:[1,0]
	v_pk_mul_f32 v[134:135], v[134:135], s[72:73] op_sel_hi:[1,0]
	s_nop 0
	s_waitcnt lgkmcnt(1)
	v_pk_mul_f32 v[136:137], v[136:137], v[126:127]
	v_rcp_f32_e32 v66, v56
	v_cndmask_b32_e64 v137, v137, -v137, s[8:9]
	v_cndmask_b32_e64 v136, v136, -v136, s[8:9]
	v_pk_fma_f32 v[134:135], v[134:135], v[122:123], v[136:137]
	v_cvt_f32_f16_sdwa v137, v48 dst_sel:DWORD dst_unused:UNUSED_PAD src0_sel:WORD_1
	v_pk_mul_f32 v[138:139], v[134:135], v[56:57]
	v_cvt_f32_f16_sdwa v135, v52 dst_sel:DWORD dst_unused:UNUSED_PAD src0_sel:WORD_1
	v_cvt_f32_f16_e32 v134, v52
	v_cvt_f32_f16_e32 v136, v48
	s_nop 0
	v_rcp_f32_e32 v67, v57
	v_pk_mul_f32 v[126:127], v[126:127], v[134:135]
	v_add3_u32 v52, v72, v89, v247
	v_cndmask_b32_e64 v127, v127, -v127, s[8:9]
	v_cndmask_b32_e64 v126, v126, -v126, s[8:9]
	v_pk_fma_f32 v[122:123], v[122:123], v[136:137], v[126:127]
	ds_read_b128 v[134:137], v94
	v_pk_mul_f32 v[126:127], v[122:123], v[66:67]
	v_cvt_f32_f16_e32 v58, v63
	s_nop 0
	s_waitcnt lgkmcnt(1)
	v_fma_mixlo_f16 v48, v130, v126, 0
	ds_write_b16 v52, v48 offset:46080
	v_fma_mixlo_f16 v48, v131, v127, 0
	ds_write_b16 v113, v48 offset:46080
	v_mul_f32_e32 v48, 0x3fb8aa3b, v68
	v_exp_f32_e32 v66, v48
	v_mul_f32_e32 v48, 0x3fb8aa3b, v69
	v_cvt_f32_f16_sdwa v69, v59 dst_sel:DWORD dst_unused:UNUSED_PAD src0_sel:WORD_1
	v_cvt_f32_f16_e32 v68, v59
	v_cvt_f32_f16_sdwa v59, v63 dst_sel:DWORD dst_unused:UNUSED_PAD src0_sel:WORD_1
	v_exp_f32_e32 v67, v48
	v_cvt_f32_f16_e32 v52, v49
	v_pk_mul_f32 v[68:69], v[68:69], s[72:73] op_sel_hi:[1,0]
	v_pk_mul_f32 v[58:59], v[58:59], s[72:73] op_sel_hi:[1,0]
	v_rcp_f32_e32 v62, v66
	v_pk_mul_f32 v[58:59], v[58:59], v[128:129]
	v_rcp_f32_e32 v63, v67
	v_cndmask_b32_e64 v59, v59, -v59, s[8:9]
	v_cndmask_b32_e64 v58, v58, -v58, s[8:9]
	v_pk_fma_f32 v[58:59], v[68:69], v[124:125], v[58:59]
	v_cvt_pk_f16_f32 v56, v138, v139
	v_pk_mul_f32 v[130:131], v[58:59], v[66:67]
	v_cvt_f32_f16_sdwa v59, v53 dst_sel:DWORD dst_unused:UNUSED_PAD src0_sel:WORD_1
	v_cvt_f32_f16_e32 v58, v53
	v_cvt_f32_f16_sdwa v53, v49 dst_sel:DWORD dst_unused:UNUSED_PAD src0_sel:WORD_1
	v_cvt_pk_f16_f32 v57, v130, v131
	v_pk_mul_f32 v[48:49], v[128:129], v[58:59]
	s_nop 0
	v_cndmask_b32_e64 v49, v49, -v49, s[8:9]
	v_cndmask_b32_e64 v48, v48, -v48, s[8:9]
	v_pk_fma_f32 v[48:49], v[124:125], v[52:53], v[48:49]
	v_cvt_f32_f16_sdwa v59, v60 dst_sel:DWORD dst_unused:UNUSED_PAD src0_sel:WORD_1
	v_pk_mul_f32 v[48:49], v[48:49], v[62:63]
	v_cvt_f32_f16_sdwa v63, v64 dst_sel:DWORD dst_unused:UNUSED_PAD src0_sel:WORD_1
	v_fma_mixlo_f16 v52, v132, v48, 0
	ds_write_b16 v113, v52 offset:46224
	v_fma_mixlo_f16 v52, v133, v49, 0
	ds_write_b16 v113, v52 offset:46368
	ds_read_b128 v[122:125], v141
	ds_read_b128 v[66:69], v140
	v_cvt_f32_f16_e32 v62, v64
	v_cvt_f32_f16_e32 v58, v60
	v_mul_f32_e32 v52, 0x3fb8aa3b, v118
	v_mul_f32_e32 v53, 0x3fb8aa3b, v119
	v_pk_mul_f32 v[62:63], v[62:63], s[72:73] op_sel_hi:[1,0]
	v_exp_f32_e32 v52, v52
	s_nop 0
	s_waitcnt lgkmcnt(1)
	v_pk_mul_f32 v[62:63], v[62:63], v[122:123]
	v_exp_f32_e32 v53, v53
	v_pk_mul_f32 v[58:59], v[58:59], s[72:73] op_sel_hi:[1,0]
	v_cndmask_b32_e64 v63, v63, -v63, s[8:9]
	v_cndmask_b32_e64 v62, v62, -v62, s[8:9]
	s_waitcnt lgkmcnt(0)
	v_pk_fma_f32 v[58:59], v[58:59], v[66:67], v[62:63]
	v_cvt_f32_f16_sdwa v63, v54 dst_sel:DWORD dst_unused:UNUSED_PAD src0_sel:WORD_1
	v_cvt_f32_f16_e32 v62, v54
	v_cvt_f32_f16_sdwa v129, v50 dst_sel:DWORD dst_unused:UNUSED_PAD src0_sel:WORD_1
	v_cvt_f32_f16_e32 v128, v50
	v_rcp_f32_e32 v118, v52
	v_rcp_f32_e32 v119, v53
	v_pk_mul_f32 v[62:63], v[122:123], v[62:63]
	v_cvt_f32_f16_e32 v60, v65
	v_cndmask_b32_e64 v63, v63, -v63, s[8:9]
	v_cndmask_b32_e64 v62, v62, -v62, s[8:9]
	v_pk_fma_f32 v[62:63], v[66:67], v[128:129], v[62:63]
	v_pk_mul_f32 v[52:53], v[58:59], v[52:53]
	v_pk_mul_f32 v[66:67], v[62:63], v[118:119]
	v_cvt_f32_f16_sdwa v119, v61 dst_sel:DWORD dst_unused:UNUSED_PAD src0_sel:WORD_1
	v_fma_mixlo_f16 v50, v134, v66, 0
	v_cvt_f32_f16_e32 v118, v61
	v_cvt_f32_f16_sdwa v61, v65 dst_sel:DWORD dst_unused:UNUSED_PAD src0_sel:WORD_1
	ds_write_b16 v113, v50 offset:46512
	v_fma_mixlo_f16 v50, v135, v67, 0
	ds_write_b16 v113, v50 offset:46656
	v_mul_f32_e32 v50, 0x3fb8aa3b, v120
	v_exp_f32_e32 v62, v50
	v_mul_f32_e32 v50, 0x3fb8aa3b, v121
	v_exp_f32_e32 v63, v50
	v_pk_mul_f32 v[60:61], v[60:61], s[72:73] op_sel_hi:[1,0]
	v_pk_mul_f32 v[118:119], v[118:119], s[72:73] op_sel_hi:[1,0]
	v_pk_mul_f32 v[60:61], v[60:61], v[124:125]
	v_rcp_f32_e32 v64, v62
	v_cndmask_b32_e64 v61, v61, -v61, s[8:9]
	v_cndmask_b32_e64 v60, v60, -v60, s[8:9]
	v_pk_fma_f32 v[60:61], v[118:119], v[68:69], v[60:61]
	v_rcp_f32_e32 v65, v63
	v_pk_mul_f32 v[60:61], v[60:61], v[62:63]
	v_bfe_u32 v62, v131, 16, 1
	v_bfe_u32 v63, v130, 16, 1
	v_bfe_u32 v75, v53, 16, 1
	v_bfe_u32 v79, v52, 16, 1
	v_cvt_pk_f16_f32 v58, v52, v53
	v_bfe_u32 v50, v61, 16, 1
	v_add3_u32 v120, v130, v63, s34
	v_add3_u32 v62, v131, v62, s34
	v_add3_u32 v52, v52, v79, s34
	v_add3_u32 v53, v53, v75, s34
	v_cvt_pk_f16_f32 v59, v60, v61
	v_bfe_u32 v54, v60, 16, 1
	v_add3_u32 v50, v61, v50, s34
	v_perm_b32 v61, v62, v120, s35
	v_perm_b32 v62, v53, v52, s35
	v_cvt_f32_f16_sdwa v53, v55 dst_sel:DWORD dst_unused:UNUSED_PAD src0_sel:WORD_1
	v_cvt_f32_f16_e32 v52, v55
	v_add3_u32 v54, v60, v54, s34
	v_perm_b32 v63, v50, v54, s35
	v_cvt_f32_f16_sdwa v55, v51 dst_sel:DWORD dst_unused:UNUSED_PAD src0_sel:WORD_1
	v_cvt_f32_f16_e32 v54, v51
	v_pk_mul_f32 v[50:51], v[124:125], v[52:53]
	v_bfe_u32 v118, v139, 16, 1
	v_cndmask_b32_e64 v51, v51, -v51, s[8:9]
	v_cndmask_b32_e64 v50, v50, -v50, s[8:9]
	v_pk_fma_f32 v[50:51], v[68:69], v[54:55], v[50:51]
	v_bfe_u32 v119, v138, 16, 1
	v_pk_mul_f32 v[52:53], v[50:51], v[64:65]
	v_bfe_u32 v51, v48, 16, 1
	v_fma_mixlo_f16 v50, v136, v52, 0
	v_bfe_u32 v54, v53, 16, 1
	v_bfe_u32 v55, v52, 16, 1
	ds_write_b16 v113, v50 offset:46800
	v_bfe_u32 v50, v49, 16, 1
	v_bfe_u32 v64, v67, 16, 1
	v_bfe_u32 v65, v66, 16, 1
	v_bfe_u32 v68, v127, 16, 1
	v_bfe_u32 v69, v126, 16, 1
	v_add3_u32 v52, v52, v55, s34
	v_add3_u32 v54, v53, v54, s34
	v_add3_u32 v60, v138, v119, s34
	v_add3_u32 v118, v139, v118, s34
	v_add3_u32 v48, v48, v51, s34
	v_add3_u32 v49, v49, v50, s34
	v_add3_u32 v55, v126, v69, s34
	v_add3_u32 v68, v127, v68, s34
	v_add3_u32 v50, v66, v65, s34
	v_add3_u32 v64, v67, v64, s34
	v_perm_b32 v51, v54, v52, s35
	v_fma_mixlo_f16 v52, v137, v53, 0
	v_perm_b32 v60, v118, v60, s35
	v_perm_b32 v49, v49, v48, s35
	v_perm_b32 v50, v64, v50, s35
	v_perm_b32 v48, v68, v55, s35
	ds_write_b16 v113, v52 offset:46944
	ds_write_b128 v83, v[60:63] offset:18432
	ds_write_b128 v83, v[48:51] offset:27648
	ds_write_b128 v83, v[56:59] offset:36864
	v_add_u32_e32 v56, v73, v0
	s_nop 0
	s_barrier
	v_add_u32_e32 v251, v86, v95
	ds_read_b128 v[52:55], v251 offset:36864
	ds_read_b128 v[64:67], v56 offset:64
	ds_read_b128 v[142:145], v251 offset:36928
	ds_read_b128 v[60:63], v251 offset:39168
	ds_read_b128 v[118:121], v251 offset:39232
	ds_read_b128 v[122:125], v251 offset:41472
	ds_read_b128 v[126:129], v251 offset:41536
	ds_read_b128 v[130:133], v251 offset:43776
	ds_read_b128 v[134:137], v251 offset:43840
	ds_read_b128 v[48:51], v56
	v_add_u32_e32 v68, v86, v95
	s_waitcnt lgkmcnt(0)
	v_mfma_f32_16x16x32_f16 v[52:55], v[48:51], v[52:55], 0
	v_add_u32_e32 v75, v92, v0
	v_mov_b32_e32 v68, 0
	v_mov_b32_e32 v69, 0
	s_nop 0
	v_mfma_f32_16x16x32_f16 v[60:63], v[48:51], v[60:63], 0
	s_nop 0
	v_mfma_f32_16x16x32_f16 v[122:125], v[48:51], v[122:125], 0
	s_nop 0
	v_mfma_f32_16x16x32_f16 v[48:51], v[48:51], v[130:133], 0
	v_mfma_f32_16x16x32_f16 v[52:55], v[64:67], v[142:145], v[52:55]
	v_mfma_f32_16x16x32_f16 v[56:59], v[64:67], v[118:121], v[60:63]
	v_mfma_f32_16x16x32_f16 v[60:63], v[64:67], v[126:129], v[122:125]
	s_nop 0
	v_mfma_f32_16x16x32_f16 v[48:51], v[64:67], v[134:137], v[48:51]
	v_mov_b32_e32 v64, 0
	v_mov_b32_e32 v66, 0
	v_mov_b32_e32 v67, 0
	s_and_saveexec_b64 s[0:1], s[10:11]
	s_cbranch_execz .LBB0_1009
	v_add_u32_e32 v251, v86, v98
	ds_read_b128 v[66:69], v75 offset:18432
	ds_read_b128 v[118:121], v251 offset:27648
	v_add_u32_e32 v65, v86, v98
	s_nop 0
	s_nop 0
	s_nop 0
	s_waitcnt lgkmcnt(0)
	v_mfma_f32_16x16x32_bf16 v[66:69], v[118:121], v[66:69], 0
	ds_read_b128 v[122:125], v65 offset:27712
	ds_read_b128 v[118:121], v75 offset:18496
	s_nop 0
	s_nop 0
	s_waitcnt lgkmcnt(0)
	v_mfma_f32_16x16x32_bf16 v[66:69], v[122:125], v[118:121], v[66:69]

.LBB0_1028:
	s_andn2_b64 vcc, exec, s[24:25]
	s_mov_b64 s[26:27], -1
	s_cbranch_vccnz .LBB0_1036
	s_and_b32 s26, s76, 1
	v_lshl_add_u32 v0, s26, 13, v229
	ds_read2_b64 v[36:39], v0 offset1:32
	v_mad_u32_u24 v2, s26, v167, v230
	s_waitcnt lgkmcnt(0)
	v_pk_mul_f32 v[66:67], v[36:37], v[38:39]
	ds_read2_b64 v[38:41], v0 offset0:64 offset1:96
	s_waitcnt lgkmcnt(0)
	v_pk_mul_f32 v[64:65], v[66:67], v[38:39]
	s_nop 0
	v_pk_mul_f32 v[60:61], v[64:65], v[40:41]
	ds_read2_b64 v[38:41], v0 offset0:128 offset1:160
	s_waitcnt lgkmcnt(0)
	v_pk_mul_f32 v[54:55], v[60:61], v[38:39]
	s_nop 0
	v_pk_mul_f32 v[48:49], v[54:55], v[40:41]
	ds_read2_b64 v[38:41], v0 offset0:192 offset1:224
	v_add_u32_e32 v0, 0x800, v0
	ds_read2_b64 v[68:71], v0 offset0:128 offset1:160
	s_waitcnt lgkmcnt(1)
	v_pk_mul_f32 v[44:45], v[48:49], v[38:39]
	s_nop 0
	v_pk_mul_f32 v[38:39], v[44:45], v[40:41]
	ds_read2_b64 v[40:43], v0 offset1:32
	s_waitcnt lgkmcnt(0)
	v_pk_mul_f32 v[58:59], v[38:39], v[40:41]
	s_nop 0
	v_pk_mul_f32 v[50:51], v[58:59], v[42:43]
	ds_read2_b64 v[40:43], v0 offset0:64 offset1:96
	s_waitcnt lgkmcnt(0)
	v_pk_mul_f32 v[46:47], v[50:51], v[40:41]
	s_nop 0
	v_pk_mul_f32 v[42:43], v[46:47], v[42:43]
	v_rcp_f32_e32 v40, v38
	v_pk_mul_f32 v[62:63], v[42:43], v[68:69]
	v_rcp_f32_e32 v41, v39
	v_pk_mul_f32 v[56:57], v[62:63], v[70:71]
	ds_read2_b64 v[68:71], v0 offset0:192 offset1:224
	s_waitcnt lgkmcnt(0)
	v_pk_mul_f32 v[52:53], v[56:57], v[68:69]
	s_nop 0
	v_pk_mul_f32 v[0:1], v[52:53], v[70:71]
	s_and_saveexec_b64 s[26:27], s[4:5]
	s_cbranch_execz .LBB0_1031
	v_lshl_add_u32 v251, v175, 1, v2
	ds_read2st64_b32 v[72:73], v251 offset0:96 offset1:112
	ds_read2st64_b32 v[68:69], v251 offset0:64 offset1:80
	v_lshl_add_u32 v74, v175, 1, v2
	s_nop 0
	ds_read_b32 v84, v74 offset:32768
	s_nop 0
	v_rcp_f32_e32 v70, v36
	v_rcp_f32_e32 v71, v37
	s_nop 0
	s_nop 0
	s_waitcnt lgkmcnt(2)
	v_cvt_f32_f16_e32 v78, v73
	v_cvt_f32_f16_sdwa v79, v73 dst_sel:DWORD dst_unused:UNUSED_PAD src0_sel:WORD_1
	v_lshl_add_u32 v251, v182, 1, v2
	ds_read2st64_b32 v[146:147], v251 offset0:64 offset1:80
	s_waitcnt lgkmcnt(2)
	v_cvt_f32_f16_e32 v74, v68
	v_cvt_f32_f16_sdwa v75, v68 dst_sel:DWORD dst_unused:UNUSED_PAD src0_sel:WORD_1
	v_cvt_f32_f16_e32 v76, v72
	ds_read2st64_b32 v[148:149], v251 offset0:96 offset1:112
	v_cvt_f32_f16_sdwa v77, v72 dst_sel:DWORD dst_unused:UNUSED_PAD src0_sel:WORD_1
	v_cvt_f32_f16_e32 v72, v69
	v_cvt_f32_f16_sdwa v73, v69 dst_sel:DWORD dst_unused:UNUSED_PAD src0_sel:WORD_1
	v_pk_mul_f32 v[78:79], v[36:37], v[78:79]
	v_pk_mul_f32 v[76:77], v[70:71], v[76:77]
	v_pk_mul_f32 v[70:71], v[70:71], v[74:75]
	v_pk_mul_f32 v[72:73], v[40:41], v[72:73]
	v_pk_mul_f32 v[74:75], v[40:41], v[78:79]
	v_cvt_pk_f16_f32 v68, v78, v79
	v_pk_mul_f32 v[80:81], v[38:39], v[76:77]
	v_pk_mul_f32 v[82:83], v[38:39], v[70:71]
	ds_write2st64_b32 v181, v69, v68 offset1:18
	v_cvt_pk_f16_f32 v68, v72, v73
	v_cvt_pk_f16_f32 v69, v74, v75
	v_pk_mul_f32 v[76:77], v[0:1], v[76:77]
	ds_write2st64_b32 v181, v68, v69 offset0:36 offset1:54
	v_cvt_pk_f16_f32 v68, v80, v81
	v_cvt_pk_f16_f32 v69, v82, v83
	ds_write2st64_b32 v181, v68, v69 offset0:72 offset1:90
	v_cvt_f16_f32_e32 v68, v76
	v_pk_mul_f32 v[70:71], v[0:1], v[70:71]
	v_cvt_f16_f32_e32 v69, v77
	v_cvt_f16_f32_e32 v70, v70
	v_cvt_f16_f32_e32 v71, v71
	ds_write_b16 v176, v68
	ds_write_b16 v176, v69 offset:40
	ds_write_b16 v176, v70 offset:5120
	ds_write_b16 v176, v71 offset:5160
	s_waitcnt lgkmcnt(9)
	ds_write_b16 v176, v84 offset:10240
	v_lshl_add_u32 v74, v182, 1, v2
	s_nop 0
	s_nop 0
	ds_read_b32 v82, v74 offset:32768
	v_rcp_f32_e32 v70, v66
	v_rcp_f32_e32 v71, v67
	s_waitcnt lgkmcnt(10)
	v_cvt_f32_f16_e32 v76, v147
	v_cvt_f32_f16_sdwa v77, v147 dst_sel:DWORD dst_unused:UNUSED_PAD src0_sel:WORD_1
	s_waitcnt lgkmcnt(9)
	v_cvt_f32_f16_e32 v80, v149
	v_cvt_f32_f16_sdwa v81, v149 dst_sel:DWORD dst_unused:UNUSED_PAD src0_sel:WORD_1
	v_lshl_add_u32 v251, v184, 1, v2
	ds_read2st64_b32 v[162:163], v251 offset0:64 offset1:80
	v_cvt_f32_f16_e32 v74, v146
	v_cvt_f32_f16_e32 v78, v148
	v_cvt_f32_f16_sdwa v79, v148 dst_sel:DWORD dst_unused:UNUSED_PAD src0_sel:WORD_1
	ds_read2st64_b32 v[148:149], v251 offset0:96 offset1:112
	v_cvt_f32_f16_sdwa v75, v146 dst_sel:DWORD dst_unused:UNUSED_PAD src0_sel:WORD_1
	v_pk_mul_f32 v[36:37], v[36:37], v[76:77]
	v_pk_mul_f32 v[68:69], v[66:67], v[80:81]
	v_pk_mul_f32 v[72:73], v[70:71], v[78:79]
	v_pk_mul_f32 v[70:71], v[70:71], v[74:75]
	v_pk_mul_f32 v[74:75], v[40:41], v[36:37]
	v_pk_mul_f32 v[76:77], v[40:41], v[68:69]
	v_cvt_pk_f16_f32 v36, v36, v37
	v_cvt_pk_f16_f32 v37, v68, v69
	v_pk_mul_f32 v[78:79], v[38:39], v[72:73]
	v_pk_mul_f32 v[80:81], v[38:39], v[70:71]
	ds_write2st64_b32 v183, v36, v37 offset1:18
	v_cvt_pk_f16_f32 v36, v74, v75
	v_cvt_pk_f16_f32 v37, v76, v77
	v_pk_mul_f32 v[72:73], v[0:1], v[72:73]
	ds_write2st64_b32 v183, v36, v37 offset0:36 offset1:54
	v_cvt_pk_f16_f32 v36, v78, v79
	v_cvt_pk_f16_f32 v37, v80, v81
	ds_write2st64_b32 v183, v36, v37 offset0:72 offset1:90
	v_cvt_f16_f32_e32 v36, v72
	v_pk_mul_f32 v[70:71], v[0:1], v[70:71]
	v_cvt_f16_f32_e32 v37, v73
	v_cvt_f16_f32_e32 v68, v70
	v_cvt_f16_f32_e32 v69, v71
	ds_write_b16 v176, v36 offset:2
	s_waitcnt lgkmcnt(14)
	ds_write_b16 v176, v37 offset:42
	s_waitcnt lgkmcnt(14)
	ds_write_b16 v176, v68 offset:5122
	s_waitcnt lgkmcnt(14)
	ds_write_b16 v176, v69 offset:5162
	s_waitcnt lgkmcnt(9)
	ds_write_b16 v176, v82 offset:10242
	v_lshl_add_u32 v72, v184, 1, v2
	s_nop 0
	s_nop 0
	ds_read_b32 v80, v72 offset:32768
	v_rcp_f32_e32 v68, v64
	v_rcp_f32_e32 v69, v65
	s_waitcnt lgkmcnt(10)
	v_cvt_f32_f16_e32 v74, v163
	v_cvt_f32_f16_sdwa v75, v163 dst_sel:DWORD dst_unused:UNUSED_PAD src0_sel:WORD_1
	s_waitcnt lgkmcnt(9)
	v_cvt_f32_f16_e32 v78, v149
	v_cvt_f32_f16_sdwa v79, v149 dst_sel:DWORD dst_unused:UNUSED_PAD src0_sel:WORD_1
	v_lshl_add_u32 v251, v186, 1, v2
	ds_read2st64_b32 v[146:147], v251 offset0:64 offset1:80
	v_cvt_f32_f16_e32 v72, v162
	v_cvt_f32_f16_e32 v76, v148
	v_cvt_f32_f16_sdwa v77, v148 dst_sel:DWORD dst_unused:UNUSED_PAD src0_sel:WORD_1
	ds_read2st64_b32 v[148:149], v251 offset0:96 offset1:112
	v_cvt_f32_f16_sdwa v73, v162 dst_sel:DWORD dst_unused:UNUSED_PAD src0_sel:WORD_1
	v_pk_mul_f32 v[36:37], v[66:67], v[74:75]
	v_pk_mul_f32 v[66:67], v[64:65], v[78:79]
	v_pk_mul_f32 v[70:71], v[68:69], v[76:77]
	v_pk_mul_f32 v[68:69], v[68:69], v[72:73]
	v_pk_mul_f32 v[72:73], v[40:41], v[36:37]
	v_pk_mul_f32 v[74:75], v[40:41], v[66:67]
	v_cvt_pk_f16_f32 v36, v36, v37
	v_cvt_pk_f16_f32 v37, v66, v67
	v_pk_mul_f32 v[76:77], v[38:39], v[70:71]
	v_pk_mul_f32 v[78:79], v[38:39], v[68:69]
	ds_write2st64_b32 v185, v36, v37 offset1:18
	v_cvt_pk_f16_f32 v36, v72, v73
	v_cvt_pk_f16_f32 v37, v74, v75
	v_pk_mul_f32 v[70:71], v[0:1], v[70:71]
	ds_write2st64_b32 v185, v36, v37 offset0:36 offset1:54
	v_cvt_pk_f16_f32 v36, v76, v77
	v_cvt_pk_f16_f32 v37, v78, v79
	ds_write2st64_b32 v185, v36, v37 offset0:72 offset1:90
	v_cvt_f16_f32_e32 v36, v70
	v_pk_mul_f32 v[68:69], v[0:1], v[68:69]
	v_cvt_f16_f32_e32 v37, v71
	v_cvt_f16_f32_e32 v66, v68
	v_cvt_f16_f32_e32 v67, v69
	ds_write_b16 v176, v36 offset:4
	s_waitcnt lgkmcnt(14)
	ds_write_b16 v176, v37 offset:44
	s_waitcnt lgkmcnt(14)
	ds_write_b16 v176, v66 offset:5124
	s_waitcnt lgkmcnt(14)
	ds_write_b16 v176, v67 offset:5164
	s_waitcnt lgkmcnt(9)
	ds_write_b16 v176, v80 offset:10244
	v_lshl_add_u32 v70, v186, 1, v2
	s_nop 0
	s_nop 0
	ds_read_b32 v78, v70 offset:32768
	v_rcp_f32_e32 v66, v60
	v_rcp_f32_e32 v67, v61
	s_waitcnt lgkmcnt(10)
	v_cvt_f32_f16_e32 v72, v147
	v_cvt_f32_f16_sdwa v73, v147 dst_sel:DWORD dst_unused:UNUSED_PAD src0_sel:WORD_1
	s_waitcnt lgkmcnt(9)
	v_cvt_f32_f16_e32 v76, v149
	v_cvt_f32_f16_sdwa v77, v149 dst_sel:DWORD dst_unused:UNUSED_PAD src0_sel:WORD_1
	v_cvt_f32_f16_e32 v70, v146
	v_cvt_f32_f16_e32 v74, v148
	v_cvt_f32_f16_sdwa v75, v148 dst_sel:DWORD dst_unused:UNUSED_PAD src0_sel:WORD_1
	v_cvt_f32_f16_sdwa v71, v146 dst_sel:DWORD dst_unused:UNUSED_PAD src0_sel:WORD_1
	v_pk_mul_f32 v[36:37], v[64:65], v[72:73]
	v_pk_mul_f32 v[64:65], v[60:61], v[76:77]
	v_pk_mul_f32 v[68:69], v[66:67], v[74:75]
	v_pk_mul_f32 v[66:67], v[66:67], v[70:71]
	v_pk_mul_f32 v[70:71], v[40:41], v[36:37]
	v_pk_mul_f32 v[72:73], v[40:41], v[64:65]
	v_cvt_pk_f16_f32 v36, v36, v37
	v_cvt_pk_f16_f32 v37, v64, v65
	v_pk_mul_f32 v[74:75], v[38:39], v[68:69]
	v_pk_mul_f32 v[76:77], v[38:39], v[66:67]
	ds_write2st64_b32 v187, v36, v37 offset1:18
	v_cvt_pk_f16_f32 v36, v70, v71
	v_cvt_pk_f16_f32 v37, v72, v73
	v_pk_mul_f32 v[68:69], v[0:1], v[68:69]
	ds_write2st64_b32 v187, v36, v37 offset0:36 offset1:54
	v_cvt_pk_f16_f32 v36, v74, v75
	v_cvt_pk_f16_f32 v37, v76, v77
	ds_write2st64_b32 v187, v36, v37 offset0:72 offset1:90
	v_cvt_f16_f32_e32 v36, v68
	v_pk_mul_f32 v[66:67], v[0:1], v[66:67]
	v_cvt_f16_f32_e32 v37, v69
	v_cvt_f16_f32_e32 v64, v66
	v_cvt_f16_f32_e32 v65, v67
	ds_write_b16 v176, v36 offset:6
	ds_write_b16 v176, v37 offset:46
	ds_write_b16 v176, v64 offset:5126
	s_waitcnt lgkmcnt(14)
	ds_write_b16 v176, v65 offset:5166
	s_nop 0
	s_waitcnt lgkmcnt(7)
	ds_write_b16 v176, v78 offset:10246
	v_perm_b32 v36, v82, v84, s35
	v_perm_b32 v37, v78, v80, s35
	ds_write_b64 v176, v[36:37] offset:10280

.LBB0_1041:
	v_cmp_lt_i32_e32 vcc, 2, v174
	s_and_saveexec_b64 s[28:29], vcc
	s_xor_b64 s[28:29], exec, s[28:29]
	s_cbranch_execz .LBB0_1043
	v_lshl_add_u32 v251, v204, 1, v2
	ds_read2st64_b32 v[36:37], v251 offset0:64 offset1:80
	ds_read2st64_b32 v[46:47], v251 offset0:96 offset1:112
	v_lshl_add_u32 v48, v204, 1, v2
	s_nop 0
	s_nop 0
	ds_read_b32 v60, v48 offset:32768
	v_rcp_f32_e32 v44, v62
	v_rcp_f32_e32 v45, v63
	s_nop 0
	s_waitcnt lgkmcnt(1)
	v_cvt_f32_f16_e32 v58, v47
	v_cvt_f32_f16_e32 v50, v37
	v_cvt_f32_f16_sdwa v51, v37 dst_sel:DWORD dst_unused:UNUSED_PAD src0_sel:WORD_1
	v_cvt_f32_f16_sdwa v59, v47 dst_sel:DWORD dst_unused:UNUSED_PAD src0_sel:WORD_1
	v_lshl_add_u32 v251, v206, 1, v2
	ds_read2st64_b32 v[146:147], v251 offset0:64 offset1:80
	v_cvt_f32_f16_e32 v48, v36
	v_cvt_f32_f16_e32 v54, v46
	v_cvt_f32_f16_sdwa v55, v46 dst_sel:DWORD dst_unused:UNUSED_PAD src0_sel:WORD_1
	ds_read2st64_b32 v[148:149], v251 offset0:96 offset1:112
	v_cvt_f32_f16_sdwa v49, v36 dst_sel:DWORD dst_unused:UNUSED_PAD src0_sel:WORD_1
	v_pk_mul_f32 v[36:37], v[42:43], v[50:51]
	v_pk_mul_f32 v[42:43], v[62:63], v[58:59]
	v_pk_mul_f32 v[46:47], v[44:45], v[54:55]
	v_pk_mul_f32 v[44:45], v[44:45], v[48:49]
	v_pk_mul_f32 v[48:49], v[40:41], v[36:37]
	v_pk_mul_f32 v[50:51], v[40:41], v[42:43]
	v_cvt_pk_f16_f32 v36, v36, v37
	v_cvt_pk_f16_f32 v37, v42, v43
	v_pk_mul_f32 v[54:55], v[38:39], v[46:47]
	v_pk_mul_f32 v[58:59], v[38:39], v[44:45]
	ds_write2st64_b32 v205, v36, v37 offset1:18
	v_cvt_pk_f16_f32 v36, v48, v49
	v_cvt_pk_f16_f32 v37, v50, v51
	v_pk_mul_f32 v[46:47], v[0:1], v[46:47]
	ds_write2st64_b32 v205, v36, v37 offset0:36 offset1:54
	v_cvt_pk_f16_f32 v36, v54, v55
	v_cvt_pk_f16_f32 v37, v58, v59
	ds_write2st64_b32 v205, v36, v37 offset0:72 offset1:90
	v_cvt_f16_f32_e32 v36, v46
	v_pk_mul_f32 v[44:45], v[0:1], v[44:45]
	v_cvt_f16_f32_e32 v37, v47
	v_cvt_f16_f32_e32 v42, v44
	v_cvt_f16_f32_e32 v43, v45
	ds_write_b16 v176, v36 offset:24
	ds_write_b16 v176, v37 offset:64
	ds_write_b16 v176, v42 offset:5144
	ds_write_b16 v176, v43 offset:5184
	s_waitcnt lgkmcnt(9)
	ds_write_b16 v176, v60 offset:10264
	v_lshl_add_u32 v46, v206, 1, v2
	s_nop 0
	s_nop 0
	ds_read_b32 v61, v46 offset:32768
	v_rcp_f32_e32 v42, v56
	v_rcp_f32_e32 v43, v57
	s_waitcnt lgkmcnt(10)
	v_cvt_f32_f16_e32 v48, v147
	v_cvt_f32_f16_sdwa v49, v147 dst_sel:DWORD dst_unused:UNUSED_PAD src0_sel:WORD_1
	s_waitcnt lgkmcnt(9)
	v_cvt_f32_f16_e32 v54, v149
	v_cvt_f32_f16_sdwa v55, v149 dst_sel:DWORD dst_unused:UNUSED_PAD src0_sel:WORD_1
	v_cvt_f32_f16_e32 v46, v146
	v_lshl_add_u32 v251, v208, 1, v2
	ds_read2st64_b32 v[162:163], v251 offset0:64 offset1:80
	v_cvt_f32_f16_e32 v50, v148
	v_cvt_f32_f16_sdwa v51, v148 dst_sel:DWORD dst_unused:UNUSED_PAD src0_sel:WORD_1
	v_cvt_f32_f16_sdwa v47, v146 dst_sel:DWORD dst_unused:UNUSED_PAD src0_sel:WORD_1
	ds_read2st64_b32 v[146:147], v251 offset0:96 offset1:112
	v_pk_mul_f32 v[36:37], v[62:63], v[48:49]
	v_pk_mul_f32 v[44:45], v[56:57], v[54:55]
	v_pk_mul_f32 v[48:49], v[42:43], v[50:51]
	v_pk_mul_f32 v[42:43], v[42:43], v[46:47]
	v_pk_mul_f32 v[46:47], v[40:41], v[36:37]
	v_pk_mul_f32 v[50:51], v[40:41], v[44:45]
	v_cvt_pk_f16_f32 v36, v36, v37
	v_cvt_pk_f16_f32 v37, v44, v45
	v_pk_mul_f32 v[54:55], v[38:39], v[48:49]
	v_pk_mul_f32 v[58:59], v[38:39], v[42:43]
	ds_write2st64_b32 v207, v36, v37 offset1:18
	v_cvt_pk_f16_f32 v36, v46, v47
	v_cvt_pk_f16_f32 v37, v50, v51
	v_pk_mul_f32 v[48:49], v[0:1], v[48:49]
	ds_write2st64_b32 v207, v36, v37 offset0:36 offset1:54
	v_cvt_pk_f16_f32 v36, v54, v55
	v_cvt_pk_f16_f32 v37, v58, v59
	ds_write2st64_b32 v207, v36, v37 offset0:72 offset1:90
	v_cvt_f16_f32_e32 v36, v48
	v_pk_mul_f32 v[42:43], v[0:1], v[42:43]
	v_cvt_f16_f32_e32 v37, v49
	v_cvt_f16_f32_e32 v42, v42
	v_cvt_f16_f32_e32 v43, v43
	ds_write_b16 v176, v36 offset:26
	s_waitcnt lgkmcnt(14)
	ds_write_b16 v176, v37 offset:66
	s_waitcnt lgkmcnt(14)
	ds_write_b16 v176, v42 offset:5146
	s_waitcnt lgkmcnt(14)
	ds_write_b16 v176, v43 offset:5186
	s_waitcnt lgkmcnt(9)
	ds_write_b16 v176, v61 offset:10266
	v_lshl_add_u32 v46, v208, 1, v2
	s_nop 0
	s_nop 0
	ds_read_b32 v58, v46 offset:32768
	v_rcp_f32_e32 v42, v52
	v_rcp_f32_e32 v43, v53
	v_lshl_add_u32 v2, v210, 1, v2
	s_nop 0
	s_waitcnt lgkmcnt(10)
	v_cvt_f32_f16_e32 v48, v163
	v_cvt_f32_f16_sdwa v49, v163 dst_sel:DWORD dst_unused:UNUSED_PAD src0_sel:WORD_1
	s_nop 0
	s_waitcnt lgkmcnt(9)
	v_cvt_f32_f16_e32 v54, v147
	ds_read2st64_b32 v[148:149], v2 offset0:64 offset1:80
	v_cvt_f32_f16_sdwa v55, v147 dst_sel:DWORD dst_unused:UNUSED_PAD src0_sel:WORD_1
	v_cvt_f32_f16_e32 v46, v162
	v_cvt_f32_f16_e32 v50, v146
	ds_read2st64_b32 v[164:165], v2 offset0:96 offset1:112
	v_cvt_f32_f16_sdwa v51, v146 dst_sel:DWORD dst_unused:UNUSED_PAD src0_sel:WORD_1
	v_cvt_f32_f16_sdwa v47, v162 dst_sel:DWORD dst_unused:UNUSED_PAD src0_sel:WORD_1
	v_pk_mul_f32 v[36:37], v[56:57], v[48:49]
	v_pk_mul_f32 v[44:45], v[52:53], v[54:55]
	v_pk_mul_f32 v[48:49], v[42:43], v[50:51]
	v_pk_mul_f32 v[42:43], v[42:43], v[46:47]
	v_pk_mul_f32 v[46:47], v[40:41], v[36:37]
	v_pk_mul_f32 v[50:51], v[40:41], v[44:45]
	v_cvt_pk_f16_f32 v36, v36, v37
	v_cvt_pk_f16_f32 v37, v44, v45
	v_pk_mul_f32 v[54:55], v[38:39], v[48:49]
	v_pk_mul_f32 v[56:57], v[38:39], v[42:43]
	ds_write2st64_b32 v209, v36, v37 offset1:18
	v_cvt_pk_f16_f32 v36, v46, v47
	v_cvt_pk_f16_f32 v37, v50, v51
	v_pk_mul_f32 v[48:49], v[0:1], v[48:49]
	ds_write2st64_b32 v209, v36, v37 offset0:36 offset1:54
	v_cvt_pk_f16_f32 v36, v54, v55
	v_cvt_pk_f16_f32 v37, v56, v57
	ds_write2st64_b32 v209, v36, v37 offset0:72 offset1:90
	v_cvt_f16_f32_e32 v36, v48
	v_pk_mul_f32 v[42:43], v[0:1], v[42:43]
	v_cvt_f16_f32_e32 v37, v49
	v_cvt_f16_f32_e32 v42, v42
	v_cvt_f16_f32_e32 v43, v43
	ds_write_b16 v176, v36 offset:28
	s_waitcnt lgkmcnt(14)
	ds_write_b16 v176, v37 offset:68
	s_waitcnt lgkmcnt(14)
	ds_write_b16 v176, v42 offset:5148
	s_waitcnt lgkmcnt(14)
	ds_write_b16 v176, v43 offset:5188
	s_waitcnt lgkmcnt(9)
	ds_write_b16 v176, v58 offset:10268
	ds_read_b32 v2, v2 offset:32768
	v_rcp_f32_e32 v42, v0
	v_rcp_f32_e32 v43, v1
	s_waitcnt lgkmcnt(10)
	v_cvt_f32_f16_e32 v48, v149
	v_cvt_f32_f16_sdwa v49, v149 dst_sel:DWORD dst_unused:UNUSED_PAD src0_sel:WORD_1
	s_waitcnt lgkmcnt(9)
	v_cvt_f32_f16_e32 v54, v165
	v_cvt_f32_f16_sdwa v55, v165 dst_sel:DWORD dst_unused:UNUSED_PAD src0_sel:WORD_1
	v_cvt_f32_f16_e32 v46, v148
	v_cvt_f32_f16_e32 v50, v164
	v_cvt_f32_f16_sdwa v51, v164 dst_sel:DWORD dst_unused:UNUSED_PAD src0_sel:WORD_1
	v_cvt_f32_f16_sdwa v47, v148 dst_sel:DWORD dst_unused:UNUSED_PAD src0_sel:WORD_1
	v_pk_mul_f32 v[36:37], v[52:53], v[48:49]
	v_pk_mul_f32 v[44:45], v[0:1], v[54:55]
	v_pk_mul_f32 v[48:49], v[42:43], v[50:51]
	v_pk_mul_f32 v[42:43], v[42:43], v[46:47]
	v_pk_mul_f32 v[46:47], v[40:41], v[36:37]
	v_pk_mul_f32 v[40:41], v[40:41], v[44:45]
	v_cvt_pk_f16_f32 v36, v36, v37
	v_cvt_pk_f16_f32 v37, v44, v45
	v_pk_mul_f32 v[50:51], v[38:39], v[48:49]
	v_pk_mul_f32 v[38:39], v[38:39], v[42:43]
	ds_write2st64_b32 v211, v36, v37 offset1:18
	v_cvt_pk_f16_f32 v36, v46, v47
	v_cvt_pk_f16_f32 v37, v40, v41
	v_pk_mul_f32 v[48:49], v[0:1], v[48:49]
	ds_write2st64_b32 v211, v36, v37 offset0:36 offset1:54
	v_cvt_pk_f16_f32 v36, v50, v51
	v_cvt_pk_f16_f32 v37, v38, v39
	ds_write2st64_b32 v211, v36, v37 offset0:72 offset1:90
	v_cvt_f16_f32_e32 v36, v48
	v_pk_mul_f32 v[42:43], v[0:1], v[42:43]
	v_cvt_f16_f32_e32 v37, v49
	v_cvt_f16_f32_e32 v38, v42
	v_cvt_f16_f32_e32 v39, v43
	ds_write_b16 v176, v36 offset:30
	ds_write_b16 v176, v37 offset:70
	ds_write_b16 v176, v38 offset:5150
	s_waitcnt lgkmcnt(14)
	ds_write_b16 v176, v39 offset:5190
	s_nop 0
	s_waitcnt lgkmcnt(7)
	ds_write_b16 v176, v2 offset:10270
	v_perm_b32 v36, v61, v60, s35
	v_perm_b32 v37, v2, v58, s35
	ds_write_b64 v176, v[36:37] offset:10304
.LBB0_1043:
	s_andn2_saveexec_b64 s[28:29], s[28:29]
	s_cbranch_execz .LBB0_1045
	v_lshl_add_u32 v251, v196, 1, v2
	ds_read2st64_b32 v[36:37], v251 offset0:64 offset1:80
	ds_read2st64_b32 v[48:49], v251 offset0:96 offset1:112
	v_lshl_add_u32 v52, v196, 1, v2
	s_nop 0
	s_nop 0
	ds_read_b32 v64, v52 offset:32768
	v_rcp_f32_e32 v44, v58
	v_rcp_f32_e32 v45, v59
	s_nop 0
	s_waitcnt lgkmcnt(1)
	v_cvt_f32_f16_e32 v60, v49
	v_cvt_f32_f16_e32 v54, v37
	v_cvt_f32_f16_sdwa v55, v37 dst_sel:DWORD dst_unused:UNUSED_PAD src0_sel:WORD_1
	v_cvt_f32_f16_sdwa v61, v49 dst_sel:DWORD dst_unused:UNUSED_PAD src0_sel:WORD_1
	v_lshl_add_u32 v251, v198, 1, v2
	ds_read2st64_b32 v[146:147], v251 offset0:64 offset1:80
	v_cvt_f32_f16_e32 v52, v36
	v_cvt_f32_f16_e32 v56, v48
	v_cvt_f32_f16_sdwa v57, v48 dst_sel:DWORD dst_unused:UNUSED_PAD src0_sel:WORD_1
	ds_read2st64_b32 v[148:149], v251 offset0:96 offset1:112
	v_cvt_f32_f16_sdwa v53, v36 dst_sel:DWORD dst_unused:UNUSED_PAD src0_sel:WORD_1
	v_pk_mul_f32 v[36:37], v[38:39], v[54:55]
	v_pk_mul_f32 v[48:49], v[58:59], v[60:61]
	v_pk_mul_f32 v[54:55], v[44:45], v[56:57]
	v_pk_mul_f32 v[44:45], v[44:45], v[52:53]
	v_pk_mul_f32 v[52:53], v[40:41], v[36:37]
	v_pk_mul_f32 v[56:57], v[40:41], v[48:49]
	v_cvt_pk_f16_f32 v36, v36, v37
	v_cvt_pk_f16_f32 v37, v48, v49
	v_pk_mul_f32 v[60:61], v[38:39], v[54:55]
	v_pk_mul_f32 v[62:63], v[38:39], v[44:45]
	ds_write2st64_b32 v197, v36, v37 offset1:18
	v_cvt_pk_f16_f32 v36, v52, v53
	v_cvt_pk_f16_f32 v37, v56, v57
	v_pk_mul_f32 v[54:55], v[0:1], v[54:55]
	ds_write2st64_b32 v197, v36, v37 offset0:36 offset1:54
	v_cvt_pk_f16_f32 v36, v60, v61
	v_cvt_pk_f16_f32 v37, v62, v63
	ds_write2st64_b32 v197, v36, v37 offset0:72 offset1:90
	v_cvt_f16_f32_e32 v36, v54
	v_pk_mul_f32 v[44:45], v[0:1], v[44:45]
	v_cvt_f16_f32_e32 v37, v55
	v_cvt_f16_f32_e32 v44, v44
	v_cvt_f16_f32_e32 v45, v45
	ds_write_b16 v176, v36 offset:16
	ds_write_b16 v176, v37 offset:56
	ds_write_b16 v176, v44 offset:5136
	ds_write_b16 v176, v45 offset:5176
	s_waitcnt lgkmcnt(9)
	ds_write_b16 v176, v64 offset:10256
	v_lshl_add_u32 v52, v198, 1, v2
	s_nop 0
	s_nop 0
	ds_read_b32 v62, v52 offset:32768
	v_rcp_f32_e32 v44, v50
	v_rcp_f32_e32 v45, v51
	s_waitcnt lgkmcnt(10)
	v_cvt_f32_f16_e32 v54, v147
	v_cvt_f32_f16_sdwa v55, v147 dst_sel:DWORD dst_unused:UNUSED_PAD src0_sel:WORD_1
	s_waitcnt lgkmcnt(9)
	v_cvt_f32_f16_e32 v60, v149
	v_cvt_f32_f16_sdwa v61, v149 dst_sel:DWORD dst_unused:UNUSED_PAD src0_sel:WORD_1
	v_cvt_f32_f16_e32 v52, v146
	v_lshl_add_u32 v251, v200, 1, v2
	ds_read2st64_b32 v[162:163], v251 offset0:64 offset1:80
	v_cvt_f32_f16_e32 v56, v148
	v_cvt_f32_f16_sdwa v57, v148 dst_sel:DWORD dst_unused:UNUSED_PAD src0_sel:WORD_1
	v_cvt_f32_f16_sdwa v53, v146 dst_sel:DWORD dst_unused:UNUSED_PAD src0_sel:WORD_1
	ds_read2st64_b32 v[146:147], v251 offset0:96 offset1:112
	v_pk_mul_f32 v[36:37], v[58:59], v[54:55]
	v_pk_mul_f32 v[48:49], v[50:51], v[60:61]
	v_pk_mul_f32 v[54:55], v[44:45], v[56:57]
	v_pk_mul_f32 v[44:45], v[44:45], v[52:53]
	v_pk_mul_f32 v[52:53], v[40:41], v[36:37]
	v_pk_mul_f32 v[56:57], v[40:41], v[48:49]
	v_cvt_pk_f16_f32 v36, v36, v37
	v_cvt_pk_f16_f32 v37, v48, v49
	v_pk_mul_f32 v[58:59], v[38:39], v[54:55]
	v_pk_mul_f32 v[60:61], v[38:39], v[44:45]
	ds_write2st64_b32 v199, v36, v37 offset1:18
	v_cvt_pk_f16_f32 v36, v52, v53
	v_cvt_pk_f16_f32 v37, v56, v57
	v_pk_mul_f32 v[54:55], v[0:1], v[54:55]
	ds_write2st64_b32 v199, v36, v37 offset0:36 offset1:54
	v_cvt_pk_f16_f32 v36, v58, v59
	v_cvt_pk_f16_f32 v37, v60, v61
	ds_write2st64_b32 v199, v36, v37 offset0:72 offset1:90
	v_cvt_f16_f32_e32 v36, v54
	v_pk_mul_f32 v[44:45], v[0:1], v[44:45]
	v_cvt_f16_f32_e32 v37, v55
	v_cvt_f16_f32_e32 v44, v44
	v_cvt_f16_f32_e32 v45, v45
	ds_write_b16 v176, v36 offset:18
	s_waitcnt lgkmcnt(14)
	ds_write_b16 v176, v37 offset:58
	s_waitcnt lgkmcnt(14)
	ds_write_b16 v176, v44 offset:5138
	s_waitcnt lgkmcnt(14)
	ds_write_b16 v176, v45 offset:5178
	s_waitcnt lgkmcnt(9)
	ds_write_b16 v176, v62 offset:10258
	v_lshl_add_u32 v52, v200, 1, v2
	s_nop 0
	s_nop 0
	ds_read_b32 v60, v52 offset:32768
	v_rcp_f32_e32 v44, v46
	v_rcp_f32_e32 v45, v47
	v_lshl_add_u32 v2, v202, 1, v2
	s_nop 0
	s_waitcnt lgkmcnt(10)
	v_cvt_f32_f16_e32 v54, v163
	v_cvt_f32_f16_sdwa v55, v163 dst_sel:DWORD dst_unused:UNUSED_PAD src0_sel:WORD_1
	s_nop 0
	s_waitcnt lgkmcnt(9)
	v_cvt_f32_f16_e32 v58, v147
	ds_read2st64_b32 v[148:149], v2 offset0:64 offset1:80
	v_cvt_f32_f16_sdwa v59, v147 dst_sel:DWORD dst_unused:UNUSED_PAD src0_sel:WORD_1
	v_cvt_f32_f16_e32 v52, v162
	v_cvt_f32_f16_e32 v56, v146
	ds_read2st64_b32 v[164:165], v2 offset0:96 offset1:112
	v_cvt_f32_f16_sdwa v57, v146 dst_sel:DWORD dst_unused:UNUSED_PAD src0_sel:WORD_1
	v_cvt_f32_f16_sdwa v53, v162 dst_sel:DWORD dst_unused:UNUSED_PAD src0_sel:WORD_1
	v_pk_mul_f32 v[36:37], v[50:51], v[54:55]
	v_pk_mul_f32 v[48:49], v[46:47], v[58:59]
	v_pk_mul_f32 v[50:51], v[44:45], v[56:57]
	v_pk_mul_f32 v[44:45], v[44:45], v[52:53]
	v_pk_mul_f32 v[52:53], v[40:41], v[36:37]
	v_pk_mul_f32 v[54:55], v[40:41], v[48:49]
	v_cvt_pk_f16_f32 v36, v36, v37
	v_cvt_pk_f16_f32 v37, v48, v49
	v_pk_mul_f32 v[56:57], v[38:39], v[50:51]
	v_pk_mul_f32 v[58:59], v[38:39], v[44:45]
	ds_write2st64_b32 v201, v36, v37 offset1:18
	v_cvt_pk_f16_f32 v36, v52, v53
	v_cvt_pk_f16_f32 v37, v54, v55
	v_pk_mul_f32 v[50:51], v[0:1], v[50:51]
	ds_write2st64_b32 v201, v36, v37 offset0:36 offset1:54
	v_cvt_pk_f16_f32 v36, v56, v57
	v_cvt_pk_f16_f32 v37, v58, v59
	ds_write2st64_b32 v201, v36, v37 offset0:72 offset1:90
	v_cvt_f16_f32_e32 v36, v50
	v_pk_mul_f32 v[44:45], v[0:1], v[44:45]
	v_cvt_f16_f32_e32 v37, v51
	v_cvt_f16_f32_e32 v44, v44
	v_cvt_f16_f32_e32 v45, v45
	ds_write_b16 v176, v36 offset:20
	s_waitcnt lgkmcnt(14)
	ds_write_b16 v176, v37 offset:60
	s_waitcnt lgkmcnt(14)
	ds_write_b16 v176, v44 offset:5140
	s_waitcnt lgkmcnt(14)
	ds_write_b16 v176, v45 offset:5180
	s_waitcnt lgkmcnt(9)
	ds_write_b16 v176, v60 offset:10260
	ds_read_b32 v2, v2 offset:32768
	v_rcp_f32_e32 v44, v42
	v_rcp_f32_e32 v45, v43
	s_waitcnt lgkmcnt(10)
	v_cvt_f32_f16_e32 v52, v149
	v_cvt_f32_f16_sdwa v53, v149 dst_sel:DWORD dst_unused:UNUSED_PAD src0_sel:WORD_1
	s_waitcnt lgkmcnt(9)
	v_cvt_f32_f16_e32 v56, v165
	v_cvt_f32_f16_sdwa v57, v165 dst_sel:DWORD dst_unused:UNUSED_PAD src0_sel:WORD_1
	v_cvt_f32_f16_e32 v50, v148
	v_cvt_f32_f16_e32 v54, v164
	v_cvt_f32_f16_sdwa v55, v164 dst_sel:DWORD dst_unused:UNUSED_PAD src0_sel:WORD_1
	v_cvt_f32_f16_sdwa v51, v148 dst_sel:DWORD dst_unused:UNUSED_PAD src0_sel:WORD_1
	v_pk_mul_f32 v[36:37], v[46:47], v[52:53]
	v_pk_mul_f32 v[42:43], v[42:43], v[56:57]
	v_pk_mul_f32 v[46:47], v[44:45], v[54:55]
	v_pk_mul_f32 v[44:45], v[44:45], v[50:51]
	v_pk_mul_f32 v[48:49], v[40:41], v[36:37]
	v_pk_mul_f32 v[40:41], v[40:41], v[42:43]
	v_cvt_pk_f16_f32 v36, v36, v37
	v_cvt_pk_f16_f32 v37, v42, v43
	v_pk_mul_f32 v[50:51], v[38:39], v[46:47]
	v_pk_mul_f32 v[38:39], v[38:39], v[44:45]
	ds_write2st64_b32 v203, v36, v37 offset1:18
	v_cvt_pk_f16_f32 v36, v48, v49
	v_cvt_pk_f16_f32 v37, v40, v41
	v_pk_mul_f32 v[46:47], v[0:1], v[46:47]
	ds_write2st64_b32 v203, v36, v37 offset0:36 offset1:54
	v_cvt_pk_f16_f32 v36, v50, v51
	v_cvt_pk_f16_f32 v37, v38, v39
	ds_write2st64_b32 v203, v36, v37 offset0:72 offset1:90
	v_cvt_f16_f32_e32 v36, v46
	v_pk_mul_f32 v[44:45], v[0:1], v[44:45]
	v_cvt_f16_f32_e32 v37, v47
	v_cvt_f16_f32_e32 v38, v44
	v_cvt_f16_f32_e32 v39, v45
	ds_write_b16 v176, v36 offset:22
	ds_write_b16 v176, v37 offset:62
	ds_write_b16 v176, v38 offset:5142
	s_waitcnt lgkmcnt(14)
	ds_write_b16 v176, v39 offset:5182
	s_nop 0
	s_waitcnt lgkmcnt(7)
	ds_write_b16 v176, v2 offset:10262
	v_perm_b32 v36, v62, v64, s35
	v_perm_b32 v37, v2, v60, s35
	ds_write_b64 v176, v[36:37] offset:10296

.LBB0_1046:
	v_cmp_eq_u32_e32 vcc, 1, v174
	s_and_saveexec_b64 s[28:29], vcc
	s_cbranch_execz .LBB0_1048
	v_lshl_add_u32 v251, v188, 1, v2
	ds_read2st64_b32 v[36:37], v251 offset0:64 offset1:80
	ds_read2st64_b32 v[46:47], v251 offset0:96 offset1:112
	v_lshl_add_u32 v50, v188, 1, v2
	s_nop 0
	s_nop 0
	ds_read_b32 v62, v50 offset:32768
	v_rcp_f32_e32 v42, v54
	v_rcp_f32_e32 v43, v55
	s_nop 0
	s_waitcnt lgkmcnt(1)
	v_cvt_f32_f16_e32 v58, v47
	v_cvt_f32_f16_e32 v52, v37
	v_cvt_f32_f16_sdwa v53, v37 dst_sel:DWORD dst_unused:UNUSED_PAD src0_sel:WORD_1
	v_cvt_f32_f16_sdwa v59, v47 dst_sel:DWORD dst_unused:UNUSED_PAD src0_sel:WORD_1
	v_lshl_add_u32 v251, v190, 1, v2
	ds_read2st64_b32 v[146:147], v251 offset0:64 offset1:80
	v_cvt_f32_f16_e32 v50, v36
	v_cvt_f32_f16_e32 v56, v46
	v_cvt_f32_f16_sdwa v57, v46 dst_sel:DWORD dst_unused:UNUSED_PAD src0_sel:WORD_1
	ds_read2st64_b32 v[148:149], v251 offset0:96 offset1:112
	v_cvt_f32_f16_sdwa v51, v36 dst_sel:DWORD dst_unused:UNUSED_PAD src0_sel:WORD_1
	v_pk_mul_f32 v[36:37], v[60:61], v[52:53]
	v_pk_mul_f32 v[46:47], v[54:55], v[58:59]
	v_pk_mul_f32 v[52:53], v[42:43], v[56:57]
	v_pk_mul_f32 v[42:43], v[42:43], v[50:51]
	v_pk_mul_f32 v[50:51], v[40:41], v[36:37]
	v_pk_mul_f32 v[56:57], v[40:41], v[46:47]
	v_cvt_pk_f16_f32 v36, v36, v37
	v_cvt_pk_f16_f32 v37, v46, v47
	v_pk_mul_f32 v[58:59], v[38:39], v[52:53]
	v_pk_mul_f32 v[60:61], v[38:39], v[42:43]
	ds_write2st64_b32 v189, v36, v37 offset1:18
	v_cvt_pk_f16_f32 v36, v50, v51
	v_cvt_pk_f16_f32 v37, v56, v57
	v_pk_mul_f32 v[52:53], v[0:1], v[52:53]
	ds_write2st64_b32 v189, v36, v37 offset0:36 offset1:54
	v_cvt_pk_f16_f32 v36, v58, v59
	v_cvt_pk_f16_f32 v37, v60, v61
	ds_write2st64_b32 v189, v36, v37 offset0:72 offset1:90
	v_cvt_f16_f32_e32 v36, v52
	v_pk_mul_f32 v[42:43], v[0:1], v[42:43]
	v_cvt_f16_f32_e32 v37, v53
	v_cvt_f16_f32_e32 v42, v42
	v_cvt_f16_f32_e32 v43, v43
	ds_write_b16 v176, v36 offset:8
	ds_write_b16 v176, v37 offset:48
	ds_write_b16 v176, v42 offset:5128
	ds_write_b16 v176, v43 offset:5168
	s_waitcnt lgkmcnt(9)
	ds_write_b16 v176, v62 offset:10248
	v_lshl_add_u32 v50, v190, 1, v2
	s_nop 0
	s_nop 0
	ds_read_b32 v60, v50 offset:32768
	v_rcp_f32_e32 v42, v48
	v_rcp_f32_e32 v43, v49
	s_waitcnt lgkmcnt(10)
	v_cvt_f32_f16_e32 v52, v147
	v_cvt_f32_f16_sdwa v53, v147 dst_sel:DWORD dst_unused:UNUSED_PAD src0_sel:WORD_1
	s_waitcnt lgkmcnt(9)
	v_cvt_f32_f16_e32 v58, v149
	v_cvt_f32_f16_sdwa v59, v149 dst_sel:DWORD dst_unused:UNUSED_PAD src0_sel:WORD_1
	v_cvt_f32_f16_e32 v50, v146
	v_lshl_add_u32 v251, v192, 1, v2
	ds_read2st64_b32 v[162:163], v251 offset0:64 offset1:80
	v_cvt_f32_f16_e32 v56, v148
	v_cvt_f32_f16_sdwa v57, v148 dst_sel:DWORD dst_unused:UNUSED_PAD src0_sel:WORD_1
	v_cvt_f32_f16_sdwa v51, v146 dst_sel:DWORD dst_unused:UNUSED_PAD src0_sel:WORD_1
	ds_read2st64_b32 v[146:147], v251 offset0:96 offset1:112
	v_pk_mul_f32 v[36:37], v[54:55], v[52:53]
	v_pk_mul_f32 v[46:47], v[48:49], v[58:59]
	v_pk_mul_f32 v[52:53], v[42:43], v[56:57]
	v_pk_mul_f32 v[42:43], v[42:43], v[50:51]
	v_pk_mul_f32 v[50:51], v[40:41], v[36:37]
	v_pk_mul_f32 v[54:55], v[40:41], v[46:47]
	v_cvt_pk_f16_f32 v36, v36, v37
	v_cvt_pk_f16_f32 v37, v46, v47
	v_pk_mul_f32 v[56:57], v[38:39], v[52:53]
	v_pk_mul_f32 v[58:59], v[38:39], v[42:43]
	ds_write2st64_b32 v191, v36, v37 offset1:18
	v_cvt_pk_f16_f32 v36, v50, v51
	v_cvt_pk_f16_f32 v37, v54, v55
	v_pk_mul_f32 v[52:53], v[0:1], v[52:53]
	ds_write2st64_b32 v191, v36, v37 offset0:36 offset1:54
	v_cvt_pk_f16_f32 v36, v56, v57
	v_cvt_pk_f16_f32 v37, v58, v59
	ds_write2st64_b32 v191, v36, v37 offset0:72 offset1:90
	v_cvt_f16_f32_e32 v36, v52
	v_pk_mul_f32 v[42:43], v[0:1], v[42:43]
	v_cvt_f16_f32_e32 v37, v53
	v_cvt_f16_f32_e32 v42, v42
	v_cvt_f16_f32_e32 v43, v43
	ds_write_b16 v176, v36 offset:10
	s_waitcnt lgkmcnt(14)
	ds_write_b16 v176, v37 offset:50
	s_waitcnt lgkmcnt(14)
	ds_write_b16 v176, v42 offset:5130
	s_waitcnt lgkmcnt(14)
	ds_write_b16 v176, v43 offset:5170
	s_waitcnt lgkmcnt(9)
	ds_write_b16 v176, v60 offset:10250
	v_lshl_add_u32 v50, v192, 1, v2
	s_nop 0
	s_nop 0
	ds_read_b32 v58, v50 offset:32768
	v_rcp_f32_e32 v42, v44
	v_rcp_f32_e32 v43, v45
	v_lshl_add_u32 v2, v194, 1, v2
	s_nop 0
	s_waitcnt lgkmcnt(10)
	v_cvt_f32_f16_e32 v52, v163
	v_cvt_f32_f16_sdwa v53, v163 dst_sel:DWORD dst_unused:UNUSED_PAD src0_sel:WORD_1
	ds_read2st64_b32 v[148:149], v2 offset0:64 offset1:80
	s_waitcnt lgkmcnt(10)
	v_cvt_f32_f16_e32 v56, v147
	v_cvt_f32_f16_sdwa v57, v147 dst_sel:DWORD dst_unused:UNUSED_PAD src0_sel:WORD_1
	ds_read2st64_b32 v[164:165], v2 offset0:96 offset1:112
	v_cvt_f32_f16_e32 v50, v162
	v_cvt_f32_f16_e32 v54, v146
	v_cvt_f32_f16_sdwa v55, v146 dst_sel:DWORD dst_unused:UNUSED_PAD src0_sel:WORD_1
	v_cvt_f32_f16_sdwa v51, v162 dst_sel:DWORD dst_unused:UNUSED_PAD src0_sel:WORD_1
	v_pk_mul_f32 v[36:37], v[48:49], v[52:53]
	v_pk_mul_f32 v[46:47], v[44:45], v[56:57]
	v_pk_mul_f32 v[48:49], v[42:43], v[54:55]
	v_pk_mul_f32 v[42:43], v[42:43], v[50:51]
	v_pk_mul_f32 v[50:51], v[40:41], v[36:37]
	v_pk_mul_f32 v[52:53], v[40:41], v[46:47]
	v_cvt_pk_f16_f32 v36, v36, v37
	v_cvt_pk_f16_f32 v37, v46, v47
	v_pk_mul_f32 v[54:55], v[38:39], v[48:49]
	v_pk_mul_f32 v[56:57], v[38:39], v[42:43]
	ds_write2st64_b32 v193, v36, v37 offset1:18
	v_cvt_pk_f16_f32 v36, v50, v51
	v_cvt_pk_f16_f32 v37, v52, v53
	v_pk_mul_f32 v[48:49], v[0:1], v[48:49]
	ds_write2st64_b32 v193, v36, v37 offset0:36 offset1:54
	v_cvt_pk_f16_f32 v36, v54, v55
	v_cvt_pk_f16_f32 v37, v56, v57
	ds_write2st64_b32 v193, v36, v37 offset0:72 offset1:90
	v_cvt_f16_f32_e32 v36, v48
	v_pk_mul_f32 v[42:43], v[0:1], v[42:43]
	v_cvt_f16_f32_e32 v37, v49
	v_cvt_f16_f32_e32 v42, v42
	v_cvt_f16_f32_e32 v43, v43
	ds_write_b16 v176, v36 offset:12
	s_waitcnt lgkmcnt(14)
	ds_write_b16 v176, v37 offset:52
	s_waitcnt lgkmcnt(14)
	ds_write_b16 v176, v42 offset:5132
	s_waitcnt lgkmcnt(14)
	ds_write_b16 v176, v43 offset:5172
	s_waitcnt lgkmcnt(9)
	ds_write_b16 v176, v58 offset:10252
	ds_read_b32 v2, v2 offset:32768
	s_waitcnt lgkmcnt(10)
	v_cvt_f32_f16_e32 v48, v149
	v_cvt_f32_f16_sdwa v49, v149 dst_sel:DWORD dst_unused:UNUSED_PAD src0_sel:WORD_1
	s_waitcnt lgkmcnt(9)
	v_cvt_f32_f16_e32 v52, v165
	v_cvt_f32_f16_sdwa v53, v165 dst_sel:DWORD dst_unused:UNUSED_PAD src0_sel:WORD_1
	v_cvt_f32_f16_e32 v46, v148
	v_cvt_f32_f16_e32 v50, v164
	v_cvt_f32_f16_sdwa v51, v164 dst_sel:DWORD dst_unused:UNUSED_PAD src0_sel:WORD_1
	v_cvt_f32_f16_sdwa v47, v148 dst_sel:DWORD dst_unused:UNUSED_PAD src0_sel:WORD_1
	v_pk_mul_f32 v[36:37], v[44:45], v[48:49]
	v_pk_mul_f32 v[42:43], v[38:39], v[52:53]
	v_pk_mul_f32 v[44:45], v[40:41], v[50:51]
	v_pk_mul_f32 v[46:47], v[40:41], v[46:47]
	v_pk_mul_f32 v[48:49], v[40:41], v[36:37]
	v_pk_mul_f32 v[40:41], v[40:41], v[42:43]
	v_cvt_pk_f16_f32 v36, v36, v37
	v_cvt_pk_f16_f32 v37, v42, v43
	v_pk_mul_f32 v[50:51], v[38:39], v[44:45]
	v_pk_mul_f32 v[38:39], v[38:39], v[46:47]
	ds_write2st64_b32 v195, v36, v37 offset1:18
	v_cvt_pk_f16_f32 v36, v48, v49
	v_cvt_pk_f16_f32 v37, v40, v41
	v_pk_mul_f32 v[44:45], v[0:1], v[44:45]
	ds_write2st64_b32 v195, v36, v37 offset0:36 offset1:54
	v_cvt_pk_f16_f32 v36, v50, v51
	v_cvt_pk_f16_f32 v37, v38, v39
	ds_write2st64_b32 v195, v36, v37 offset0:72 offset1:90
	v_cvt_f16_f32_e32 v36, v44
	v_pk_mul_f32 v[46:47], v[0:1], v[46:47]
	v_cvt_f16_f32_e32 v37, v45
	v_cvt_f16_f32_e32 v38, v46
	v_cvt_f16_f32_e32 v39, v47
	ds_write_b16 v176, v36 offset:14
	ds_write_b16 v176, v37 offset:54
	ds_write_b16 v176, v38 offset:5134
	s_waitcnt lgkmcnt(14)
	ds_write_b16 v176, v39 offset:5174
	s_nop 0
	s_waitcnt lgkmcnt(7)
	ds_write_b16 v176, v2 offset:10254
	v_perm_b32 v36, v60, v62, s35
	v_perm_b32 v37, v2, v58, s35
	ds_write_b64 v176, v[36:37] offset:10288
